# lgkm0-before-barrier
# baseline (speedup 1.0000x reference)
;     __device__ bool next(int i, Unit& u) const { const int L = i * G + c; if (L >= 64 * 9) return false; u.pm = L; u.pn = L / 9; u.kt0 = 0; u.nt = ntf; u.ks = 0; return true; }
; #define PG8_STAGE(bufoff, gbase, voff) do { _Pragma("unroll") for (int _i = 0; _i < 2; ++_i) \
;         __builtin_amdgcn_global_load_lds((const unsigned*)((const char*)(gbase) + (voff)[_i]), (LAS unsigned*)(lds + (bufoff) + ldsw + _i * 8192), 16, 0, 0); } while (0)
; #define PG8_LDA(dst, b, h) do { _Pragma("unroll") for (int m = 0; m < 4; ++m) _Pragma("unroll") for (int k = 0; k < 2; ++k) dst[m][k] = *(const LAS bf16x8*)(lds + PG8_SA(b, h) + aoff + m * 2048 + k * 1024); } while (0)
; #define PG8_LDB(dst, b, h) do { _Pragma("unroll") for (int n = 0; n < 2; ++n) _Pragma("unroll") for (int k = 0; k < 2; ++k) dst[n][k] = *(const LAS bf16x8*)(lds + PG8_SB(b, h) + boff + n * 2048 + k * 1024); } while (0)
; template <class Epi, class Sched, bool ATILE = false>
; __device__ __forceinline__ void gemm_phase(LAS unsigned char* lds, const Gemm g, const Sched& S, const Epi& E) {
;     ...
;         const bool has_next = S.next(ui + 1, nxt);
;         const char* nA = has_next ? (const char*)g.A + (size_t)nxt.pm * tstepA + (size_t)nxt.kt0 * kstepA : cA; const char* nB = has_next ? (const char*)g.Bt + (size_t)nxt.pn * tstepB + (size_t)nxt.kt0 * kstep : cB;
;         int nt = cur.nt; asm volatile("" : "+s"(nt));
;         for (int t = 0; t < nt; t += 2) {
;             const bool last = (t == nt - 2);
;             const char* a1 = cA + (size_t)(t + 1) * kstepA;
;             const char* a2 = last ? nA : cA + (size_t)(t + 2) * kstepA; const char* b2 = last ? nB : cB + (size_t)(t + 2) * kstep;
;             const char* a3 = a2 + kstepA; const char* b3 = b2 + kstep;
;             PG8_LDB(B0, 0, 0); PG8_SCHED; PG8_LDA(At, 0, 0); PG8_STAGE(PG8_SA(1, 1), a1 + hstepA, voffA);
;             PG8_WAIT_L(8); PG8_BAR; PG8_WAIT_L(0); PG8_MMA(0, 0, At, B0); PG8_BAR; PG8_SCHED;
;             PG8_LDB(B1, 0, 1); PG8_STAGE(PG8_SB(0, 0), b2, voffB);
;             PG8_BAR; PG8_WAIT_L(0); PG8_MMA(0, 1, At, B1); PG8_BAR;
;             PG8_LDA(At, 0, 1); PG8_STAGE(PG8_SA(0, 0), a2, voffA);
;             PG8_BAR; PG8_WAIT_L(0); PG8_MMA(1, 0, At, B0); PG8_BAR; PG8_SCHED;
;             PG8_STAGE(PG8_SB(0, 1), b2 + hstepB, voffB);
;             PG8_WAIT_V(6); PG8_BAR; PG8_MMA(1, 1, At, B1); PG8_BAR;
.LBB0_625:
	ds_read_b128 v[182:185], v139
	ds_read_b128 v[186:189], v139 offset:1024
	ds_read_b128 v[190:193], v139 offset:2048
	ds_read_b128 v[194:197], v139 offset:3072
	s_add_i32 s62, s28, 2
	s_add_u32 s29, s26, 0xfff80080
	s_addc_u32 s30, s27, -1
	s_cmp_eq_u32 s59, s28
	s_cselect_b32 s28, s58, s60
	s_cselect_b32 s31, s13, s30
	s_cselect_b32 s30, s56, s29
	s_cselect_b32 s29, s57, s61
	s_add_i32 m0, s35, 0xc000
	ds_read_b128 v[198:201], v163
	ds_read_b128 v[202:205], v163 offset:1024
	ds_read_b128 v[206:209], v163 offset:2048
	ds_read_b128 v[210:213], v163 offset:3072
	ds_read_b128 v[214:217], v163 offset:4096
	ds_read_b128 v[218:221], v163 offset:5120
	ds_read_b128 v[222:225], v163 offset:6144
	ds_read_b128 v[226:229], v163 offset:7168
	global_load_lds_dwordx4 v172, s[26:27]
	s_add_i32 m0, s35, 0xe000
	s_nop 0
	global_load_lds_dwordx4 v174, s[26:27]
	s_waitcnt lgkmcnt(8)
	s_waitcnt lgkmcnt(0)
	s_setprio 1
	s_barrier
	v_mfma_f32_16x16x32_bf16 v[120:123], v[182:185], v[198:201], v[120:123]
	v_mfma_f32_16x16x32_bf16 v[112:115], v[190:193], v[198:201], v[112:115]
	v_mfma_f32_16x16x32_bf16 v[104:107], v[182:185], v[206:209], v[104:107]
	v_mfma_f32_16x16x32_bf16 v[96:99], v[190:193], v[206:209], v[96:99]
	v_mfma_f32_16x16x32_bf16 v[88:91], v[182:185], v[214:217], v[88:91]
	v_mfma_f32_16x16x32_bf16 v[80:83], v[190:193], v[214:217], v[80:83]
	v_mfma_f32_16x16x32_bf16 v[72:75], v[182:185], v[222:225], v[72:75]
	v_mfma_f32_16x16x32_bf16 v[64:67], v[190:193], v[222:225], v[64:67]
	v_mfma_f32_16x16x32_bf16 v[120:123], v[186:189], v[202:205], v[120:123]
	v_mfma_f32_16x16x32_bf16 v[112:115], v[194:197], v[202:205], v[112:115]
	v_mfma_f32_16x16x32_bf16 v[104:107], v[186:189], v[210:213], v[104:107]
	v_mfma_f32_16x16x32_bf16 v[96:99], v[194:197], v[210:213], v[96:99]
	v_mfma_f32_16x16x32_bf16 v[88:91], v[186:189], v[218:221], v[88:91]
	v_mfma_f32_16x16x32_bf16 v[80:83], v[194:197], v[218:221], v[80:83]
	v_mfma_f32_16x16x32_bf16 v[72:75], v[186:189], v[226:229], v[72:75]
	v_mfma_f32_16x16x32_bf16 v[64:67], v[194:197], v[226:229], v[64:67]
	s_barrier
	s_setprio 0
	s_add_i32 s63, s53, s34
	s_add_u32 s98, s28, s0
	s_addc_u32 s99, s29, s1
	s_mov_b32 m0, s63
	ds_read_b128 v[230:233], v167
	ds_read_b128 v[234:237], v167 offset:1024
	ds_read_b128 v[238:241], v167 offset:2048
	ds_read_b128 v[242:245], v167 offset:3072
	global_load_lds_dwordx4 v130, s[28:29]
	s_add_i32 m0, s63, 0x2000
	s_nop 0
	global_load_lds_dwordx4 v134, s[28:29]
	s_waitcnt lgkmcnt(0)
	s_setprio 1
	s_barrier
	v_mfma_f32_16x16x32_bf16 v[124:127], v[230:233], v[198:201], v[124:127]
	v_mfma_f32_16x16x32_bf16 v[116:119], v[238:241], v[198:201], v[116:119]
	v_mfma_f32_16x16x32_bf16 v[108:111], v[230:233], v[206:209], v[108:111]
	v_mfma_f32_16x16x32_bf16 v[100:103], v[238:241], v[206:209], v[100:103]
	v_mfma_f32_16x16x32_bf16 v[92:95], v[230:233], v[214:217], v[92:95]
	v_mfma_f32_16x16x32_bf16 v[84:87], v[238:241], v[214:217], v[84:87]
	v_mfma_f32_16x16x32_bf16 v[76:79], v[230:233], v[222:225], v[76:79]
	v_mfma_f32_16x16x32_bf16 v[68:71], v[238:241], v[222:225], v[68:71]
	v_mfma_f32_16x16x32_bf16 v[124:127], v[234:237], v[202:205], v[124:127]
	v_mfma_f32_16x16x32_bf16 v[116:119], v[242:245], v[202:205], v[116:119]
	v_mfma_f32_16x16x32_bf16 v[108:111], v[234:237], v[210:213], v[108:111]
	v_mfma_f32_16x16x32_bf16 v[100:103], v[242:245], v[210:213], v[100:103]
	v_mfma_f32_16x16x32_bf16 v[92:95], v[234:237], v[218:221], v[92:95]
	v_mfma_f32_16x16x32_bf16 v[84:87], v[242:245], v[218:221], v[84:87]
	v_mfma_f32_16x16x32_bf16 v[76:79], v[234:237], v[226:229], v[76:79]
	v_mfma_f32_16x16x32_bf16 v[68:71], v[242:245], v[226:229], v[68:71]
	s_barrier
	s_setprio 0
	s_mov_b32 m0, s35
	s_add_u32 s100, s30, s0
	s_addc_u32 s101, s31, s1
	ds_read_b128 v[198:201], v163 offset:16384
	ds_read_b128 v[202:205], v163 offset:17408
	ds_read_b128 v[206:209], v163 offset:18432
	ds_read_b128 v[210:213], v163 offset:19456
	ds_read_b128 v[214:217], v163 offset:20480
	ds_read_b128 v[218:221], v163 offset:21504
	ds_read_b128 v[222:225], v163 offset:22528
	ds_read_b128 v[226:229], v163 offset:23552
	global_load_lds_dwordx4 v128, s[30:31]
	s_mov_b32 m0, s36
	s_nop 0
	global_load_lds_dwordx4 v132, s[30:31]
	s_waitcnt lgkmcnt(0)
	s_setprio 1
	s_barrier
	v_mfma_f32_16x16x32_bf16 v[56:59], v[182:185], v[198:201], v[56:59]
	v_mfma_f32_16x16x32_bf16 v[48:51], v[190:193], v[198:201], v[48:51]
	v_mfma_f32_16x16x32_bf16 v[40:43], v[182:185], v[206:209], v[40:43]
	v_mfma_f32_16x16x32_bf16 v[32:35], v[190:193], v[206:209], v[32:35]
	v_mfma_f32_16x16x32_bf16 v[24:27], v[182:185], v[214:217], v[24:27]
	v_mfma_f32_16x16x32_bf16 v[16:19], v[190:193], v[214:217], v[16:19]
	v_mfma_f32_16x16x32_bf16 v[8:11], v[182:185], v[222:225], v[8:11]
	v_mfma_f32_16x16x32_bf16 v[4:7], v[190:193], v[222:225], v[4:7]
	v_mfma_f32_16x16x32_bf16 v[56:59], v[186:189], v[202:205], v[56:59]
	v_mfma_f32_16x16x32_bf16 v[48:51], v[194:197], v[202:205], v[48:51]
	v_mfma_f32_16x16x32_bf16 v[40:43], v[186:189], v[210:213], v[40:43]
	v_mfma_f32_16x16x32_bf16 v[32:35], v[194:197], v[210:213], v[32:35]
	v_mfma_f32_16x16x32_bf16 v[24:27], v[186:189], v[218:221], v[24:27]
	v_mfma_f32_16x16x32_bf16 v[16:19], v[194:197], v[218:221], v[16:19]
	v_mfma_f32_16x16x32_bf16 v[8:11], v[186:189], v[226:229], v[8:11]
	v_mfma_f32_16x16x32_bf16 v[4:7], v[194:197], v[226:229], v[4:7]
	s_barrier
	s_setprio 0
	s_add_u32 s64, s28, 0x80000
	s_addc_u32 s65, s29, 0
	s_add_i32 s63, s54, s34
	s_mov_b32 m0, s63
	s_nop 0
	global_load_lds_dwordx4 v130, s[64:65]
	s_add_i32 m0, s63, 0x2000
	s_nop 0
	global_load_lds_dwordx4 v134, s[64:65]
	s_waitcnt vmcnt(6)
	s_setprio 1
	s_barrier
; #define PG8_STAGE(bufoff, gbase, voff) do { _Pragma("unroll") for (int _i = 0; _i < 2; ++_i) \
;         __builtin_amdgcn_global_load_lds((const unsigned*)((const char*)(gbase) + (voff)[_i]), (LAS unsigned*)(lds + (bufoff) + ldsw + _i * 8192), 16, 0, 0); } while (0)
; #define PG8_LDA(dst, b, h) do { _Pragma("unroll") for (int m = 0; m < 4; ++m) _Pragma("unroll") for (int k = 0; k < 2; ++k) dst[m][k] = *(const LAS bf16x8*)(lds + PG8_SA(b, h) + aoff + m * 2048 + k * 1024); } while (0)
; #define PG8_LDB(dst, b, h) do { _Pragma("unroll") for (int n = 0; n < 2; ++n) _Pragma("unroll") for (int k = 0; k < 2; ++k) dst[n][k] = *(const LAS bf16x8*)(lds + PG8_SB(b, h) + boff + n * 2048 + k * 1024); } while (0)
; #define PG8_MMA(ai, bj, At, Bt) do { __builtin_amdgcn_s_setprio(1); _Pragma("unroll") for (int m = 0; m < 4; ++m) _Pragma("unroll") for (int n = 0; n < 2; ++n) _Pragma("unroll") for (int k = 0; k < 2; ++k) \
;         acc[ai][bj][m][n] = __builtin_amdgcn_mfma_f32_16x16x32_bf16(Bt[n][k], At[m][k], acc[ai][bj][m][n], 0, 0, 0); __builtin_amdgcn_s_setprio(0); } while (0)
; #define PG8_WAIT_V(n) asm volatile("s_waitcnt vmcnt(" #n ")" ::: "memory")
; #define PG8_WAIT_L(n) asm volatile("s_waitcnt lgkmcnt(" #n ")" ::: "memory")
; #define PG8_BAR __builtin_amdgcn_s_barrier()
; #define PG8_SCHED __builtin_amdgcn_sched_barrier(0)
; template <class Epi, class Sched, bool ATILE = false>
; __device__ __forceinline__ void gemm_phase(LAS unsigned char* lds, const Gemm g, const Sched& S, const Epi& E) {
;     ...
;             PG8_WAIT_V(6); PG8_BAR; PG8_MMA(1, 1, At, B1); PG8_BAR;
;             PG8_LDB(B0, 1, 0); PG8_SCHED; PG8_LDA(At, 1, 0); PG8_STAGE(PG8_SA(0, 1), a2 + hstepA, voffA);
;             PG8_WAIT_L(8); PG8_BAR; PG8_WAIT_L(0); PG8_MMA(0, 0, At, B0); PG8_BAR; PG8_SCHED;
;             PG8_LDB(B1, 1, 1); PG8_STAGE(PG8_SB(1, 0), b3, voffB);
;             PG8_BAR; PG8_WAIT_L(0); PG8_MMA(0, 1, At, B1); PG8_BAR;
	v_mfma_f32_16x16x32_bf16 v[60:63], v[230:233], v[198:201], v[60:63]
	v_mfma_f32_16x16x32_bf16 v[52:55], v[238:241], v[198:201], v[52:55]
	v_mfma_f32_16x16x32_bf16 v[44:47], v[230:233], v[206:209], v[44:47]
	v_mfma_f32_16x16x32_bf16 v[36:39], v[238:241], v[206:209], v[36:39]
	v_mfma_f32_16x16x32_bf16 v[28:31], v[230:233], v[214:217], v[28:31]
	v_mfma_f32_16x16x32_bf16 v[20:23], v[238:241], v[214:217], v[20:23]
	v_mfma_f32_16x16x32_bf16 v[12:15], v[230:233], v[222:225], v[12:15]
	v_mfma_f32_16x16x32_bf16 v[0:3], v[238:241], v[222:225], v[0:3]
	v_mfma_f32_16x16x32_bf16 v[60:63], v[234:237], v[202:205], v[60:63]
	v_mfma_f32_16x16x32_bf16 v[52:55], v[242:245], v[202:205], v[52:55]
	v_mfma_f32_16x16x32_bf16 v[44:47], v[234:237], v[210:213], v[44:47]
	v_mfma_f32_16x16x32_bf16 v[36:39], v[242:245], v[210:213], v[36:39]
	v_mfma_f32_16x16x32_bf16 v[28:31], v[234:237], v[218:221], v[28:31]
	v_mfma_f32_16x16x32_bf16 v[20:23], v[242:245], v[218:221], v[20:23]
	v_mfma_f32_16x16x32_bf16 v[12:15], v[234:237], v[226:229], v[12:15]
	v_mfma_f32_16x16x32_bf16 v[0:3], v[242:245], v[226:229], v[0:3]
	s_barrier
	s_setprio 0
	s_add_i32 s63, 0, 0x18000
	v_add_u32_e32 v176, s63, v161
	ds_read_b128 v[182:185], v176
	ds_read_b128 v[186:189], v176 offset:1024
	ds_read_b128 v[190:193], v176 offset:2048
	ds_read_b128 v[194:197], v176 offset:3072
	s_add_u32 s30, s30, 0x80000
	s_addc_u32 s31, s31, 0
	s_mov_b32 m0, s37
	ds_read_b128 v[198:201], v163 offset:32768
	ds_read_b128 v[202:205], v163 offset:33792
	ds_read_b128 v[206:209], v163 offset:34816
	ds_read_b128 v[210:213], v163 offset:35840
	ds_read_b128 v[214:217], v163 offset:36864
	ds_read_b128 v[218:221], v163 offset:37888
	ds_read_b128 v[222:225], v163 offset:38912
	ds_read_b128 v[226:229], v163 offset:39936
	global_load_lds_dwordx4 v128, s[30:31]
	s_mov_b32 m0, s38
	s_nop 0
	global_load_lds_dwordx4 v132, s[30:31]
	s_waitcnt lgkmcnt(8)
	s_waitcnt lgkmcnt(0)
	s_setprio 1
	s_barrier
	v_mfma_f32_16x16x32_bf16 v[120:123], v[182:185], v[198:201], v[120:123]
	v_mfma_f32_16x16x32_bf16 v[112:115], v[190:193], v[198:201], v[112:115]
	v_mfma_f32_16x16x32_bf16 v[104:107], v[182:185], v[206:209], v[104:107]
	v_mfma_f32_16x16x32_bf16 v[96:99], v[190:193], v[206:209], v[96:99]
	v_mfma_f32_16x16x32_bf16 v[88:91], v[182:185], v[214:217], v[88:91]
	v_mfma_f32_16x16x32_bf16 v[80:83], v[190:193], v[214:217], v[80:83]
	v_mfma_f32_16x16x32_bf16 v[72:75], v[182:185], v[222:225], v[72:75]
	v_mfma_f32_16x16x32_bf16 v[64:67], v[190:193], v[222:225], v[64:67]
	v_mfma_f32_16x16x32_bf16 v[120:123], v[186:189], v[202:205], v[120:123]
	v_mfma_f32_16x16x32_bf16 v[112:115], v[194:197], v[202:205], v[112:115]
	v_mfma_f32_16x16x32_bf16 v[104:107], v[186:189], v[210:213], v[104:107]
	v_mfma_f32_16x16x32_bf16 v[96:99], v[194:197], v[210:213], v[96:99]
	v_mfma_f32_16x16x32_bf16 v[88:91], v[186:189], v[218:221], v[88:91]
	v_mfma_f32_16x16x32_bf16 v[80:83], v[194:197], v[218:221], v[80:83]
	v_mfma_f32_16x16x32_bf16 v[72:75], v[186:189], v[226:229], v[72:75]
	v_mfma_f32_16x16x32_bf16 v[64:67], v[194:197], v[226:229], v[64:67]
	s_barrier
	s_setprio 0
	s_add_i32 s30, 0, 0x1c000
	s_add_i32 s31, s63, s34
	v_add_u32_e32 v176, s30, v161
	s_mov_b32 m0, s31
	ds_read_b128 v[230:233], v176
	ds_read_b128 v[234:237], v176 offset:1024
	ds_read_b128 v[238:241], v176 offset:2048
	ds_read_b128 v[242:245], v176 offset:3072
	global_load_lds_dwordx4 v130, s[98:99]
	s_add_i32 m0, s31, 0x2000
	s_nop 0
	global_load_lds_dwordx4 v134, s[98:99]
	s_waitcnt lgkmcnt(0)
	s_setprio 1
	s_barrier
; #define PG8_STAGE(bufoff, gbase, voff) do { _Pragma("unroll") for (int _i = 0; _i < 2; ++_i) \
;         __builtin_amdgcn_global_load_lds((const unsigned*)((const char*)(gbase) + (voff)[_i]), (LAS unsigned*)(lds + (bufoff) + ldsw + _i * 8192), 16, 0, 0); } while (0)
; #define PG8_LDA(dst, b, h) do { _Pragma("unroll") for (int m = 0; m < 4; ++m) _Pragma("unroll") for (int k = 0; k < 2; ++k) dst[m][k] = *(const LAS bf16x8*)(lds + PG8_SA(b, h) + aoff + m * 2048 + k * 1024); } while (0)
; #define PG8_MMA(ai, bj, At, Bt) do { __builtin_amdgcn_s_setprio(1); _Pragma("unroll") for (int m = 0; m < 4; ++m) _Pragma("unroll") for (int n = 0; n < 2; ++n) _Pragma("unroll") for (int k = 0; k < 2; ++k) \
;         acc[ai][bj][m][n] = __builtin_amdgcn_mfma_f32_16x16x32_bf16(Bt[n][k], At[m][k], acc[ai][bj][m][n], 0, 0, 0); __builtin_amdgcn_s_setprio(0); } while (0)
; #define PG8_WAIT_V(n) asm volatile("s_waitcnt vmcnt(" #n ")" ::: "memory")
; #define PG8_WAIT_L(n) asm volatile("s_waitcnt lgkmcnt(" #n ")" ::: "memory")
; #define PG8_BAR __builtin_amdgcn_s_barrier()
; #define PG8_SCHED __builtin_amdgcn_sched_barrier(0)
; template <class Epi, class Sched, bool ATILE = false>
; __device__ __forceinline__ void gemm_phase(LAS unsigned char* lds, const Gemm g, const Sched& S, const Epi& E) {
;     ...
;             PG8_BAR; PG8_WAIT_L(0); PG8_MMA(0, 1, At, B1); PG8_BAR;
;             PG8_LDA(At, 1, 1); PG8_STAGE(PG8_SA(1, 0), a3, voffA);
;             PG8_BAR; PG8_WAIT_L(0); PG8_MMA(1, 0, At, B0); PG8_BAR; PG8_SCHED;
;             PG8_STAGE(PG8_SB(1, 1), b3 + hstepB, voffB);
;             PG8_WAIT_V(6); PG8_BAR; PG8_MMA(1, 1, At, B1); PG8_BAR;
;         }
	v_mfma_f32_16x16x32_bf16 v[124:127], v[230:233], v[198:201], v[124:127]
	v_mfma_f32_16x16x32_bf16 v[116:119], v[238:241], v[198:201], v[116:119]
	v_mfma_f32_16x16x32_bf16 v[108:111], v[230:233], v[206:209], v[108:111]
	v_mfma_f32_16x16x32_bf16 v[100:103], v[238:241], v[206:209], v[100:103]
	v_mfma_f32_16x16x32_bf16 v[92:95], v[230:233], v[214:217], v[92:95]
	v_mfma_f32_16x16x32_bf16 v[84:87], v[238:241], v[214:217], v[84:87]
	v_mfma_f32_16x16x32_bf16 v[76:79], v[230:233], v[222:225], v[76:79]
	v_mfma_f32_16x16x32_bf16 v[68:71], v[238:241], v[222:225], v[68:71]
	v_mfma_f32_16x16x32_bf16 v[124:127], v[234:237], v[202:205], v[124:127]
	v_mfma_f32_16x16x32_bf16 v[116:119], v[242:245], v[202:205], v[116:119]
	v_mfma_f32_16x16x32_bf16 v[108:111], v[234:237], v[210:213], v[108:111]
	v_mfma_f32_16x16x32_bf16 v[100:103], v[242:245], v[210:213], v[100:103]
	v_mfma_f32_16x16x32_bf16 v[92:95], v[234:237], v[218:221], v[92:95]
	v_mfma_f32_16x16x32_bf16 v[84:87], v[242:245], v[218:221], v[84:87]
	v_mfma_f32_16x16x32_bf16 v[76:79], v[234:237], v[226:229], v[76:79]
	v_mfma_f32_16x16x32_bf16 v[68:71], v[242:245], v[226:229], v[68:71]
	s_barrier
	s_setprio 0
	s_mov_b32 m0, s41
	ds_read_b128 v[198:201], v163 offset:49152
	ds_read_b128 v[202:205], v163 offset:50176
	ds_read_b128 v[206:209], v163 offset:51200
	ds_read_b128 v[210:213], v163 offset:52224
	ds_read_b128 v[214:217], v163 offset:53248
	ds_read_b128 v[218:221], v163 offset:54272
	ds_read_b128 v[222:225], v163 offset:55296
	ds_read_b128 v[226:229], v163 offset:56320
	global_load_lds_dwordx4 v128, s[100:101]
	s_mov_b32 m0, s42
	s_nop 0
	global_load_lds_dwordx4 v132, s[100:101]
	s_waitcnt lgkmcnt(0)
	s_setprio 1
	s_barrier
	v_mfma_f32_16x16x32_bf16 v[56:59], v[182:185], v[198:201], v[56:59]
	v_mfma_f32_16x16x32_bf16 v[48:51], v[190:193], v[198:201], v[48:51]
	v_mfma_f32_16x16x32_bf16 v[40:43], v[182:185], v[206:209], v[40:43]
	v_mfma_f32_16x16x32_bf16 v[32:35], v[190:193], v[206:209], v[32:35]
	v_mfma_f32_16x16x32_bf16 v[24:27], v[182:185], v[214:217], v[24:27]
	v_mfma_f32_16x16x32_bf16 v[16:19], v[190:193], v[214:217], v[16:19]
	v_mfma_f32_16x16x32_bf16 v[8:11], v[182:185], v[222:225], v[8:11]
	v_mfma_f32_16x16x32_bf16 v[4:7], v[190:193], v[222:225], v[4:7]
	v_mfma_f32_16x16x32_bf16 v[56:59], v[186:189], v[202:205], v[56:59]
	v_mfma_f32_16x16x32_bf16 v[48:51], v[194:197], v[202:205], v[48:51]
	v_mfma_f32_16x16x32_bf16 v[40:43], v[186:189], v[210:213], v[40:43]
	v_mfma_f32_16x16x32_bf16 v[32:35], v[194:197], v[210:213], v[32:35]
	v_mfma_f32_16x16x32_bf16 v[24:27], v[186:189], v[218:221], v[24:27]
	v_mfma_f32_16x16x32_bf16 v[16:19], v[194:197], v[218:221], v[16:19]
	v_mfma_f32_16x16x32_bf16 v[8:11], v[186:189], v[226:229], v[8:11]
	v_mfma_f32_16x16x32_bf16 v[4:7], v[194:197], v[226:229], v[4:7]
	s_barrier
	s_setprio 0
	s_add_u32 s28, s28, 0x80080
	s_addc_u32 s29, s29, 0
	s_add_i32 s30, s30, s34
	s_mov_b32 m0, s30
	s_nop 0
	global_load_lds_dwordx4 v130, s[28:29]
	s_add_i32 m0, s30, 0x2000
	s_nop 0
	global_load_lds_dwordx4 v134, s[28:29]
	s_waitcnt vmcnt(6)
	s_setprio 1
	s_barrier
	v_mfma_f32_16x16x32_bf16 v[60:63], v[230:233], v[198:201], v[60:63]
	v_mfma_f32_16x16x32_bf16 v[52:55], v[238:241], v[198:201], v[52:55]
	v_mfma_f32_16x16x32_bf16 v[44:47], v[230:233], v[206:209], v[44:47]
	v_mfma_f32_16x16x32_bf16 v[36:39], v[238:241], v[206:209], v[36:39]
	v_mfma_f32_16x16x32_bf16 v[28:31], v[230:233], v[214:217], v[28:31]
	v_mfma_f32_16x16x32_bf16 v[20:23], v[238:241], v[214:217], v[20:23]
	v_mfma_f32_16x16x32_bf16 v[12:15], v[230:233], v[222:225], v[12:15]
	v_mfma_f32_16x16x32_bf16 v[0:3], v[238:241], v[222:225], v[0:3]
	v_mfma_f32_16x16x32_bf16 v[60:63], v[234:237], v[202:205], v[60:63]
	v_mfma_f32_16x16x32_bf16 v[52:55], v[242:245], v[202:205], v[52:55]
	v_mfma_f32_16x16x32_bf16 v[44:47], v[234:237], v[210:213], v[44:47]
	v_mfma_f32_16x16x32_bf16 v[36:39], v[242:245], v[210:213], v[36:39]
	v_mfma_f32_16x16x32_bf16 v[28:31], v[234:237], v[218:221], v[28:31]
	v_mfma_f32_16x16x32_bf16 v[20:23], v[242:245], v[218:221], v[20:23]
	v_mfma_f32_16x16x32_bf16 v[12:15], v[234:237], v[226:229], v[12:15]
	v_mfma_f32_16x16x32_bf16 v[0:3], v[242:245], v[226:229], v[0:3]
	s_barrier
	s_setprio 0
	s_add_u32 s26, s26, 0x100
	s_addc_u32 s27, s27, 0
	s_add_u32 s60, s60, 0x100
	s_addc_u32 s61, s61, 0
	s_cmp_ge_i32 s62, s11
	s_mov_b32 s28, s62
	s_cbranch_scc0 .LBB0_625
	s_branch .LBB0_616

;     __device__ bool next(int i, Unit& u) const { const int L = i * G + c; if (L >= 64 * 9) return false; u.pm = L; u.pn = L / 9; u.kt0 = 0; u.nt = ntf; u.ks = 0; return true; }
; #define PG8_STAGE(bufoff, gbase, voff) do { _Pragma("unroll") for (int _i = 0; _i < 2; ++_i) \
;         __builtin_amdgcn_global_load_lds((const unsigned*)((const char*)(gbase) + (voff)[_i]), (LAS unsigned*)(lds + (bufoff) + ldsw + _i * 8192), 16, 0, 0); } while (0)
; #define PG8_LDA(dst, b, h) do { _Pragma("unroll") for (int m = 0; m < 4; ++m) _Pragma("unroll") for (int k = 0; k < 2; ++k) dst[m][k] = *(const LAS bf16x8*)(lds + PG8_SA(b, h) + aoff + m * 2048 + k * 1024); } while (0)
; #define PG8_LDB(dst, b, h) do { _Pragma("unroll") for (int n = 0; n < 2; ++n) _Pragma("unroll") for (int k = 0; k < 2; ++k) dst[n][k] = *(const LAS bf16x8*)(lds + PG8_SB(b, h) + boff + n * 2048 + k * 1024); } while (0)
; template <class Epi, class Sched, bool ATILE = false>
; __device__ __forceinline__ void gemm_phase(LAS unsigned char* lds, const Gemm g, const Sched& S, const Epi& E) {
;     ...
;         const bool has_next = S.next(ui + 1, nxt);
;         const char* nA = has_next ? (const char*)g.A + (size_t)nxt.pm * tstepA + (size_t)nxt.kt0 * kstepA : cA; const char* nB = has_next ? (const char*)g.Bt + (size_t)nxt.pn * tstepB + (size_t)nxt.kt0 * kstep : cB;
;         int nt = cur.nt; asm volatile("" : "+s"(nt));
;         for (int t = 0; t < nt; t += 2) {
;             const bool last = (t == nt - 2);
;             const char* a1 = cA + (size_t)(t + 1) * kstepA;
;             const char* a2 = last ? nA : cA + (size_t)(t + 2) * kstepA; const char* b2 = last ? nB : cB + (size_t)(t + 2) * kstep;
;             const char* a3 = a2 + kstepA; const char* b3 = b2 + kstep;
;             PG8_LDB(B0, 0, 0); PG8_SCHED; PG8_LDA(At, 0, 0); PG8_STAGE(PG8_SA(1, 1), a1 + hstepA, voffA);
;             PG8_WAIT_L(8); PG8_BAR; PG8_WAIT_L(0); PG8_MMA(0, 0, At, B0); PG8_BAR; PG8_SCHED;
;             PG8_LDB(B1, 0, 1); PG8_STAGE(PG8_SB(0, 0), b2, voffB);
;             PG8_BAR; PG8_WAIT_L(0); PG8_MMA(0, 1, At, B1); PG8_BAR;
;             PG8_LDA(At, 0, 1); PG8_STAGE(PG8_SA(0, 0), a2, voffA);
;             PG8_BAR; PG8_WAIT_L(0); PG8_MMA(1, 0, At, B0); PG8_BAR; PG8_SCHED;
;             PG8_STAGE(PG8_SB(0, 1), b2 + hstepB, voffB);
;             PG8_WAIT_V(6); PG8_BAR; PG8_MMA(1, 1, At, B1); PG8_BAR;
.LBB0_739:
	ds_read_b128 v[20:23], v165
	ds_read_b128 v[28:31], v165 offset:1024
	ds_read_b128 v[136:139], v165 offset:2048
	ds_read_b128 v[140:143], v165 offset:3072
	s_add_i32 s62, s26, 2
	s_add_u32 s27, s24, 0x4000
	s_addc_u32 s28, s25, 0
	s_cmp_eq_u32 s11, s26
	s_cselect_b32 s30, s20, s27
	s_cselect_b32 s31, s21, s28
	s_cselect_b32 s26, s22, s60
	s_cselect_b32 s27, s23, s61
	s_add_u32 s28, s30, 0x8000
	s_addc_u32 s29, s31, 0
	s_add_i32 m0, s34, 0xc000
	ds_read_b128 v[144:147], v167
	ds_read_b128 v[148:151], v167 offset:1024
	ds_read_b128 v[200:203], v167 offset:2048
	ds_read_b128 v[204:207], v167 offset:3072
	ds_read_b128 v[208:211], v167 offset:4096
	ds_read_b128 v[212:215], v167 offset:5120
	ds_read_b128 v[220:223], v167 offset:6144
	ds_read_b128 v[224:227], v167 offset:7168
	global_load_lds_dwordx4 v194, s[24:25]
	s_add_i32 m0, s34, 0xe000
	s_nop 0
	global_load_lds_dwordx4 v196, s[24:25]
	s_waitcnt lgkmcnt(8)
	s_waitcnt lgkmcnt(0)
	s_setprio 1
	s_barrier
	v_mfma_f32_16x16x32_bf16 v[0:3], v[20:23], v[144:147], v[0:3]
	v_mfma_f32_16x16x32_bf16 v[4:7], v[136:139], v[144:147], v[4:7]
	v_mfma_f32_16x16x32_bf16 v[44:47], v[20:23], v[200:203], v[44:47]
	v_mfma_f32_16x16x32_bf16 v[36:39], v[136:139], v[200:203], v[36:39]
	v_mfma_f32_16x16x32_bf16 v[52:55], v[20:23], v[208:211], v[52:55]
	v_mfma_f32_16x16x32_bf16 v[48:51], v[136:139], v[208:211], v[48:51]
	v_mfma_f32_16x16x32_bf16 v[92:95], v[20:23], v[220:223], v[92:95]
	v_mfma_f32_16x16x32_bf16 v[84:87], v[136:139], v[220:223], v[84:87]
	v_mfma_f32_16x16x32_bf16 v[0:3], v[28:31], v[148:151], v[0:3]
	v_mfma_f32_16x16x32_bf16 v[4:7], v[140:143], v[148:151], v[4:7]
	v_mfma_f32_16x16x32_bf16 v[44:47], v[28:31], v[204:207], v[44:47]
	v_mfma_f32_16x16x32_bf16 v[36:39], v[140:143], v[204:207], v[36:39]
	v_mfma_f32_16x16x32_bf16 v[52:55], v[28:31], v[212:215], v[52:55]
	v_mfma_f32_16x16x32_bf16 v[48:51], v[140:143], v[212:215], v[48:51]
	v_mfma_f32_16x16x32_bf16 v[92:95], v[28:31], v[224:227], v[92:95]
	v_mfma_f32_16x16x32_bf16 v[84:87], v[140:143], v[224:227], v[84:87]
	s_barrier
	s_setprio 0
	s_add_i32 s63, s52, s33
	s_add_u32 s98, s26, s6
	s_addc_u32 s99, s27, s7
	s_mov_b32 m0, s63
	ds_read_b128 v[228:231], v177
	ds_read_b128 v[232:235], v177 offset:1024
	ds_read_b128 v[236:239], v177 offset:2048
	ds_read_b128 v[240:243], v177 offset:3072
	global_load_lds_dwordx4 v170, s[26:27]
	s_add_i32 m0, s63, 0x2000
	s_nop 0
	global_load_lds_dwordx4 v174, s[26:27]
	s_waitcnt lgkmcnt(0)
	s_setprio 1
	s_barrier
	v_mfma_f32_16x16x32_bf16 v[12:15], v[228:231], v[144:147], v[12:15]
	v_mfma_f32_16x16x32_bf16 v[8:11], v[236:239], v[144:147], v[8:11]
	v_mfma_f32_16x16x32_bf16 v[24:27], v[228:231], v[200:203], v[24:27]
	v_mfma_f32_16x16x32_bf16 v[16:19], v[236:239], v[200:203], v[16:19]
	v_mfma_f32_16x16x32_bf16 v[40:43], v[228:231], v[208:211], v[40:43]
	v_mfma_f32_16x16x32_bf16 v[32:35], v[236:239], v[208:211], v[32:35]
	v_mfma_f32_16x16x32_bf16 v[56:59], v[228:231], v[220:223], v[56:59]
	v_mfma_f32_16x16x32_bf16 v[60:63], v[236:239], v[220:223], v[60:63]
	v_mfma_f32_16x16x32_bf16 v[12:15], v[232:235], v[148:151], v[12:15]
	v_mfma_f32_16x16x32_bf16 v[8:11], v[240:243], v[148:151], v[8:11]
	v_mfma_f32_16x16x32_bf16 v[24:27], v[232:235], v[204:207], v[24:27]
	v_mfma_f32_16x16x32_bf16 v[16:19], v[240:243], v[204:207], v[16:19]
	v_mfma_f32_16x16x32_bf16 v[40:43], v[232:235], v[212:215], v[40:43]
	v_mfma_f32_16x16x32_bf16 v[32:35], v[240:243], v[212:215], v[32:35]
	v_mfma_f32_16x16x32_bf16 v[56:59], v[232:235], v[224:227], v[56:59]
	v_mfma_f32_16x16x32_bf16 v[60:63], v[240:243], v[224:227], v[60:63]
	s_barrier
	s_setprio 0
	s_mov_b32 m0, s34
	ds_read_b128 v[144:147], v167 offset:16384
	ds_read_b128 v[148:151], v167 offset:17408
	ds_read_b128 v[200:203], v167 offset:18432
	ds_read_b128 v[204:207], v167 offset:19456
	ds_read_b128 v[208:211], v167 offset:20480
	ds_read_b128 v[212:215], v167 offset:21504
	ds_read_b128 v[220:223], v167 offset:22528
	ds_read_b128 v[224:227], v167 offset:23552
	global_load_lds_dwordx4 v168, s[30:31]
	s_mov_b32 m0, s35
	s_nop 0
	global_load_lds_dwordx4 v172, s[30:31]
	s_waitcnt lgkmcnt(0)
	s_setprio 1
	s_barrier
	v_mfma_f32_16x16x32_bf16 v[64:67], v[20:23], v[144:147], v[64:67]
	v_mfma_f32_16x16x32_bf16 v[68:71], v[136:139], v[144:147], v[68:71]
	v_mfma_f32_16x16x32_bf16 v[108:111], v[20:23], v[200:203], v[108:111]
	v_mfma_f32_16x16x32_bf16 v[100:103], v[136:139], v[200:203], v[100:103]
	v_mfma_f32_16x16x32_bf16 v[116:119], v[20:23], v[208:211], v[116:119]
	v_mfma_f32_16x16x32_bf16 v[112:115], v[136:139], v[208:211], v[112:115]
	v_mfma_f32_16x16x32_bf16 v[20:23], v[20:23], v[220:223], v[132:135]
	v_mfma_f32_16x16x32_bf16 v[64:67], v[28:31], v[148:151], v[64:67]
	v_mfma_f32_16x16x32_bf16 v[68:71], v[140:143], v[148:151], v[68:71]
	v_mfma_f32_16x16x32_bf16 v[108:111], v[28:31], v[204:207], v[108:111]
	v_mfma_f32_16x16x32_bf16 v[100:103], v[140:143], v[204:207], v[100:103]
	v_mfma_f32_16x16x32_bf16 v[116:119], v[28:31], v[212:215], v[116:119]
	v_mfma_f32_16x16x32_bf16 v[112:115], v[140:143], v[212:215], v[112:115]
	v_mfma_f32_16x16x32_bf16 v[20:23], v[28:31], v[224:227], v[20:23]
	v_mfma_f32_16x16x32_bf16 v[28:31], v[136:139], v[220:223], v[128:131]
	v_mfma_f32_16x16x32_bf16 v[28:31], v[140:143], v[224:227], v[28:31]
	s_barrier
	s_setprio 0
	s_add_u32 s64, s26, 0x158000
	s_addc_u32 s65, s27, 0
	s_add_i32 s63, s53, s33
	s_mov_b32 m0, s63
	s_nop 0
	global_load_lds_dwordx4 v170, s[64:65]
	s_add_i32 m0, s63, 0x2000
	s_nop 0
	global_load_lds_dwordx4 v174, s[64:65]
	s_waitcnt vmcnt(6)
	s_setprio 1
	s_barrier
; #define PG8_STAGE(bufoff, gbase, voff) do { _Pragma("unroll") for (int _i = 0; _i < 2; ++_i) \
;         __builtin_amdgcn_global_load_lds((const unsigned*)((const char*)(gbase) + (voff)[_i]), (LAS unsigned*)(lds + (bufoff) + ldsw + _i * 8192), 16, 0, 0); } while (0)
; #define PG8_LDA(dst, b, h) do { _Pragma("unroll") for (int m = 0; m < 4; ++m) _Pragma("unroll") for (int k = 0; k < 2; ++k) dst[m][k] = *(const LAS bf16x8*)(lds + PG8_SA(b, h) + aoff + m * 2048 + k * 1024); } while (0)
; #define PG8_LDB(dst, b, h) do { _Pragma("unroll") for (int n = 0; n < 2; ++n) _Pragma("unroll") for (int k = 0; k < 2; ++k) dst[n][k] = *(const LAS bf16x8*)(lds + PG8_SB(b, h) + boff + n * 2048 + k * 1024); } while (0)
; #define PG8_MMA(ai, bj, At, Bt) do { __builtin_amdgcn_s_setprio(1); _Pragma("unroll") for (int m = 0; m < 4; ++m) _Pragma("unroll") for (int n = 0; n < 2; ++n) _Pragma("unroll") for (int k = 0; k < 2; ++k) \
;         acc[ai][bj][m][n] = __builtin_amdgcn_mfma_f32_16x16x32_bf16(Bt[n][k], At[m][k], acc[ai][bj][m][n], 0, 0, 0); __builtin_amdgcn_s_setprio(0); } while (0)
; #define PG8_WAIT_V(n) asm volatile("s_waitcnt vmcnt(" #n ")" ::: "memory")
; #define PG8_WAIT_L(n) asm volatile("s_waitcnt lgkmcnt(" #n ")" ::: "memory")
; #define PG8_BAR __builtin_amdgcn_s_barrier()
; #define PG8_SCHED __builtin_amdgcn_sched_barrier(0)
; template <class Epi, class Sched, bool ATILE = false>
; __device__ __forceinline__ void gemm_phase(LAS unsigned char* lds, const Gemm g, const Sched& S, const Epi& E) {
;     ...
;             PG8_WAIT_V(6); PG8_BAR; PG8_MMA(1, 1, At, B1); PG8_BAR;
;             PG8_LDB(B0, 1, 0); PG8_SCHED; PG8_LDA(At, 1, 0); PG8_STAGE(PG8_SA(0, 1), a2 + hstepA, voffA);
;             PG8_WAIT_L(8); PG8_BAR; PG8_WAIT_L(0); PG8_MMA(0, 0, At, B0); PG8_BAR; PG8_SCHED;
;             PG8_LDB(B1, 1, 1); PG8_STAGE(PG8_SB(1, 0), b3, voffB);
;             PG8_BAR; PG8_WAIT_L(0); PG8_MMA(0, 1, At, B1); PG8_BAR;
;             PG8_LDA(At, 1, 1); PG8_STAGE(PG8_SA(1, 0), a3, voffA);
;             PG8_BAR; PG8_WAIT_L(0); PG8_MMA(1, 0, At, B0); PG8_BAR; PG8_SCHED;
	v_mfma_f32_16x16x32_bf16 v[76:79], v[228:231], v[144:147], v[76:79]
	v_mfma_f32_16x16x32_bf16 v[72:75], v[236:239], v[144:147], v[72:75]
	v_mfma_f32_16x16x32_bf16 v[88:91], v[228:231], v[200:203], v[88:91]
	v_mfma_f32_16x16x32_bf16 v[80:83], v[236:239], v[200:203], v[80:83]
	v_mfma_f32_16x16x32_bf16 v[104:107], v[228:231], v[208:211], v[104:107]
	v_mfma_f32_16x16x32_bf16 v[96:99], v[236:239], v[208:211], v[96:99]
	v_mfma_f32_16x16x32_bf16 v[120:123], v[228:231], v[220:223], v[120:123]
	v_mfma_f32_16x16x32_bf16 v[124:127], v[236:239], v[220:223], v[124:127]
	v_mfma_f32_16x16x32_bf16 v[76:79], v[232:235], v[148:151], v[76:79]
	v_mfma_f32_16x16x32_bf16 v[72:75], v[240:243], v[148:151], v[72:75]
	v_mfma_f32_16x16x32_bf16 v[88:91], v[232:235], v[204:207], v[88:91]
	v_mfma_f32_16x16x32_bf16 v[80:83], v[240:243], v[204:207], v[80:83]
	v_mfma_f32_16x16x32_bf16 v[104:107], v[232:235], v[212:215], v[104:107]
	v_mfma_f32_16x16x32_bf16 v[96:99], v[240:243], v[212:215], v[96:99]
	v_mfma_f32_16x16x32_bf16 v[120:123], v[232:235], v[224:227], v[120:123]
	v_mfma_f32_16x16x32_bf16 v[124:127], v[240:243], v[224:227], v[124:127]
	s_barrier
	s_setprio 0
	s_add_i32 s63, 0, 0x18000
	v_add_u32_e32 v140, s63, v161
	ds_read_b128 v[128:131], v140
	ds_read_b128 v[132:135], v140 offset:1024
	ds_read_b128 v[136:139], v140 offset:2048
	ds_read_b128 v[140:143], v140 offset:3072
	s_add_u32 s30, s30, 0x4000
	s_addc_u32 s31, s31, 0
	s_mov_b32 m0, s36
	ds_read_b128 v[144:147], v167 offset:32768
	ds_read_b128 v[148:151], v167 offset:33792
	ds_read_b128 v[200:203], v167 offset:34816
	ds_read_b128 v[204:207], v167 offset:35840
	ds_read_b128 v[208:211], v167 offset:36864
	ds_read_b128 v[212:215], v167 offset:37888
	ds_read_b128 v[220:223], v167 offset:38912
	ds_read_b128 v[224:227], v167 offset:39936
	global_load_lds_dwordx4 v168, s[30:31]
	s_mov_b32 m0, s37
	s_nop 0
	global_load_lds_dwordx4 v172, s[30:31]
	s_waitcnt lgkmcnt(8)
	s_waitcnt lgkmcnt(0)
	s_setprio 1
	s_barrier
	v_mfma_f32_16x16x32_bf16 v[0:3], v[128:131], v[144:147], v[0:3]
	v_mfma_f32_16x16x32_bf16 v[4:7], v[136:139], v[144:147], v[4:7]
	v_mfma_f32_16x16x32_bf16 v[44:47], v[128:131], v[200:203], v[44:47]
	v_mfma_f32_16x16x32_bf16 v[36:39], v[136:139], v[200:203], v[36:39]
	v_mfma_f32_16x16x32_bf16 v[52:55], v[128:131], v[208:211], v[52:55]
	v_mfma_f32_16x16x32_bf16 v[48:51], v[136:139], v[208:211], v[48:51]
	v_mfma_f32_16x16x32_bf16 v[92:95], v[128:131], v[220:223], v[92:95]
	v_mfma_f32_16x16x32_bf16 v[84:87], v[136:139], v[220:223], v[84:87]
	v_mfma_f32_16x16x32_bf16 v[0:3], v[132:135], v[148:151], v[0:3]
	v_mfma_f32_16x16x32_bf16 v[4:7], v[140:143], v[148:151], v[4:7]
	v_mfma_f32_16x16x32_bf16 v[44:47], v[132:135], v[204:207], v[44:47]
	v_mfma_f32_16x16x32_bf16 v[36:39], v[140:143], v[204:207], v[36:39]
	v_mfma_f32_16x16x32_bf16 v[52:55], v[132:135], v[212:215], v[52:55]
	v_mfma_f32_16x16x32_bf16 v[48:51], v[140:143], v[212:215], v[48:51]
	v_mfma_f32_16x16x32_bf16 v[92:95], v[132:135], v[224:227], v[92:95]
	v_mfma_f32_16x16x32_bf16 v[84:87], v[140:143], v[224:227], v[84:87]
	s_barrier
	s_setprio 0
	s_add_i32 s30, 0, 0x1c000
	s_add_i32 s31, s63, s33
	v_add_u32_e32 v219, s30, v161
	s_mov_b32 m0, s31
	ds_read_b128 v[228:231], v219
	ds_read_b128 v[232:235], v219 offset:1024
	ds_read_b128 v[236:239], v219 offset:2048
	ds_read_b128 v[240:243], v219 offset:3072
	global_load_lds_dwordx4 v170, s[98:99]
	s_add_i32 m0, s31, 0x2000
	s_nop 0
	global_load_lds_dwordx4 v174, s[98:99]
	s_waitcnt lgkmcnt(0)
	s_setprio 1
	s_barrier
	v_mfma_f32_16x16x32_bf16 v[12:15], v[228:231], v[144:147], v[12:15]
	v_mfma_f32_16x16x32_bf16 v[8:11], v[236:239], v[144:147], v[8:11]
	v_mfma_f32_16x16x32_bf16 v[24:27], v[228:231], v[200:203], v[24:27]
	v_mfma_f32_16x16x32_bf16 v[16:19], v[236:239], v[200:203], v[16:19]
	v_mfma_f32_16x16x32_bf16 v[40:43], v[228:231], v[208:211], v[40:43]
	v_mfma_f32_16x16x32_bf16 v[32:35], v[236:239], v[208:211], v[32:35]
	v_mfma_f32_16x16x32_bf16 v[56:59], v[228:231], v[220:223], v[56:59]
	v_mfma_f32_16x16x32_bf16 v[60:63], v[236:239], v[220:223], v[60:63]
	v_mfma_f32_16x16x32_bf16 v[12:15], v[232:235], v[148:151], v[12:15]
	v_mfma_f32_16x16x32_bf16 v[8:11], v[240:243], v[148:151], v[8:11]
	v_mfma_f32_16x16x32_bf16 v[24:27], v[232:235], v[204:207], v[24:27]
	v_mfma_f32_16x16x32_bf16 v[16:19], v[240:243], v[204:207], v[16:19]
	v_mfma_f32_16x16x32_bf16 v[40:43], v[232:235], v[212:215], v[40:43]
	v_mfma_f32_16x16x32_bf16 v[32:35], v[240:243], v[212:215], v[32:35]
	v_mfma_f32_16x16x32_bf16 v[56:59], v[232:235], v[224:227], v[56:59]
	v_mfma_f32_16x16x32_bf16 v[60:63], v[240:243], v[224:227], v[60:63]
	s_barrier
	s_setprio 0
	s_mov_b32 m0, s39
	ds_read_b128 v[144:147], v167 offset:49152
	ds_read_b128 v[148:151], v167 offset:50176
	ds_read_b128 v[200:203], v167 offset:51200
	ds_read_b128 v[204:207], v167 offset:52224
	ds_read_b128 v[208:211], v167 offset:53248
	ds_read_b128 v[212:215], v167 offset:54272
	ds_read_b128 v[220:223], v167 offset:55296
	ds_read_b128 v[224:227], v167 offset:56320
	global_load_lds_dwordx4 v168, s[28:29]
	s_mov_b32 m0, s40
	s_nop 0
	global_load_lds_dwordx4 v172, s[28:29]
	s_waitcnt lgkmcnt(0)
	s_setprio 1
	s_barrier
; __device__ __forceinline__ float bflo(unsigned w) { return __uint_as_float(w << 16); }
; __device__ __forceinline__ float bfhi(unsigned w) { return __uint_as_float(w & 0xffff0000u); }
; #define PG8_STAGE(bufoff, gbase, voff) do { _Pragma("unroll") for (int _i = 0; _i < 2; ++_i) \
;         __builtin_amdgcn_global_load_lds((const unsigned*)((const char*)(gbase) + (voff)[_i]), (LAS unsigned*)(lds + (bufoff) + ldsw + _i * 8192), 16, 0, 0); } while (0)
; #define PG8_MMA(ai, bj, At, Bt) do { __builtin_amdgcn_s_setprio(1); _Pragma("unroll") for (int m = 0; m < 4; ++m) _Pragma("unroll") for (int n = 0; n < 2; ++n) _Pragma("unroll") for (int k = 0; k < 2; ++k) \
;         acc[ai][bj][m][n] = __builtin_amdgcn_mfma_f32_16x16x32_bf16(Bt[n][k], At[m][k], acc[ai][bj][m][n], 0, 0, 0); __builtin_amdgcn_s_setprio(0); } while (0)
; #define PG8_WAIT_V(n) asm volatile("s_waitcnt vmcnt(" #n ")" ::: "memory")
; #define PG8_WAIT_L(n) asm volatile("s_waitcnt lgkmcnt(" #n ")" ::: "memory")
; #define PG8_BAR __builtin_amdgcn_s_barrier()
; #define PG8_SCHED __builtin_amdgcn_sched_barrier(0)
; template <class Epi, class Sched, bool ATILE = false>
; __device__ __forceinline__ void gemm_phase(LAS unsigned char* lds, const Gemm g, const Sched& S, const Epi& E) {
;     ...
;             PG8_BAR; PG8_WAIT_L(0); PG8_MMA(1, 0, At, B0); PG8_BAR; PG8_SCHED;
;             PG8_STAGE(PG8_SB(1, 1), b3 + hstepB, voffB);
;             PG8_WAIT_V(6); PG8_BAR; PG8_MMA(1, 1, At, B1); PG8_BAR;
;         }
;     __device__ __forceinline__ void operator()(const f32x4 (&acc)[2][2][4][2], const Unit& u, int wr, int wc, int fr, int fq) const {
;     ...
;                     const f32x4 v0 = (f32x4){bflo(x.x), bfhi(x.x), bflo(x.y), bfhi(x.y)} + alpha * acc[ai][bj][m][0];
;                     const f32x4 v1 = (f32x4){bflo(x.z), bfhi(x.z), bflo(x.w), bfhi(x.w)} + alpha * acc[ai][bj][m][1];
	v_mfma_f32_16x16x32_bf16 v[64:67], v[128:131], v[144:147], v[64:67]
	v_mfma_f32_16x16x32_bf16 v[108:111], v[128:131], v[200:203], v[108:111]
	v_mfma_f32_16x16x32_bf16 v[116:119], v[128:131], v[208:211], v[116:119]
	v_mfma_f32_16x16x32_bf16 v[20:23], v[128:131], v[220:223], v[20:23]
	v_mfma_f32_16x16x32_bf16 v[64:67], v[132:135], v[148:151], v[64:67]
	v_mfma_f32_16x16x32_bf16 v[68:71], v[136:139], v[144:147], v[68:71]
	v_mfma_f32_16x16x32_bf16 v[108:111], v[132:135], v[204:207], v[108:111]
	v_mfma_f32_16x16x32_bf16 v[100:103], v[136:139], v[200:203], v[100:103]
	v_mfma_f32_16x16x32_bf16 v[116:119], v[132:135], v[212:215], v[116:119]
	v_mfma_f32_16x16x32_bf16 v[112:115], v[136:139], v[208:211], v[112:115]
	v_mfma_f32_16x16x32_bf16 v[132:135], v[132:135], v[224:227], v[20:23]
	v_mfma_f32_16x16x32_bf16 v[20:23], v[136:139], v[220:223], v[28:31]
	v_mfma_f32_16x16x32_bf16 v[68:71], v[140:143], v[148:151], v[68:71]
	v_mfma_f32_16x16x32_bf16 v[100:103], v[140:143], v[204:207], v[100:103]
	v_mfma_f32_16x16x32_bf16 v[112:115], v[140:143], v[212:215], v[112:115]
	v_mfma_f32_16x16x32_bf16 v[128:131], v[140:143], v[224:227], v[20:23]
	s_barrier
	s_setprio 0
	s_add_u32 s26, s26, 0x158080
	s_addc_u32 s27, s27, 0
	s_add_i32 s28, s30, s33
	s_mov_b32 m0, s28
	s_nop 0
	global_load_lds_dwordx4 v170, s[26:27]
	s_add_i32 m0, s28, 0x2000
	s_nop 0
	global_load_lds_dwordx4 v174, s[26:27]
	s_waitcnt vmcnt(6)
	s_setprio 1
	s_barrier
	v_mfma_f32_16x16x32_bf16 v[20:23], v[228:231], v[144:147], v[76:79]
	v_mfma_f32_16x16x32_bf16 v[76:79], v[232:235], v[148:151], v[20:23]
	v_mfma_f32_16x16x32_bf16 v[20:23], v[236:239], v[144:147], v[72:75]
	v_mfma_f32_16x16x32_bf16 v[72:75], v[240:243], v[148:151], v[20:23]
	v_mfma_f32_16x16x32_bf16 v[20:23], v[228:231], v[200:203], v[88:91]
	v_mfma_f32_16x16x32_bf16 v[88:91], v[232:235], v[204:207], v[20:23]
	v_mfma_f32_16x16x32_bf16 v[20:23], v[236:239], v[200:203], v[80:83]
	v_mfma_f32_16x16x32_bf16 v[80:83], v[240:243], v[204:207], v[20:23]
	v_mfma_f32_16x16x32_bf16 v[20:23], v[228:231], v[208:211], v[104:107]
	v_mfma_f32_16x16x32_bf16 v[104:107], v[232:235], v[212:215], v[20:23]
	v_mfma_f32_16x16x32_bf16 v[20:23], v[236:239], v[208:211], v[96:99]
	v_mfma_f32_16x16x32_bf16 v[96:99], v[240:243], v[212:215], v[20:23]
	v_mfma_f32_16x16x32_bf16 v[20:23], v[228:231], v[220:223], v[120:123]
	v_mfma_f32_16x16x32_bf16 v[120:123], v[232:235], v[224:227], v[20:23]
	v_mfma_f32_16x16x32_bf16 v[20:23], v[236:239], v[220:223], v[124:127]
	v_mfma_f32_16x16x32_bf16 v[124:127], v[240:243], v[224:227], v[20:23]
	s_barrier
	s_setprio 0
	s_add_u32 s60, s60, 0x100
	s_addc_u32 s61, s61, 0
	s_add_u32 s24, s24, 0x10000
	s_addc_u32 s25, s25, 0
	s_cmp_ge_i32 s62, s59
	s_mov_b32 s26, s62
	s_cbranch_scc0 .LBB0_739
	v_pk_mul_f32 v[2:3], v[2:3], 0.5 op_sel_hi:[1,0]
	v_pk_mul_f32 v[0:1], v[0:1], 0.5 op_sel_hi:[1,0]
	v_pk_mul_f32 v[6:7], v[6:7], 0.5 op_sel_hi:[1,0]
	v_pk_mul_f32 v[4:5], v[4:5], 0.5 op_sel_hi:[1,0]
	v_pk_mul_f32 v[22:23], v[14:15], 0.5 op_sel_hi:[1,0]
	v_pk_mul_f32 v[20:21], v[12:13], 0.5 op_sel_hi:[1,0]
	v_pk_mul_f32 v[30:31], v[10:11], 0.5 op_sel_hi:[1,0]
	v_pk_mul_f32 v[28:29], v[8:9], 0.5 op_sel_hi:[1,0]
	v_pk_mul_f32 v[10:11], v[46:47], 0.5 op_sel_hi:[1,0]
	v_pk_mul_f32 v[8:9], v[44:45], 0.5 op_sel_hi:[1,0]
	v_pk_mul_f32 v[14:15], v[38:39], 0.5 op_sel_hi:[1,0]
	v_pk_mul_f32 v[12:13], v[36:37], 0.5 op_sel_hi:[1,0]
	v_pk_mul_f32 v[38:39], v[26:27], 0.5 op_sel_hi:[1,0]
	v_pk_mul_f32 v[36:37], v[24:25], 0.5 op_sel_hi:[1,0]
	v_pk_mul_f32 v[46:47], v[18:19], 0.5 op_sel_hi:[1,0]
	v_pk_mul_f32 v[44:45], v[16:17], 0.5 op_sel_hi:[1,0]
	v_pk_mul_f32 v[18:19], v[54:55], 0.5 op_sel_hi:[1,0]
	v_pk_mul_f32 v[16:17], v[52:53], 0.5 op_sel_hi:[1,0]
	v_pk_mul_f32 v[26:27], v[50:51], 0.5 op_sel_hi:[1,0]
	v_pk_mul_f32 v[24:25], v[48:49], 0.5 op_sel_hi:[1,0]
	v_pk_mul_f32 v[50:51], v[42:43], 0.5 op_sel_hi:[1,0]
	v_pk_mul_f32 v[48:49], v[40:41], 0.5 op_sel_hi:[1,0]
	v_pk_mul_f32 v[54:55], v[34:35], 0.5 op_sel_hi:[1,0]
	v_pk_mul_f32 v[52:53], v[32:33], 0.5 op_sel_hi:[1,0]
	v_pk_mul_f32 v[34:35], v[94:95], 0.5 op_sel_hi:[1,0]
	v_pk_mul_f32 v[32:33], v[92:93], 0.5 op_sel_hi:[1,0]
	v_pk_mul_f32 v[42:43], v[86:87], 0.5 op_sel_hi:[1,0]
	v_pk_mul_f32 v[40:41], v[84:85], 0.5 op_sel_hi:[1,0]
	v_pk_mul_f32 v[58:59], v[58:59], 0.5 op_sel_hi:[1,0]
	v_pk_mul_f32 v[56:57], v[56:57], 0.5 op_sel_hi:[1,0]
	v_pk_mul_f32 v[62:63], v[62:63], 0.5 op_sel_hi:[1,0]
	v_pk_mul_f32 v[60:61], v[60:61], 0.5 op_sel_hi:[1,0]
	v_pk_mul_f32 v[66:67], v[66:67], 0.5 op_sel_hi:[1,0]
	v_pk_mul_f32 v[64:65], v[64:65], 0.5 op_sel_hi:[1,0]
	v_pk_mul_f32 v[70:71], v[70:71], 0.5 op_sel_hi:[1,0]
	v_pk_mul_f32 v[68:69], v[68:69], 0.5 op_sel_hi:[1,0]
	v_pk_mul_f32 v[86:87], v[78:79], 0.5 op_sel_hi:[1,0]
	v_pk_mul_f32 v[84:85], v[76:77], 0.5 op_sel_hi:[1,0]
	v_pk_mul_f32 v[94:95], v[74:75], 0.5 op_sel_hi:[1,0]
	v_pk_mul_f32 v[92:93], v[72:73], 0.5 op_sel_hi:[1,0]
	v_pk_mul_f32 v[74:75], v[110:111], 0.5 op_sel_hi:[1,0]
	v_pk_mul_f32 v[72:73], v[108:109], 0.5 op_sel_hi:[1,0]
	v_pk_mul_f32 v[78:79], v[102:103], 0.5 op_sel_hi:[1,0]
	v_pk_mul_f32 v[76:77], v[100:101], 0.5 op_sel_hi:[1,0]
	v_pk_mul_f32 v[102:103], v[90:91], 0.5 op_sel_hi:[1,0]
	v_pk_mul_f32 v[100:101], v[88:89], 0.5 op_sel_hi:[1,0]
	v_pk_mul_f32 v[110:111], v[82:83], 0.5 op_sel_hi:[1,0]
	v_pk_mul_f32 v[108:109], v[80:81], 0.5 op_sel_hi:[1,0]
	v_pk_mul_f32 v[82:83], v[118:119], 0.5 op_sel_hi:[1,0]
	v_pk_mul_f32 v[80:81], v[116:117], 0.5 op_sel_hi:[1,0]
	v_pk_mul_f32 v[90:91], v[114:115], 0.5 op_sel_hi:[1,0]
	v_pk_mul_f32 v[88:89], v[112:113], 0.5 op_sel_hi:[1,0]
	v_pk_mul_f32 v[114:115], v[106:107], 0.5 op_sel_hi:[1,0]
	v_pk_mul_f32 v[112:113], v[104:105], 0.5 op_sel_hi:[1,0]
	v_pk_mul_f32 v[118:119], v[98:99], 0.5 op_sel_hi:[1,0]
	v_pk_mul_f32 v[116:117], v[96:97], 0.5 op_sel_hi:[1,0]
	v_pk_mul_f32 v[98:99], v[134:135], 0.5 op_sel_hi:[1,0]
	v_pk_mul_f32 v[96:97], v[132:133], 0.5 op_sel_hi:[1,0]
	v_pk_mul_f32 v[106:107], v[130:131], 0.5 op_sel_hi:[1,0]
	v_pk_mul_f32 v[104:105], v[128:129], 0.5 op_sel_hi:[1,0]
	v_pk_mul_f32 v[122:123], v[122:123], 0.5 op_sel_hi:[1,0]
	v_pk_mul_f32 v[120:121], v[120:121], 0.5 op_sel_hi:[1,0]
	v_pk_mul_f32 v[126:127], v[126:127], 0.5 op_sel_hi:[1,0]
	v_pk_mul_f32 v[124:125], v[124:125], 0.5 op_sel_hi:[1,0]
	s_branch .LBB0_744

;     __device__ bool next(int i, Unit& u) const { const int L = i * G + c; if (L >= 64 * 9) return false; u.pm = L; u.pn = L / 9; u.kt0 = 0; u.nt = ntf; u.ks = 0; return true; }
; #define PG8_STAGE(bufoff, gbase, voff) do { _Pragma("unroll") for (int _i = 0; _i < 2; ++_i) \
;         __builtin_amdgcn_global_load_lds((const unsigned*)((const char*)(gbase) + (voff)[_i]), (LAS unsigned*)(lds + (bufoff) + ldsw + _i * 8192), 16, 0, 0); } while (0)
; #define PG8_LDA(dst, b, h) do { _Pragma("unroll") for (int m = 0; m < 4; ++m) _Pragma("unroll") for (int k = 0; k < 2; ++k) dst[m][k] = *(const LAS bf16x8*)(lds + PG8_SA(b, h) + aoff + m * 2048 + k * 1024); } while (0)
; #define PG8_LDB(dst, b, h) do { _Pragma("unroll") for (int n = 0; n < 2; ++n) _Pragma("unroll") for (int k = 0; k < 2; ++k) dst[n][k] = *(const LAS bf16x8*)(lds + PG8_SB(b, h) + boff + n * 2048 + k * 1024); } while (0)
; template <class Epi, class Sched, bool ATILE = false>
; __device__ __forceinline__ void gemm_phase(LAS unsigned char* lds, const Gemm g, const Sched& S, const Epi& E) {
;     ...
;         const bool has_next = S.next(ui + 1, nxt);
;         const char* nA = has_next ? (const char*)g.A + (size_t)nxt.pm * tstepA + (size_t)nxt.kt0 * kstepA : cA; const char* nB = has_next ? (const char*)g.Bt + (size_t)nxt.pn * tstepB + (size_t)nxt.kt0 * kstep : cB;
;         int nt = cur.nt; asm volatile("" : "+s"(nt));
;         for (int t = 0; t < nt; t += 2) {
;             const bool last = (t == nt - 2);
;             const char* a1 = cA + (size_t)(t + 1) * kstepA;
;             const char* a2 = last ? nA : cA + (size_t)(t + 2) * kstepA; const char* b2 = last ? nB : cB + (size_t)(t + 2) * kstep;
;             const char* a3 = a2 + kstepA; const char* b3 = b2 + kstep;
;             PG8_LDB(B0, 0, 0); PG8_SCHED; PG8_LDA(At, 0, 0); PG8_STAGE(PG8_SA(1, 1), a1 + hstepA, voffA);
;             PG8_WAIT_L(8); PG8_BAR; PG8_WAIT_L(0); PG8_MMA(0, 0, At, B0); PG8_BAR; PG8_SCHED;
;             PG8_LDB(B1, 0, 1); PG8_STAGE(PG8_SB(0, 0), b2, voffB);
;             PG8_BAR; PG8_WAIT_L(0); PG8_MMA(0, 1, At, B1); PG8_BAR;
;             PG8_LDA(At, 0, 1); PG8_STAGE(PG8_SA(0, 0), a2, voffA);
;             PG8_BAR; PG8_WAIT_L(0); PG8_MMA(1, 0, At, B0); PG8_BAR; PG8_SCHED;
;             PG8_STAGE(PG8_SB(0, 1), b2 + hstepB, voffB);
;             PG8_WAIT_V(6); PG8_BAR; PG8_MMA(1, 1, At, B1); PG8_BAR;
.LBB0_895:
	ds_read_b128 v[32:35], v165
	ds_read_b128 v[36:39], v165 offset:1024
	ds_read_b128 v[178:181], v165 offset:2048
	ds_read_b128 v[182:185], v165 offset:3072
	s_add_i32 s88, s73, 2
	s_add_u32 s84, s12, 0xfff80080
	s_addc_u32 s85, s13, -1
	s_cmp_eq_u32 s53, s73
	s_cselect_b32 s87, s11, s85
	s_cselect_b32 s86, s20, s84
	s_cselect_b32 s85, s41, s63
	s_cselect_b32 s84, s52, s62
	s_add_i32 m0, s35, 0xc000
	ds_read_b128 v[192:195], v167
	ds_read_b128 v[196:199], v167 offset:1024
	ds_read_b128 v[200:203], v167 offset:2048
	ds_read_b128 v[204:207], v167 offset:3072
	ds_read_b128 v[208:211], v167 offset:4096
	ds_read_b128 v[212:215], v167 offset:5120
	ds_read_b128 v[216:219], v167 offset:6144
	ds_read_b128 v[220:223], v167 offset:7168
	global_load_lds_dwordx4 v170, s[12:13]
	s_add_i32 m0, s35, 0xe000
	s_nop 0
	global_load_lds_dwordx4 v172, s[12:13]
	s_waitcnt lgkmcnt(8)
	s_waitcnt lgkmcnt(0)
	s_setprio 1
	s_barrier
	v_mfma_f32_16x16x32_bf16 v[132:135], v[32:35], v[192:195], v[132:135]
	v_mfma_f32_16x16x32_bf16 v[128:131], v[178:181], v[192:195], v[128:131]
	v_mfma_f32_16x16x32_bf16 v[116:119], v[32:35], v[200:203], v[116:119]
	v_mfma_f32_16x16x32_bf16 v[112:115], v[178:181], v[200:203], v[112:115]
	v_mfma_f32_16x16x32_bf16 v[100:103], v[32:35], v[208:211], v[100:103]
	v_mfma_f32_16x16x32_bf16 v[96:99], v[178:181], v[208:211], v[96:99]
	v_mfma_f32_16x16x32_bf16 v[84:87], v[32:35], v[216:219], v[84:87]
	v_mfma_f32_16x16x32_bf16 v[80:83], v[178:181], v[216:219], v[80:83]
	v_mfma_f32_16x16x32_bf16 v[132:135], v[36:39], v[196:199], v[132:135]
	v_mfma_f32_16x16x32_bf16 v[128:131], v[182:185], v[196:199], v[128:131]
	v_mfma_f32_16x16x32_bf16 v[116:119], v[36:39], v[204:207], v[116:119]
	v_mfma_f32_16x16x32_bf16 v[112:115], v[182:185], v[204:207], v[112:115]
	v_mfma_f32_16x16x32_bf16 v[100:103], v[36:39], v[212:215], v[100:103]
	v_mfma_f32_16x16x32_bf16 v[96:99], v[182:185], v[212:215], v[96:99]
	v_mfma_f32_16x16x32_bf16 v[84:87], v[36:39], v[220:223], v[84:87]
	v_mfma_f32_16x16x32_bf16 v[80:83], v[182:185], v[220:223], v[80:83]
	s_barrier
	s_setprio 0
	s_add_i32 s73, s43, s31
	s_add_u32 s98, s84, s22
	s_addc_u32 s99, s85, s23
	s_mov_b32 m0, s73
	ds_read_b128 v[224:227], v186
	ds_read_b128 v[228:231], v186 offset:1024
	ds_read_b128 v[232:235], v186 offset:2048
	ds_read_b128 v[236:239], v186 offset:3072
	global_load_lds_dwordx4 v138, s[84:85]
	s_add_i32 m0, s73, 0x2000
	s_nop 0
	global_load_lds_dwordx4 v142, s[84:85]
	s_waitcnt lgkmcnt(0)
	s_setprio 1
	s_barrier
	v_mfma_f32_16x16x32_bf16 v[124:127], v[224:227], v[192:195], v[124:127]
	v_mfma_f32_16x16x32_bf16 v[120:123], v[232:235], v[192:195], v[120:123]
	v_mfma_f32_16x16x32_bf16 v[108:111], v[224:227], v[200:203], v[108:111]
	v_mfma_f32_16x16x32_bf16 v[104:107], v[232:235], v[200:203], v[104:107]
	v_mfma_f32_16x16x32_bf16 v[92:95], v[224:227], v[208:211], v[92:95]
	v_mfma_f32_16x16x32_bf16 v[88:91], v[232:235], v[208:211], v[88:91]
	v_mfma_f32_16x16x32_bf16 v[76:79], v[224:227], v[216:219], v[76:79]
	v_mfma_f32_16x16x32_bf16 v[72:75], v[232:235], v[216:219], v[72:75]
	v_mfma_f32_16x16x32_bf16 v[124:127], v[228:231], v[196:199], v[124:127]
	v_mfma_f32_16x16x32_bf16 v[120:123], v[236:239], v[196:199], v[120:123]
	v_mfma_f32_16x16x32_bf16 v[108:111], v[228:231], v[204:207], v[108:111]
	v_mfma_f32_16x16x32_bf16 v[104:107], v[236:239], v[204:207], v[104:107]
	v_mfma_f32_16x16x32_bf16 v[92:95], v[228:231], v[212:215], v[92:95]
	v_mfma_f32_16x16x32_bf16 v[88:91], v[236:239], v[212:215], v[88:91]
	v_mfma_f32_16x16x32_bf16 v[76:79], v[228:231], v[220:223], v[76:79]
	v_mfma_f32_16x16x32_bf16 v[72:75], v[236:239], v[220:223], v[72:75]
	s_barrier
	s_setprio 0
	s_mov_b32 m0, s35
	s_add_u32 s100, s86, s22
	s_addc_u32 s101, s87, s23
	ds_read_b128 v[192:195], v167 offset:16384
	ds_read_b128 v[196:199], v167 offset:17408
	ds_read_b128 v[200:203], v167 offset:18432
	ds_read_b128 v[204:207], v167 offset:19456
	ds_read_b128 v[208:211], v167 offset:20480
	ds_read_b128 v[212:215], v167 offset:21504
	ds_read_b128 v[216:219], v167 offset:22528
	ds_read_b128 v[220:223], v167 offset:23552
	global_load_lds_dwordx4 v136, s[86:87]
	s_mov_b32 m0, s37
	s_nop 0
	global_load_lds_dwordx4 v140, s[86:87]
	s_waitcnt lgkmcnt(0)
	s_setprio 1
	s_barrier
	v_mfma_f32_16x16x32_bf16 v[68:71], v[32:35], v[192:195], v[68:71]
	v_mfma_f32_16x16x32_bf16 v[64:67], v[178:181], v[192:195], v[64:67]
	v_mfma_f32_16x16x32_bf16 v[52:55], v[32:35], v[200:203], v[52:55]
	v_mfma_f32_16x16x32_bf16 v[48:51], v[178:181], v[200:203], v[48:51]
	v_mfma_f32_16x16x32_bf16 v[28:31], v[32:35], v[208:211], v[28:31]
	v_mfma_f32_16x16x32_bf16 v[24:27], v[178:181], v[208:211], v[24:27]
	v_mfma_f32_16x16x32_bf16 v[12:15], v[32:35], v[216:219], v[12:15]
	v_mfma_f32_16x16x32_bf16 v[8:11], v[178:181], v[216:219], v[8:11]
	v_mfma_f32_16x16x32_bf16 v[68:71], v[36:39], v[196:199], v[68:71]
	v_mfma_f32_16x16x32_bf16 v[64:67], v[182:185], v[196:199], v[64:67]
	v_mfma_f32_16x16x32_bf16 v[52:55], v[36:39], v[204:207], v[52:55]
	v_mfma_f32_16x16x32_bf16 v[48:51], v[182:185], v[204:207], v[48:51]
	v_mfma_f32_16x16x32_bf16 v[28:31], v[36:39], v[212:215], v[28:31]
	v_mfma_f32_16x16x32_bf16 v[24:27], v[182:185], v[212:215], v[24:27]
	v_mfma_f32_16x16x32_bf16 v[12:15], v[36:39], v[220:223], v[12:15]
	v_mfma_f32_16x16x32_bf16 v[8:11], v[182:185], v[220:223], v[8:11]
	s_barrier
	s_setprio 0
	s_add_u32 vcc_lo, s84, 0x80000
	s_addc_u32 vcc_hi, s85, 0
	s_add_i32 s73, s56, s31
	v_lshl_add_u64 v[32:33], vcc, 0, v[138:139]
	s_mov_b32 m0, s73
	s_nop 0
	global_load_lds_dwordx4 v[32:33], off
	v_lshl_add_u64 v[32:33], vcc, 0, v[142:143]
	s_add_i32 m0, s73, 0x2000
	s_nop 0
	global_load_lds_dwordx4 v[32:33], off
	s_waitcnt vmcnt(6)
	s_setprio 1
	s_barrier
; #define PG8_STAGE(bufoff, gbase, voff) do { _Pragma("unroll") for (int _i = 0; _i < 2; ++_i) \
;         __builtin_amdgcn_global_load_lds((const unsigned*)((const char*)(gbase) + (voff)[_i]), (LAS unsigned*)(lds + (bufoff) + ldsw + _i * 8192), 16, 0, 0); } while (0)
; #define PG8_LDA(dst, b, h) do { _Pragma("unroll") for (int m = 0; m < 4; ++m) _Pragma("unroll") for (int k = 0; k < 2; ++k) dst[m][k] = *(const LAS bf16x8*)(lds + PG8_SA(b, h) + aoff + m * 2048 + k * 1024); } while (0)
; #define PG8_LDB(dst, b, h) do { _Pragma("unroll") for (int n = 0; n < 2; ++n) _Pragma("unroll") for (int k = 0; k < 2; ++k) dst[n][k] = *(const LAS bf16x8*)(lds + PG8_SB(b, h) + boff + n * 2048 + k * 1024); } while (0)
; #define PG8_MMA(ai, bj, At, Bt) do { __builtin_amdgcn_s_setprio(1); _Pragma("unroll") for (int m = 0; m < 4; ++m) _Pragma("unroll") for (int n = 0; n < 2; ++n) _Pragma("unroll") for (int k = 0; k < 2; ++k) \
;         acc[ai][bj][m][n] = __builtin_amdgcn_mfma_f32_16x16x32_bf16(Bt[n][k], At[m][k], acc[ai][bj][m][n], 0, 0, 0); __builtin_amdgcn_s_setprio(0); } while (0)
; #define PG8_WAIT_V(n) asm volatile("s_waitcnt vmcnt(" #n ")" ::: "memory")
; #define PG8_WAIT_L(n) asm volatile("s_waitcnt lgkmcnt(" #n ")" ::: "memory")
; #define PG8_BAR __builtin_amdgcn_s_barrier()
; #define PG8_SCHED __builtin_amdgcn_sched_barrier(0)
; template <class Epi, class Sched, bool ATILE = false>
; __device__ __forceinline__ void gemm_phase(LAS unsigned char* lds, const Gemm g, const Sched& S, const Epi& E) {
;     ...
;             PG8_WAIT_V(6); PG8_BAR; PG8_MMA(1, 1, At, B1); PG8_BAR;
;             PG8_LDB(B0, 1, 0); PG8_SCHED; PG8_LDA(At, 1, 0); PG8_STAGE(PG8_SA(0, 1), a2 + hstepA, voffA);
;             PG8_WAIT_L(8); PG8_BAR; PG8_WAIT_L(0); PG8_MMA(0, 0, At, B0); PG8_BAR; PG8_SCHED;
;             PG8_LDB(B1, 1, 1); PG8_STAGE(PG8_SB(1, 0), b3, voffB);
;             PG8_BAR; PG8_WAIT_L(0); PG8_MMA(0, 1, At, B1); PG8_BAR;
	v_mfma_f32_16x16x32_bf16 v[44:47], v[224:227], v[200:203], v[44:47]
	v_mfma_f32_16x16x32_bf16 v[40:43], v[232:235], v[200:203], v[40:43]
	v_mfma_f32_16x16x32_bf16 v[20:23], v[224:227], v[208:211], v[20:23]
	v_mfma_f32_16x16x32_bf16 v[16:19], v[232:235], v[208:211], v[16:19]
	v_mfma_f32_16x16x32_bf16 v[4:7], v[224:227], v[216:219], v[4:7]
	v_mfma_f32_16x16x32_bf16 v[0:3], v[232:235], v[216:219], v[0:3]
	v_mfma_f32_16x16x32_bf16 v[32:35], v[224:227], v[192:195], v[60:63]
	v_mfma_f32_16x16x32_bf16 v[36:39], v[232:235], v[192:195], v[56:59]
	v_mfma_f32_16x16x32_bf16 v[44:47], v[228:231], v[204:207], v[44:47]
	v_mfma_f32_16x16x32_bf16 v[40:43], v[236:239], v[204:207], v[40:43]
	v_mfma_f32_16x16x32_bf16 v[20:23], v[228:231], v[212:215], v[20:23]
	v_mfma_f32_16x16x32_bf16 v[16:19], v[236:239], v[212:215], v[16:19]
	v_mfma_f32_16x16x32_bf16 v[4:7], v[228:231], v[220:223], v[4:7]
	v_mfma_f32_16x16x32_bf16 v[0:3], v[236:239], v[220:223], v[0:3]
	v_mfma_f32_16x16x32_bf16 v[32:35], v[228:231], v[196:199], v[32:35]
	v_mfma_f32_16x16x32_bf16 v[36:39], v[236:239], v[196:199], v[36:39]
	s_barrier
	s_setprio 0
	s_add_i32 s73, 0, 0x18000
	v_add_u32_e32 v144, s73, v161
	ds_read_b128 v[56:59], v144
	ds_read_b128 v[60:63], v144 offset:1024
	ds_read_b128 v[178:181], v144 offset:2048
	ds_read_b128 v[182:185], v144 offset:3072
	s_add_u32 s86, s86, 0x80000
	s_addc_u32 s87, s87, 0
	s_mov_b32 m0, s39
	ds_read_b128 v[192:195], v167 offset:32768
	ds_read_b128 v[196:199], v167 offset:33792
	ds_read_b128 v[200:203], v167 offset:34816
	ds_read_b128 v[204:207], v167 offset:35840
	ds_read_b128 v[208:211], v167 offset:36864
	ds_read_b128 v[212:215], v167 offset:37888
	ds_read_b128 v[216:219], v167 offset:38912
	ds_read_b128 v[220:223], v167 offset:39936
	global_load_lds_dwordx4 v136, s[86:87]
	s_mov_b32 m0, s97
	s_nop 0
	global_load_lds_dwordx4 v140, s[86:87]
	s_waitcnt lgkmcnt(8)
	s_waitcnt lgkmcnt(0)
	s_setprio 1
	s_barrier
	v_mfma_f32_16x16x32_bf16 v[132:135], v[56:59], v[192:195], v[132:135]
	v_mfma_f32_16x16x32_bf16 v[128:131], v[178:181], v[192:195], v[128:131]
	v_mfma_f32_16x16x32_bf16 v[116:119], v[56:59], v[200:203], v[116:119]
	v_mfma_f32_16x16x32_bf16 v[112:115], v[178:181], v[200:203], v[112:115]
	v_mfma_f32_16x16x32_bf16 v[100:103], v[56:59], v[208:211], v[100:103]
	v_mfma_f32_16x16x32_bf16 v[96:99], v[178:181], v[208:211], v[96:99]
	v_mfma_f32_16x16x32_bf16 v[84:87], v[56:59], v[216:219], v[84:87]
	v_mfma_f32_16x16x32_bf16 v[80:83], v[178:181], v[216:219], v[80:83]
	v_mfma_f32_16x16x32_bf16 v[132:135], v[60:63], v[196:199], v[132:135]
	v_mfma_f32_16x16x32_bf16 v[128:131], v[182:185], v[196:199], v[128:131]
	v_mfma_f32_16x16x32_bf16 v[116:119], v[60:63], v[204:207], v[116:119]
	v_mfma_f32_16x16x32_bf16 v[112:115], v[182:185], v[204:207], v[112:115]
	v_mfma_f32_16x16x32_bf16 v[100:103], v[60:63], v[212:215], v[100:103]
	v_mfma_f32_16x16x32_bf16 v[96:99], v[182:185], v[212:215], v[96:99]
	v_mfma_f32_16x16x32_bf16 v[84:87], v[60:63], v[220:223], v[84:87]
	v_mfma_f32_16x16x32_bf16 v[80:83], v[182:185], v[220:223], v[80:83]
	s_barrier
	s_setprio 0
	s_add_i32 s86, 0, 0x1c000
	s_add_i32 s73, s73, s31
	v_add_u32_e32 v144, s86, v161
	s_mov_b32 m0, s73
	ds_read_b128 v[224:227], v144
	ds_read_b128 v[228:231], v144 offset:1024
	ds_read_b128 v[232:235], v144 offset:2048
	ds_read_b128 v[236:239], v144 offset:3072
	global_load_lds_dwordx4 v138, s[98:99]
	s_add_i32 m0, s73, 0x2000
	s_nop 0
	global_load_lds_dwordx4 v142, s[98:99]
	s_waitcnt lgkmcnt(0)
	s_setprio 1
	s_barrier
; #define PG8_STAGE(bufoff, gbase, voff) do { _Pragma("unroll") for (int _i = 0; _i < 2; ++_i) \
;         __builtin_amdgcn_global_load_lds((const unsigned*)((const char*)(gbase) + (voff)[_i]), (LAS unsigned*)(lds + (bufoff) + ldsw + _i * 8192), 16, 0, 0); } while (0)
; #define PG8_LDA(dst, b, h) do { _Pragma("unroll") for (int m = 0; m < 4; ++m) _Pragma("unroll") for (int k = 0; k < 2; ++k) dst[m][k] = *(const LAS bf16x8*)(lds + PG8_SA(b, h) + aoff + m * 2048 + k * 1024); } while (0)
; #define PG8_MMA(ai, bj, At, Bt) do { __builtin_amdgcn_s_setprio(1); _Pragma("unroll") for (int m = 0; m < 4; ++m) _Pragma("unroll") for (int n = 0; n < 2; ++n) _Pragma("unroll") for (int k = 0; k < 2; ++k) \
;         acc[ai][bj][m][n] = __builtin_amdgcn_mfma_f32_16x16x32_bf16(Bt[n][k], At[m][k], acc[ai][bj][m][n], 0, 0, 0); __builtin_amdgcn_s_setprio(0); } while (0)
; #define PG8_WAIT_V(n) asm volatile("s_waitcnt vmcnt(" #n ")" ::: "memory")
; #define PG8_WAIT_L(n) asm volatile("s_waitcnt lgkmcnt(" #n ")" ::: "memory")
; #define PG8_BAR __builtin_amdgcn_s_barrier()
; #define PG8_SCHED __builtin_amdgcn_sched_barrier(0)
; template <class Epi, class Sched, bool ATILE = false>
; __device__ __forceinline__ void gemm_phase(LAS unsigned char* lds, const Gemm g, const Sched& S, const Epi& E) {
;     ...
;             PG8_BAR; PG8_WAIT_L(0); PG8_MMA(0, 1, At, B1); PG8_BAR;
;             PG8_LDA(At, 1, 1); PG8_STAGE(PG8_SA(1, 0), a3, voffA);
;             PG8_BAR; PG8_WAIT_L(0); PG8_MMA(1, 0, At, B0); PG8_BAR; PG8_SCHED;
;             PG8_STAGE(PG8_SB(1, 1), b3 + hstepB, voffB);
;             PG8_WAIT_V(6); PG8_BAR; PG8_MMA(1, 1, At, B1); PG8_BAR;
;         }
	v_mfma_f32_16x16x32_bf16 v[124:127], v[224:227], v[192:195], v[124:127]
	v_mfma_f32_16x16x32_bf16 v[120:123], v[232:235], v[192:195], v[120:123]
	v_mfma_f32_16x16x32_bf16 v[108:111], v[224:227], v[200:203], v[108:111]
	v_mfma_f32_16x16x32_bf16 v[104:107], v[232:235], v[200:203], v[104:107]
	v_mfma_f32_16x16x32_bf16 v[92:95], v[224:227], v[208:211], v[92:95]
	v_mfma_f32_16x16x32_bf16 v[88:91], v[232:235], v[208:211], v[88:91]
	v_mfma_f32_16x16x32_bf16 v[76:79], v[224:227], v[216:219], v[76:79]
	v_mfma_f32_16x16x32_bf16 v[72:75], v[232:235], v[216:219], v[72:75]
	v_mfma_f32_16x16x32_bf16 v[124:127], v[228:231], v[196:199], v[124:127]
	v_mfma_f32_16x16x32_bf16 v[120:123], v[236:239], v[196:199], v[120:123]
	v_mfma_f32_16x16x32_bf16 v[108:111], v[228:231], v[204:207], v[108:111]
	v_mfma_f32_16x16x32_bf16 v[104:107], v[236:239], v[204:207], v[104:107]
	v_mfma_f32_16x16x32_bf16 v[92:95], v[228:231], v[212:215], v[92:95]
	v_mfma_f32_16x16x32_bf16 v[88:91], v[236:239], v[212:215], v[88:91]
	v_mfma_f32_16x16x32_bf16 v[76:79], v[228:231], v[220:223], v[76:79]
	v_mfma_f32_16x16x32_bf16 v[72:75], v[236:239], v[220:223], v[72:75]
	s_barrier
	s_setprio 0
	s_mov_b32 m0, s4
	ds_read_b128 v[192:195], v167 offset:49152
	ds_read_b128 v[196:199], v167 offset:50176
	ds_read_b128 v[200:203], v167 offset:51200
	ds_read_b128 v[204:207], v167 offset:52224
	ds_read_b128 v[208:211], v167 offset:53248
	ds_read_b128 v[212:215], v167 offset:54272
	ds_read_b128 v[216:219], v167 offset:55296
	ds_read_b128 v[220:223], v167 offset:56320
	global_load_lds_dwordx4 v136, s[100:101]
	s_mov_b32 m0, s5
	s_nop 0
	global_load_lds_dwordx4 v140, s[100:101]
	s_waitcnt lgkmcnt(0)
	s_setprio 1
	s_barrier
	v_mfma_f32_16x16x32_bf16 v[68:71], v[56:59], v[192:195], v[68:71]
	v_mfma_f32_16x16x32_bf16 v[64:67], v[178:181], v[192:195], v[64:67]
	v_mfma_f32_16x16x32_bf16 v[52:55], v[56:59], v[200:203], v[52:55]
	v_mfma_f32_16x16x32_bf16 v[48:51], v[178:181], v[200:203], v[48:51]
	v_mfma_f32_16x16x32_bf16 v[28:31], v[56:59], v[208:211], v[28:31]
	v_mfma_f32_16x16x32_bf16 v[24:27], v[178:181], v[208:211], v[24:27]
	v_mfma_f32_16x16x32_bf16 v[12:15], v[56:59], v[216:219], v[12:15]
	v_mfma_f32_16x16x32_bf16 v[8:11], v[178:181], v[216:219], v[8:11]
	v_mfma_f32_16x16x32_bf16 v[68:71], v[60:63], v[196:199], v[68:71]
	v_mfma_f32_16x16x32_bf16 v[64:67], v[182:185], v[196:199], v[64:67]
	v_mfma_f32_16x16x32_bf16 v[52:55], v[60:63], v[204:207], v[52:55]
	v_mfma_f32_16x16x32_bf16 v[48:51], v[182:185], v[204:207], v[48:51]
	v_mfma_f32_16x16x32_bf16 v[28:31], v[60:63], v[212:215], v[28:31]
	v_mfma_f32_16x16x32_bf16 v[24:27], v[182:185], v[212:215], v[24:27]
	v_mfma_f32_16x16x32_bf16 v[12:15], v[60:63], v[220:223], v[12:15]
	v_mfma_f32_16x16x32_bf16 v[8:11], v[182:185], v[220:223], v[8:11]
	s_barrier
	s_setprio 0
	s_add_u32 s84, s84, 0x80080
	s_addc_u32 s85, s85, 0
	s_add_i32 s73, s86, s31
	s_mov_b32 m0, s73
	s_nop 0
	global_load_lds_dwordx4 v138, s[84:85]
	s_add_i32 m0, s73, 0x2000
	s_nop 0
	global_load_lds_dwordx4 v142, s[84:85]
	s_waitcnt vmcnt(6)
	s_setprio 1
	s_barrier
	v_mfma_f32_16x16x32_bf16 v[32:35], v[224:227], v[192:195], v[32:35]
	v_mfma_f32_16x16x32_bf16 v[60:63], v[228:231], v[196:199], v[32:35]
	v_mfma_f32_16x16x32_bf16 v[32:35], v[232:235], v[192:195], v[36:39]
	v_mfma_f32_16x16x32_bf16 v[56:59], v[236:239], v[196:199], v[32:35]
	v_mfma_f32_16x16x32_bf16 v[32:35], v[224:227], v[200:203], v[44:47]
	v_mfma_f32_16x16x32_bf16 v[44:47], v[228:231], v[204:207], v[32:35]
	v_mfma_f32_16x16x32_bf16 v[32:35], v[232:235], v[200:203], v[40:43]
	v_mfma_f32_16x16x32_bf16 v[20:23], v[224:227], v[208:211], v[20:23]
	v_mfma_f32_16x16x32_bf16 v[16:19], v[232:235], v[208:211], v[16:19]
	v_mfma_f32_16x16x32_bf16 v[4:7], v[224:227], v[216:219], v[4:7]
	v_mfma_f32_16x16x32_bf16 v[0:3], v[232:235], v[216:219], v[0:3]
	v_mfma_f32_16x16x32_bf16 v[40:43], v[236:239], v[204:207], v[32:35]
	v_mfma_f32_16x16x32_bf16 v[20:23], v[228:231], v[212:215], v[20:23]
	v_mfma_f32_16x16x32_bf16 v[16:19], v[236:239], v[212:215], v[16:19]
	v_mfma_f32_16x16x32_bf16 v[4:7], v[228:231], v[220:223], v[4:7]
	v_mfma_f32_16x16x32_bf16 v[0:3], v[236:239], v[220:223], v[0:3]
	s_barrier
	s_setprio 0
	s_add_u32 s12, s12, 0x100
	s_addc_u32 s13, s13, 0
	s_add_u32 s62, s62, 0x100
	s_addc_u32 s63, s63, 0
	s_cmp_ge_i32 s88, s1
	s_mov_b32 s73, s88
	s_cbranch_scc0 .LBB0_895
	s_branch .LBB0_897

;     __device__ bool next(int i, Unit& u) const { const int L = i * G + c; if (L >= 64 * 9) return false; u.pm = L; u.pn = L / 9; u.kt0 = 0; u.nt = ntf; u.ks = 0; return true; }
; #define PG8_STAGE(bufoff, gbase, voff) do { _Pragma("unroll") for (int _i = 0; _i < 2; ++_i) \
;         __builtin_amdgcn_global_load_lds((const unsigned*)((const char*)(gbase) + (voff)[_i]), (LAS unsigned*)(lds + (bufoff) + ldsw + _i * 8192), 16, 0, 0); } while (0)
; #define PG8_LDA(dst, b, h) do { _Pragma("unroll") for (int m = 0; m < 4; ++m) _Pragma("unroll") for (int k = 0; k < 2; ++k) dst[m][k] = *(const LAS bf16x8*)(lds + PG8_SA(b, h) + aoff + m * 2048 + k * 1024); } while (0)
; #define PG8_LDB(dst, b, h) do { _Pragma("unroll") for (int n = 0; n < 2; ++n) _Pragma("unroll") for (int k = 0; k < 2; ++k) dst[n][k] = *(const LAS bf16x8*)(lds + PG8_SB(b, h) + boff + n * 2048 + k * 1024); } while (0)
; template <class Epi, class Sched, bool ATILE = false>
; __device__ __forceinline__ void gemm_phase(LAS unsigned char* lds, const Gemm g, const Sched& S, const Epi& E) {
;     ...
;         const bool has_next = S.next(ui + 1, nxt);
;         const char* nA = has_next ? (const char*)g.A + (size_t)nxt.pm * tstepA + (size_t)nxt.kt0 * kstepA : cA; const char* nB = has_next ? (const char*)g.Bt + (size_t)nxt.pn * tstepB + (size_t)nxt.kt0 * kstep : cB;
;         int nt = cur.nt; asm volatile("" : "+s"(nt));
;         for (int t = 0; t < nt; t += 2) {
;             const bool last = (t == nt - 2);
;             const char* a1 = cA + (size_t)(t + 1) * kstepA;
;             const char* a2 = last ? nA : cA + (size_t)(t + 2) * kstepA; const char* b2 = last ? nB : cB + (size_t)(t + 2) * kstep;
;             const char* a3 = a2 + kstepA; const char* b3 = b2 + kstep;
;             PG8_LDB(B0, 0, 0); PG8_SCHED; PG8_LDA(At, 0, 0); PG8_STAGE(PG8_SA(1, 1), a1 + hstepA, voffA);
;             PG8_WAIT_L(8); PG8_BAR; PG8_WAIT_L(0); PG8_MMA(0, 0, At, B0); PG8_BAR; PG8_SCHED;
;             PG8_LDB(B1, 0, 1); PG8_STAGE(PG8_SB(0, 0), b2, voffB);
;             PG8_BAR; PG8_WAIT_L(0); PG8_MMA(0, 1, At, B1); PG8_BAR;
;             PG8_LDA(At, 0, 1); PG8_STAGE(PG8_SA(0, 0), a2, voffA);
;             PG8_BAR; PG8_WAIT_L(0); PG8_MMA(1, 0, At, B0); PG8_BAR; PG8_SCHED;
;             PG8_STAGE(PG8_SB(0, 1), b2 + hstepB, voffB);
;             PG8_WAIT_V(6); PG8_BAR; PG8_MMA(1, 1, At, B1); PG8_BAR;
.LBB0_1298:
	ds_read_b128 v[82:85], v79
	ds_read_b128 v[86:89], v79 offset:1024
	ds_read_b128 v[90:93], v79 offset:2048
	ds_read_b128 v[94:97], v79 offset:3072
	s_add_i32 s60, s20, 2
	s_add_u32 s18, s16, 0x100
	s_addc_u32 s19, s17, 0
	s_cmp_eq_u32 s57, s20
	s_cselect_b32 s20, s56, s58
	s_cselect_b32 s23, s9, s19
	s_cselect_b32 s22, s8, s18
	s_cselect_b32 s21, s55, s59
	s_mov_b32 m0, s38
	v_lshl_add_u64 v[130:131], s[16:17], 0, v[74:75]
	ds_read_b128 v[98:101], v80
	ds_read_b128 v[102:105], v80 offset:1024
	ds_read_b128 v[106:109], v80 offset:2048
	ds_read_b128 v[110:113], v80 offset:3072
	ds_read_b128 v[114:117], v80 offset:4096
	ds_read_b128 v[118:121], v80 offset:5120
	ds_read_b128 v[122:125], v80 offset:6144
	ds_read_b128 v[126:129], v80 offset:7168
	global_load_lds_dwordx4 v[130:131], off
	v_lshl_add_u64 v[130:131], s[16:17], 0, v[76:77]
	s_mov_b32 m0, s39
	s_nop 0
	global_load_lds_dwordx4 v[130:131], off
	s_waitcnt lgkmcnt(8)
	s_waitcnt lgkmcnt(0)
	s_setprio 1
	s_barrier
	v_mfma_f32_16x16x32_bf16 v[60:63], v[82:85], v[98:101], v[60:63]
	v_mfma_f32_16x16x32_bf16 v[56:59], v[90:93], v[98:101], v[56:59]
	v_mfma_f32_16x16x32_bf16 v[52:55], v[82:85], v[106:109], v[52:55]
	v_mfma_f32_16x16x32_bf16 v[48:51], v[90:93], v[106:109], v[48:51]
	v_mfma_f32_16x16x32_bf16 v[44:47], v[82:85], v[114:117], v[44:47]
	v_mfma_f32_16x16x32_bf16 v[40:43], v[90:93], v[114:117], v[40:43]
	v_mfma_f32_16x16x32_bf16 v[36:39], v[82:85], v[122:125], v[36:39]
	v_mfma_f32_16x16x32_bf16 v[32:35], v[90:93], v[122:125], v[32:35]
	v_mfma_f32_16x16x32_bf16 v[60:63], v[86:89], v[102:105], v[60:63]
	v_mfma_f32_16x16x32_bf16 v[56:59], v[94:97], v[102:105], v[56:59]
	v_mfma_f32_16x16x32_bf16 v[52:55], v[86:89], v[110:113], v[52:55]
	v_mfma_f32_16x16x32_bf16 v[48:51], v[94:97], v[110:113], v[48:51]
	v_mfma_f32_16x16x32_bf16 v[44:47], v[86:89], v[118:121], v[44:47]
	v_mfma_f32_16x16x32_bf16 v[40:43], v[94:97], v[118:121], v[40:43]
	v_mfma_f32_16x16x32_bf16 v[36:39], v[86:89], v[126:129], v[36:39]
	v_mfma_f32_16x16x32_bf16 v[32:35], v[94:97], v[126:129], v[32:35]
	s_barrier
	s_setprio 0
	s_mov_b32 m0, s40
	v_lshl_add_u64 v[130:131], s[20:21], 0, v[68:69]
	global_load_lds_dwordx4 v[130:131], off
	v_lshl_add_u64 v[132:133], s[20:21], 0, v[64:65]
	s_mov_b32 m0, s41
	s_nop 0
	global_load_lds_dwordx4 v[132:133], off
	s_barrier
	s_waitcnt lgkmcnt(0)
	s_setprio 1
	s_setprio 0
	s_mov_b32 m0, s25
	v_lshl_add_u64 v[134:135], s[22:23], 0, v[70:71]
	s_barrier
	ds_read_b128 v[98:101], v80 offset:16384
	ds_read_b128 v[102:105], v80 offset:17408
	ds_read_b128 v[106:109], v80 offset:18432
	ds_read_b128 v[110:113], v80 offset:19456
	ds_read_b128 v[114:117], v80 offset:20480
	ds_read_b128 v[118:121], v80 offset:21504
	ds_read_b128 v[122:125], v80 offset:22528
	ds_read_b128 v[126:129], v80 offset:23552
	global_load_lds_dwordx4 v[134:135], off
	v_lshl_add_u64 v[136:137], s[22:23], 0, v[66:67]
	s_mov_b32 m0, s26
	s_nop 0
	global_load_lds_dwordx4 v[136:137], off
	s_waitcnt lgkmcnt(0)
	s_setprio 1
	s_barrier
	v_mfma_f32_16x16x32_bf16 v[28:31], v[82:85], v[98:101], v[28:31]
	v_mfma_f32_16x16x32_bf16 v[24:27], v[90:93], v[98:101], v[24:27]
	v_mfma_f32_16x16x32_bf16 v[20:23], v[82:85], v[106:109], v[20:23]
	v_mfma_f32_16x16x32_bf16 v[16:19], v[90:93], v[106:109], v[16:19]
	v_mfma_f32_16x16x32_bf16 v[12:15], v[82:85], v[114:117], v[12:15]
	v_mfma_f32_16x16x32_bf16 v[8:11], v[90:93], v[114:117], v[8:11]
	v_mfma_f32_16x16x32_bf16 v[4:7], v[82:85], v[122:125], v[4:7]
	v_mfma_f32_16x16x32_bf16 v[0:3], v[90:93], v[122:125], v[0:3]
	v_mfma_f32_16x16x32_bf16 v[28:31], v[86:89], v[102:105], v[28:31]
	v_mfma_f32_16x16x32_bf16 v[24:27], v[94:97], v[102:105], v[24:27]
	v_mfma_f32_16x16x32_bf16 v[20:23], v[86:89], v[110:113], v[20:23]
	v_mfma_f32_16x16x32_bf16 v[16:19], v[94:97], v[110:113], v[16:19]
	v_mfma_f32_16x16x32_bf16 v[12:15], v[86:89], v[118:121], v[12:15]
	v_mfma_f32_16x16x32_bf16 v[8:11], v[94:97], v[118:121], v[8:11]
	v_mfma_f32_16x16x32_bf16 v[4:7], v[86:89], v[126:129], v[4:7]
	v_mfma_f32_16x16x32_bf16 v[0:3], v[94:97], v[126:129], v[0:3]
	s_barrier
	s_setprio 0
	s_add_u32 s16, s20, 0x10000
	s_addc_u32 s17, s21, 0
	s_mov_b32 m0, s27
	s_nop 0
	global_load_lds_dwordx4 v68, s[16:17]
	s_mov_b32 m0, s28
	s_nop 0
	global_load_lds_dwordx4 v64, s[16:17]
	s_waitcnt vmcnt(6)
	s_barrier
; #define PG8_STAGE(bufoff, gbase, voff) do { _Pragma("unroll") for (int _i = 0; _i < 2; ++_i) \
;         __builtin_amdgcn_global_load_lds((const unsigned*)((const char*)(gbase) + (voff)[_i]), (LAS unsigned*)(lds + (bufoff) + ldsw + _i * 8192), 16, 0, 0); } while (0)
; #define PG8_LDA(dst, b, h) do { _Pragma("unroll") for (int m = 0; m < 4; ++m) _Pragma("unroll") for (int k = 0; k < 2; ++k) dst[m][k] = *(const LAS bf16x8*)(lds + PG8_SA(b, h) + aoff + m * 2048 + k * 1024); } while (0)
; #define PG8_LDB(dst, b, h) do { _Pragma("unroll") for (int n = 0; n < 2; ++n) _Pragma("unroll") for (int k = 0; k < 2; ++k) dst[n][k] = *(const LAS bf16x8*)(lds + PG8_SB(b, h) + boff + n * 2048 + k * 1024); } while (0)
; #define PG8_MMA(ai, bj, At, Bt) do { __builtin_amdgcn_s_setprio(1); _Pragma("unroll") for (int m = 0; m < 4; ++m) _Pragma("unroll") for (int n = 0; n < 2; ++n) _Pragma("unroll") for (int k = 0; k < 2; ++k) \
;         acc[ai][bj][m][n] = __builtin_amdgcn_mfma_f32_16x16x32_bf16(Bt[n][k], At[m][k], acc[ai][bj][m][n], 0, 0, 0); __builtin_amdgcn_s_setprio(0); } while (0)
; #define PG8_WAIT_V(n) asm volatile("s_waitcnt vmcnt(" #n ")" ::: "memory")
; #define PG8_WAIT_L(n) asm volatile("s_waitcnt lgkmcnt(" #n ")" ::: "memory")
; #define PG8_BAR __builtin_amdgcn_s_barrier()
; #define PG8_SCHED __builtin_amdgcn_sched_barrier(0)
; template <class Epi, class Sched, bool ATILE = false>
; __device__ __forceinline__ void gemm_phase(LAS unsigned char* lds, const Gemm g, const Sched& S, const Epi& E) {
;     ...
;             PG8_WAIT_V(6); PG8_BAR; PG8_MMA(1, 1, At, B1); PG8_BAR;
;             PG8_LDB(B0, 1, 0); PG8_SCHED; PG8_LDA(At, 1, 0); PG8_STAGE(PG8_SA(0, 1), a2 + hstepA, voffA);
;             PG8_WAIT_L(8); PG8_BAR; PG8_WAIT_L(0); PG8_MMA(0, 0, At, B0); PG8_BAR; PG8_SCHED;
;             PG8_LDB(B1, 1, 1); PG8_STAGE(PG8_SB(1, 0), b3, voffB);
;             PG8_BAR; PG8_WAIT_L(0); PG8_MMA(0, 1, At, B1); PG8_BAR;
;             PG8_LDA(At, 1, 1); PG8_STAGE(PG8_SA(1, 0), a3, voffA);
;             PG8_BAR; PG8_WAIT_L(0); PG8_MMA(1, 0, At, B0); PG8_BAR; PG8_SCHED;
;             PG8_STAGE(PG8_SB(1, 1), b3 + hstepB, voffB);
;             PG8_WAIT_V(6); PG8_BAR; PG8_MMA(1, 1, At, B1); PG8_BAR;
;         }
	s_setprio 1
	s_setprio 0
	s_barrier
	ds_read_b128 v[82:85], v81
	ds_read_b128 v[86:89], v81 offset:1024
	ds_read_b128 v[90:93], v81 offset:2048
	ds_read_b128 v[94:97], v81 offset:3072
	s_add_u32 s16, s22, 0x18000
	s_addc_u32 s17, s23, 0
	s_mov_b32 m0, s29
	ds_read_b128 v[98:101], v80 offset:32768
	ds_read_b128 v[102:105], v80 offset:33792
	ds_read_b128 v[106:109], v80 offset:34816
	ds_read_b128 v[110:113], v80 offset:35840
	ds_read_b128 v[114:117], v80 offset:36864
	ds_read_b128 v[118:121], v80 offset:37888
	ds_read_b128 v[122:125], v80 offset:38912
	ds_read_b128 v[126:129], v80 offset:39936
	global_load_lds_dwordx4 v70, s[16:17]
	s_mov_b32 m0, s30
	s_nop 0
	global_load_lds_dwordx4 v66, s[16:17]
	s_waitcnt lgkmcnt(8)
	s_waitcnt lgkmcnt(0)
	s_setprio 1
	s_barrier
	v_mfma_f32_16x16x32_bf16 v[60:63], v[82:85], v[98:101], v[60:63]
	v_mfma_f32_16x16x32_bf16 v[56:59], v[90:93], v[98:101], v[56:59]
	v_mfma_f32_16x16x32_bf16 v[52:55], v[82:85], v[106:109], v[52:55]
	v_mfma_f32_16x16x32_bf16 v[48:51], v[90:93], v[106:109], v[48:51]
	v_mfma_f32_16x16x32_bf16 v[44:47], v[82:85], v[114:117], v[44:47]
	v_mfma_f32_16x16x32_bf16 v[40:43], v[90:93], v[114:117], v[40:43]
	v_mfma_f32_16x16x32_bf16 v[36:39], v[82:85], v[122:125], v[36:39]
	v_mfma_f32_16x16x32_bf16 v[32:35], v[90:93], v[122:125], v[32:35]
	v_mfma_f32_16x16x32_bf16 v[60:63], v[86:89], v[102:105], v[60:63]
	v_mfma_f32_16x16x32_bf16 v[56:59], v[94:97], v[102:105], v[56:59]
	v_mfma_f32_16x16x32_bf16 v[52:55], v[86:89], v[110:113], v[52:55]
	v_mfma_f32_16x16x32_bf16 v[48:51], v[94:97], v[110:113], v[48:51]
	v_mfma_f32_16x16x32_bf16 v[44:47], v[86:89], v[118:121], v[44:47]
	v_mfma_f32_16x16x32_bf16 v[40:43], v[94:97], v[118:121], v[40:43]
	v_mfma_f32_16x16x32_bf16 v[36:39], v[86:89], v[126:129], v[36:39]
	v_mfma_f32_16x16x32_bf16 v[32:35], v[94:97], v[126:129], v[32:35]
	s_barrier
	s_setprio 0
	s_mov_b32 m0, s43
	v_lshl_add_u64 v[98:99], v[130:131], 0, s[6:7]
	global_load_lds_dwordx4 v[98:99], off
	v_lshl_add_u64 v[98:99], v[132:133], 0, s[6:7]
	s_mov_b32 m0, s44
	s_nop 0
	global_load_lds_dwordx4 v[98:99], off
	s_barrier
	s_waitcnt lgkmcnt(0)
	s_setprio 1
	s_setprio 0
	s_mov_b32 m0, s34
	v_lshl_add_u64 v[130:131], v[134:135], 0, s[6:7]
	s_barrier
	ds_read_b128 v[98:101], v80 offset:49152
	ds_read_b128 v[102:105], v80 offset:50176
	ds_read_b128 v[106:109], v80 offset:51200
	ds_read_b128 v[110:113], v80 offset:52224
	ds_read_b128 v[114:117], v80 offset:53248
	ds_read_b128 v[118:121], v80 offset:54272
	ds_read_b128 v[122:125], v80 offset:55296
	ds_read_b128 v[126:129], v80 offset:56320
	global_load_lds_dwordx4 v[130:131], off
	v_lshl_add_u64 v[130:131], v[136:137], 0, s[6:7]
	s_mov_b32 m0, s35
	s_nop 0
	global_load_lds_dwordx4 v[130:131], off
	s_waitcnt lgkmcnt(0)
	s_setprio 1
	s_barrier
	v_mfma_f32_16x16x32_bf16 v[28:31], v[82:85], v[98:101], v[28:31]
	v_mfma_f32_16x16x32_bf16 v[24:27], v[90:93], v[98:101], v[24:27]
	v_mfma_f32_16x16x32_bf16 v[20:23], v[82:85], v[106:109], v[20:23]
	v_mfma_f32_16x16x32_bf16 v[16:19], v[90:93], v[106:109], v[16:19]
	v_mfma_f32_16x16x32_bf16 v[12:15], v[82:85], v[114:117], v[12:15]
	v_mfma_f32_16x16x32_bf16 v[8:11], v[90:93], v[114:117], v[8:11]
	v_mfma_f32_16x16x32_bf16 v[4:7], v[82:85], v[122:125], v[4:7]
	v_mfma_f32_16x16x32_bf16 v[0:3], v[90:93], v[122:125], v[0:3]
	v_mfma_f32_16x16x32_bf16 v[28:31], v[86:89], v[102:105], v[28:31]
	v_mfma_f32_16x16x32_bf16 v[24:27], v[94:97], v[102:105], v[24:27]
	v_mfma_f32_16x16x32_bf16 v[20:23], v[86:89], v[110:113], v[20:23]
	v_mfma_f32_16x16x32_bf16 v[16:19], v[94:97], v[110:113], v[16:19]
	v_mfma_f32_16x16x32_bf16 v[12:15], v[86:89], v[118:121], v[12:15]
	v_mfma_f32_16x16x32_bf16 v[8:11], v[94:97], v[118:121], v[8:11]
	v_mfma_f32_16x16x32_bf16 v[4:7], v[86:89], v[126:129], v[4:7]
	v_mfma_f32_16x16x32_bf16 v[0:3], v[94:97], v[126:129], v[0:3]
	s_barrier
	s_setprio 0
	s_add_u32 s16, s20, 0x10080
	s_addc_u32 s17, s21, 0
	s_mov_b32 m0, s36
	s_nop 0
	global_load_lds_dwordx4 v68, s[16:17]
	s_mov_b32 m0, s37
	s_nop 0
	global_load_lds_dwordx4 v64, s[16:17]
	s_waitcnt vmcnt(6)
	s_barrier
	s_setprio 1
	s_setprio 0
	s_add_u32 s58, s58, 0x100
	s_addc_u32 s59, s59, 0
	s_cmp_ge_i32 s60, s54
	s_mov_b64 s[16:17], s[18:19]
	s_mov_b32 s20, s60
	s_barrier
	s_cbranch_scc0 .LBB0_1298
	s_branch .LBB0_1293

;     __device__ bool next(int i, Unit& u) const { const int L = i * G + c; if (L >= 64 * 9) return false; u.pm = L; u.pn = L / 9; u.kt0 = 0; u.nt = ntf; u.ks = 0; return true; }
; #define PG8_STAGE(bufoff, gbase, voff) do { _Pragma("unroll") for (int _i = 0; _i < 2; ++_i) \
;         __builtin_amdgcn_global_load_lds((const unsigned*)((const char*)(gbase) + (voff)[_i]), (LAS unsigned*)(lds + (bufoff) + ldsw + _i * 8192), 16, 0, 0); } while (0)
; #define PG8_LDA(dst, b, h) do { _Pragma("unroll") for (int m = 0; m < 4; ++m) _Pragma("unroll") for (int k = 0; k < 2; ++k) dst[m][k] = *(const LAS bf16x8*)(lds + PG8_SA(b, h) + aoff + m * 2048 + k * 1024); } while (0)
; #define PG8_LDB(dst, b, h) do { _Pragma("unroll") for (int n = 0; n < 2; ++n) _Pragma("unroll") for (int k = 0; k < 2; ++k) dst[n][k] = *(const LAS bf16x8*)(lds + PG8_SB(b, h) + boff + n * 2048 + k * 1024); } while (0)
; template <class Epi, class Sched, bool ATILE = false>
; __device__ __forceinline__ void gemm_phase(LAS unsigned char* lds, const Gemm g, const Sched& S, const Epi& E) {
;     ...
;         const bool has_next = S.next(ui + 1, nxt);
;         const char* nA = has_next ? (const char*)g.A + (size_t)nxt.pm * tstepA + (size_t)nxt.kt0 * kstepA : cA; const char* nB = has_next ? (const char*)g.Bt + (size_t)nxt.pn * tstepB + (size_t)nxt.kt0 * kstep : cB;
;         int nt = cur.nt; asm volatile("" : "+s"(nt));
;         for (int t = 0; t < nt; t += 2) {
;             const bool last = (t == nt - 2);
;             const char* a1 = cA + (size_t)(t + 1) * kstepA;
;             const char* a2 = last ? nA : cA + (size_t)(t + 2) * kstepA; const char* b2 = last ? nB : cB + (size_t)(t + 2) * kstep;
;             const char* a3 = a2 + kstepA; const char* b3 = b2 + kstep;
;             PG8_LDB(B0, 0, 0); PG8_SCHED; PG8_LDA(At, 0, 0); PG8_STAGE(PG8_SA(1, 1), a1 + hstepA, voffA);
;             PG8_WAIT_L(8); PG8_BAR; PG8_WAIT_L(0); PG8_MMA(0, 0, At, B0); PG8_BAR; PG8_SCHED;
;             PG8_LDB(B1, 0, 1); PG8_STAGE(PG8_SB(0, 0), b2, voffB);
;             PG8_BAR; PG8_WAIT_L(0); PG8_MMA(0, 1, At, B1); PG8_BAR;
;             PG8_LDA(At, 0, 1); PG8_STAGE(PG8_SA(0, 0), a2, voffA);
;             PG8_BAR; PG8_WAIT_L(0); PG8_MMA(1, 0, At, B0); PG8_BAR; PG8_SCHED;
;             PG8_STAGE(PG8_SB(0, 1), b2 + hstepB, voffB);
;             PG8_WAIT_V(6); PG8_BAR; PG8_MMA(1, 1, At, B1); PG8_BAR;
.LBB0_1426:
	ds_read_b128 v[162:165], v147
	ds_read_b128 v[166:169], v147 offset:1024
	ds_read_b128 v[170:173], v147 offset:2048
	ds_read_b128 v[174:177], v147 offset:3072
	s_add_i32 s58, s18, 2
	s_add_u32 s16, s12, 0x100
	s_addc_u32 s17, s13, 0
	s_cmp_eq_u32 s55, s18
	s_cselect_b32 s18, s10, s56
	s_cselect_b32 s21, s7, s17
	s_cselect_b32 s20, s6, s16
	s_cselect_b32 s19, s11, s57
	s_mov_b32 m0, s30
	v_lshl_add_u64 v[144:145], s[12:13], 0, v[140:141]
	ds_read_b128 v[178:181], v148
	ds_read_b128 v[182:185], v148 offset:1024
	ds_read_b128 v[186:189], v148 offset:2048
	ds_read_b128 v[190:193], v148 offset:3072
	ds_read_b128 v[194:197], v148 offset:4096
	ds_read_b128 v[198:201], v148 offset:5120
	ds_read_b128 v[202:205], v148 offset:6144
	ds_read_b128 v[206:209], v148 offset:7168
	global_load_lds_dwordx4 v[144:145], off
	v_lshl_add_u64 v[144:145], s[12:13], 0, v[142:143]
	s_mov_b32 m0, s31
	s_nop 0
	global_load_lds_dwordx4 v[144:145], off
	s_waitcnt lgkmcnt(8)
	s_waitcnt lgkmcnt(0)
	s_setprio 1
	s_barrier
	v_mfma_f32_16x16x32_bf16 v[124:127], v[162:165], v[178:181], v[124:127]
	v_mfma_f32_16x16x32_bf16 v[120:123], v[170:173], v[178:181], v[120:123]
	v_mfma_f32_16x16x32_bf16 v[108:111], v[162:165], v[186:189], v[108:111]
	v_mfma_f32_16x16x32_bf16 v[104:107], v[170:173], v[186:189], v[104:107]
	v_mfma_f32_16x16x32_bf16 v[92:95], v[162:165], v[194:197], v[92:95]
	v_mfma_f32_16x16x32_bf16 v[88:91], v[170:173], v[194:197], v[88:91]
	v_mfma_f32_16x16x32_bf16 v[76:79], v[162:165], v[202:205], v[76:79]
	v_mfma_f32_16x16x32_bf16 v[72:75], v[170:173], v[202:205], v[72:75]
	v_mfma_f32_16x16x32_bf16 v[124:127], v[166:169], v[182:185], v[124:127]
	v_mfma_f32_16x16x32_bf16 v[120:123], v[174:177], v[182:185], v[120:123]
	v_mfma_f32_16x16x32_bf16 v[108:111], v[166:169], v[190:193], v[108:111]
	v_mfma_f32_16x16x32_bf16 v[104:107], v[174:177], v[190:193], v[104:107]
	v_mfma_f32_16x16x32_bf16 v[92:95], v[166:169], v[198:201], v[92:95]
	v_mfma_f32_16x16x32_bf16 v[88:91], v[174:177], v[198:201], v[88:91]
	v_mfma_f32_16x16x32_bf16 v[76:79], v[166:169], v[206:209], v[76:79]
	v_mfma_f32_16x16x32_bf16 v[72:75], v[174:177], v[206:209], v[72:75]
	s_barrier
	s_setprio 0
	s_mov_b32 m0, s33
	v_lshl_add_u64 v[144:145], s[18:19], 0, v[132:133]
	ds_read_b128 v[210:213], v149
	ds_read_b128 v[214:217], v149 offset:1024
	ds_read_b128 v[218:221], v149 offset:2048
	ds_read_b128 v[222:225], v149 offset:3072
	global_load_lds_dwordx4 v[144:145], off
	v_lshl_add_u64 v[226:227], s[18:19], 0, v[128:129]
	s_mov_b32 m0, s34
	s_nop 0
	global_load_lds_dwordx4 v[226:227], off
	s_waitcnt lgkmcnt(0)
	s_setprio 1
	s_barrier
	v_mfma_f32_16x16x32_bf16 v[116:119], v[210:213], v[178:181], v[116:119]
	v_mfma_f32_16x16x32_bf16 v[112:115], v[218:221], v[178:181], v[112:115]
	v_mfma_f32_16x16x32_bf16 v[100:103], v[210:213], v[186:189], v[100:103]
	v_mfma_f32_16x16x32_bf16 v[96:99], v[218:221], v[186:189], v[96:99]
	v_mfma_f32_16x16x32_bf16 v[84:87], v[210:213], v[194:197], v[84:87]
	v_mfma_f32_16x16x32_bf16 v[80:83], v[218:221], v[194:197], v[80:83]
	v_mfma_f32_16x16x32_bf16 v[68:71], v[210:213], v[202:205], v[68:71]
	v_mfma_f32_16x16x32_bf16 v[64:67], v[218:221], v[202:205], v[64:67]
	v_mfma_f32_16x16x32_bf16 v[116:119], v[214:217], v[182:185], v[116:119]
	v_mfma_f32_16x16x32_bf16 v[112:115], v[222:225], v[182:185], v[112:115]
	v_mfma_f32_16x16x32_bf16 v[100:103], v[214:217], v[190:193], v[100:103]
	v_mfma_f32_16x16x32_bf16 v[96:99], v[222:225], v[190:193], v[96:99]
	v_mfma_f32_16x16x32_bf16 v[84:87], v[214:217], v[198:201], v[84:87]
	v_mfma_f32_16x16x32_bf16 v[80:83], v[222:225], v[198:201], v[80:83]
	v_mfma_f32_16x16x32_bf16 v[68:71], v[214:217], v[206:209], v[68:71]
	v_mfma_f32_16x16x32_bf16 v[64:67], v[222:225], v[206:209], v[64:67]
	s_barrier
	s_setprio 0
	s_mov_b32 m0, s22
	v_lshl_add_u64 v[228:229], s[20:21], 0, v[134:135]
	ds_read_b128 v[178:181], v148 offset:16384
	ds_read_b128 v[182:185], v148 offset:17408
	ds_read_b128 v[186:189], v148 offset:18432
	ds_read_b128 v[190:193], v148 offset:19456
	ds_read_b128 v[194:197], v148 offset:20480
	ds_read_b128 v[198:201], v148 offset:21504
	ds_read_b128 v[202:205], v148 offset:22528
	ds_read_b128 v[206:209], v148 offset:23552
	global_load_lds_dwordx4 v[228:229], off
	v_lshl_add_u64 v[230:231], s[20:21], 0, v[130:131]
	s_mov_b32 m0, s23
	s_nop 0
	global_load_lds_dwordx4 v[230:231], off
	s_waitcnt lgkmcnt(0)
	s_setprio 1
	s_barrier
	v_mfma_f32_16x16x32_bf16 v[60:63], v[162:165], v[178:181], v[60:63]
	v_mfma_f32_16x16x32_bf16 v[56:59], v[170:173], v[178:181], v[56:59]
	v_mfma_f32_16x16x32_bf16 v[44:47], v[162:165], v[186:189], v[44:47]
	v_mfma_f32_16x16x32_bf16 v[40:43], v[170:173], v[186:189], v[40:43]
	v_mfma_f32_16x16x32_bf16 v[28:31], v[162:165], v[194:197], v[28:31]
	v_mfma_f32_16x16x32_bf16 v[24:27], v[170:173], v[194:197], v[24:27]
	v_mfma_f32_16x16x32_bf16 v[12:15], v[162:165], v[202:205], v[12:15]
	v_mfma_f32_16x16x32_bf16 v[8:11], v[170:173], v[202:205], v[8:11]
	v_mfma_f32_16x16x32_bf16 v[60:63], v[166:169], v[182:185], v[60:63]
	v_mfma_f32_16x16x32_bf16 v[56:59], v[174:177], v[182:185], v[56:59]
	v_mfma_f32_16x16x32_bf16 v[44:47], v[166:169], v[190:193], v[44:47]
	v_mfma_f32_16x16x32_bf16 v[40:43], v[174:177], v[190:193], v[40:43]
	v_mfma_f32_16x16x32_bf16 v[28:31], v[166:169], v[198:201], v[28:31]
	v_mfma_f32_16x16x32_bf16 v[24:27], v[174:177], v[198:201], v[24:27]
	v_mfma_f32_16x16x32_bf16 v[12:15], v[166:169], v[206:209], v[12:15]
	v_mfma_f32_16x16x32_bf16 v[8:11], v[174:177], v[206:209], v[8:11]
	s_barrier
	s_setprio 0
	s_add_u32 s12, s18, 0x18000
	s_addc_u32 s13, s19, 0
	s_mov_b32 m0, s35
	s_nop 0
	global_load_lds_dwordx4 v132, s[12:13]
	s_mov_b32 m0, s36
	s_nop 0
	global_load_lds_dwordx4 v128, s[12:13]
	s_waitcnt vmcnt(6)
	s_setprio 1
	s_barrier
; #define PG8_STAGE(bufoff, gbase, voff) do { _Pragma("unroll") for (int _i = 0; _i < 2; ++_i) \
;         __builtin_amdgcn_global_load_lds((const unsigned*)((const char*)(gbase) + (voff)[_i]), (LAS unsigned*)(lds + (bufoff) + ldsw + _i * 8192), 16, 0, 0); } while (0)
; #define PG8_LDA(dst, b, h) do { _Pragma("unroll") for (int m = 0; m < 4; ++m) _Pragma("unroll") for (int k = 0; k < 2; ++k) dst[m][k] = *(const LAS bf16x8*)(lds + PG8_SA(b, h) + aoff + m * 2048 + k * 1024); } while (0)
; #define PG8_LDB(dst, b, h) do { _Pragma("unroll") for (int n = 0; n < 2; ++n) _Pragma("unroll") for (int k = 0; k < 2; ++k) dst[n][k] = *(const LAS bf16x8*)(lds + PG8_SB(b, h) + boff + n * 2048 + k * 1024); } while (0)
; #define PG8_MMA(ai, bj, At, Bt) do { __builtin_amdgcn_s_setprio(1); _Pragma("unroll") for (int m = 0; m < 4; ++m) _Pragma("unroll") for (int n = 0; n < 2; ++n) _Pragma("unroll") for (int k = 0; k < 2; ++k) \
;         acc[ai][bj][m][n] = __builtin_amdgcn_mfma_f32_16x16x32_bf16(Bt[n][k], At[m][k], acc[ai][bj][m][n], 0, 0, 0); __builtin_amdgcn_s_setprio(0); } while (0)
; #define PG8_WAIT_V(n) asm volatile("s_waitcnt vmcnt(" #n ")" ::: "memory")
; #define PG8_WAIT_L(n) asm volatile("s_waitcnt lgkmcnt(" #n ")" ::: "memory")
; #define PG8_BAR __builtin_amdgcn_s_barrier()
; #define PG8_SCHED __builtin_amdgcn_sched_barrier(0)
; template <class Epi, class Sched, bool ATILE = false>
; __device__ __forceinline__ void gemm_phase(LAS unsigned char* lds, const Gemm g, const Sched& S, const Epi& E) {
;     ...
;             PG8_WAIT_V(6); PG8_BAR; PG8_MMA(1, 1, At, B1); PG8_BAR;
;             PG8_LDB(B0, 1, 0); PG8_SCHED; PG8_LDA(At, 1, 0); PG8_STAGE(PG8_SA(0, 1), a2 + hstepA, voffA);
;             PG8_WAIT_L(8); PG8_BAR; PG8_WAIT_L(0); PG8_MMA(0, 0, At, B0); PG8_BAR; PG8_SCHED;
;             PG8_LDB(B1, 1, 1); PG8_STAGE(PG8_SB(1, 0), b3, voffB);
;             PG8_BAR; PG8_WAIT_L(0); PG8_MMA(0, 1, At, B1); PG8_BAR;
	v_mfma_f32_16x16x32_bf16 v[52:55], v[210:213], v[178:181], v[52:55]
	v_mfma_f32_16x16x32_bf16 v[48:51], v[218:221], v[178:181], v[48:51]
	v_mfma_f32_16x16x32_bf16 v[36:39], v[210:213], v[186:189], v[36:39]
	v_mfma_f32_16x16x32_bf16 v[32:35], v[218:221], v[186:189], v[32:35]
	v_mfma_f32_16x16x32_bf16 v[20:23], v[210:213], v[194:197], v[20:23]
	v_mfma_f32_16x16x32_bf16 v[16:19], v[218:221], v[194:197], v[16:19]
	v_mfma_f32_16x16x32_bf16 v[4:7], v[210:213], v[202:205], v[4:7]
	v_mfma_f32_16x16x32_bf16 v[0:3], v[218:221], v[202:205], v[0:3]
	v_mfma_f32_16x16x32_bf16 v[52:55], v[214:217], v[182:185], v[52:55]
	v_mfma_f32_16x16x32_bf16 v[48:51], v[222:225], v[182:185], v[48:51]
	v_mfma_f32_16x16x32_bf16 v[36:39], v[214:217], v[190:193], v[36:39]
	v_mfma_f32_16x16x32_bf16 v[32:35], v[222:225], v[190:193], v[32:35]
	v_mfma_f32_16x16x32_bf16 v[20:23], v[214:217], v[198:201], v[20:23]
	v_mfma_f32_16x16x32_bf16 v[16:19], v[222:225], v[198:201], v[16:19]
	v_mfma_f32_16x16x32_bf16 v[4:7], v[214:217], v[206:209], v[4:7]
	v_mfma_f32_16x16x32_bf16 v[0:3], v[222:225], v[206:209], v[0:3]
	s_barrier
	s_setprio 0
	ds_read_b128 v[162:165], v150
	ds_read_b128 v[166:169], v150 offset:1024
	ds_read_b128 v[170:173], v150 offset:2048
	ds_read_b128 v[174:177], v150 offset:3072
	s_add_u32 s12, s20, 0x18000
	s_addc_u32 s13, s21, 0
	s_mov_b32 m0, s24
	ds_read_b128 v[178:181], v148 offset:32768
	ds_read_b128 v[182:185], v148 offset:33792
	ds_read_b128 v[186:189], v148 offset:34816
	ds_read_b128 v[190:193], v148 offset:35840
	ds_read_b128 v[194:197], v148 offset:36864
	ds_read_b128 v[198:201], v148 offset:37888
	ds_read_b128 v[202:205], v148 offset:38912
	ds_read_b128 v[206:209], v148 offset:39936
	global_load_lds_dwordx4 v134, s[12:13]
	s_mov_b32 m0, s25
	s_nop 0
	global_load_lds_dwordx4 v130, s[12:13]
	s_waitcnt lgkmcnt(8)
	s_waitcnt lgkmcnt(0)
	s_setprio 1
	s_barrier
	v_mfma_f32_16x16x32_bf16 v[124:127], v[162:165], v[178:181], v[124:127]
	v_mfma_f32_16x16x32_bf16 v[120:123], v[170:173], v[178:181], v[120:123]
	v_mfma_f32_16x16x32_bf16 v[108:111], v[162:165], v[186:189], v[108:111]
	v_mfma_f32_16x16x32_bf16 v[104:107], v[170:173], v[186:189], v[104:107]
	v_mfma_f32_16x16x32_bf16 v[92:95], v[162:165], v[194:197], v[92:95]
	v_mfma_f32_16x16x32_bf16 v[88:91], v[170:173], v[194:197], v[88:91]
	v_mfma_f32_16x16x32_bf16 v[76:79], v[162:165], v[202:205], v[76:79]
	v_mfma_f32_16x16x32_bf16 v[72:75], v[170:173], v[202:205], v[72:75]
	v_mfma_f32_16x16x32_bf16 v[124:127], v[166:169], v[182:185], v[124:127]
	v_mfma_f32_16x16x32_bf16 v[120:123], v[174:177], v[182:185], v[120:123]
	v_mfma_f32_16x16x32_bf16 v[108:111], v[166:169], v[190:193], v[108:111]
	v_mfma_f32_16x16x32_bf16 v[104:107], v[174:177], v[190:193], v[104:107]
	v_mfma_f32_16x16x32_bf16 v[92:95], v[166:169], v[198:201], v[92:95]
	v_mfma_f32_16x16x32_bf16 v[88:91], v[174:177], v[198:201], v[88:91]
	v_mfma_f32_16x16x32_bf16 v[76:79], v[166:169], v[206:209], v[76:79]
	v_mfma_f32_16x16x32_bf16 v[72:75], v[174:177], v[206:209], v[72:75]
	s_barrier
	s_setprio 0
	s_mov_b32 m0, s40
	v_lshl_add_u64 v[144:145], v[144:145], 0, s[0:1]
	ds_read_b128 v[210:213], v157
	ds_read_b128 v[214:217], v157 offset:1024
	ds_read_b128 v[218:221], v157 offset:2048
	ds_read_b128 v[222:225], v157 offset:3072
	global_load_lds_dwordx4 v[144:145], off
	v_lshl_add_u64 v[144:145], v[226:227], 0, s[0:1]
	s_mov_b32 m0, s41
	s_nop 0
	global_load_lds_dwordx4 v[144:145], off
	s_waitcnt lgkmcnt(0)
	s_setprio 1
	s_barrier
; #define PG8_STAGE(bufoff, gbase, voff) do { _Pragma("unroll") for (int _i = 0; _i < 2; ++_i) \
;         __builtin_amdgcn_global_load_lds((const unsigned*)((const char*)(gbase) + (voff)[_i]), (LAS unsigned*)(lds + (bufoff) + ldsw + _i * 8192), 16, 0, 0); } while (0)
; #define PG8_LDA(dst, b, h) do { _Pragma("unroll") for (int m = 0; m < 4; ++m) _Pragma("unroll") for (int k = 0; k < 2; ++k) dst[m][k] = *(const LAS bf16x8*)(lds + PG8_SA(b, h) + aoff + m * 2048 + k * 1024); } while (0)
; #define PG8_MMA(ai, bj, At, Bt) do { __builtin_amdgcn_s_setprio(1); _Pragma("unroll") for (int m = 0; m < 4; ++m) _Pragma("unroll") for (int n = 0; n < 2; ++n) _Pragma("unroll") for (int k = 0; k < 2; ++k) \
;         acc[ai][bj][m][n] = __builtin_amdgcn_mfma_f32_16x16x32_bf16(Bt[n][k], At[m][k], acc[ai][bj][m][n], 0, 0, 0); __builtin_amdgcn_s_setprio(0); } while (0)
; #define PG8_WAIT_V(n) asm volatile("s_waitcnt vmcnt(" #n ")" ::: "memory")
; #define PG8_WAIT_L(n) asm volatile("s_waitcnt lgkmcnt(" #n ")" ::: "memory")
; #define PG8_BAR __builtin_amdgcn_s_barrier()
; #define PG8_SCHED __builtin_amdgcn_sched_barrier(0)
; template <class Epi, class Sched, bool ATILE = false>
; __device__ __forceinline__ void gemm_phase(LAS unsigned char* lds, const Gemm g, const Sched& S, const Epi& E) {
;     ...
;             PG8_BAR; PG8_WAIT_L(0); PG8_MMA(0, 1, At, B1); PG8_BAR;
;             PG8_LDA(At, 1, 1); PG8_STAGE(PG8_SA(1, 0), a3, voffA);
;             PG8_BAR; PG8_WAIT_L(0); PG8_MMA(1, 0, At, B0); PG8_BAR; PG8_SCHED;
;             PG8_STAGE(PG8_SB(1, 1), b3 + hstepB, voffB);
;             PG8_WAIT_V(6); PG8_BAR; PG8_MMA(1, 1, At, B1); PG8_BAR;
;         }
	v_mfma_f32_16x16x32_bf16 v[116:119], v[210:213], v[178:181], v[116:119]
	v_mfma_f32_16x16x32_bf16 v[112:115], v[218:221], v[178:181], v[112:115]
	v_mfma_f32_16x16x32_bf16 v[100:103], v[210:213], v[186:189], v[100:103]
	v_mfma_f32_16x16x32_bf16 v[96:99], v[218:221], v[186:189], v[96:99]
	v_mfma_f32_16x16x32_bf16 v[84:87], v[210:213], v[194:197], v[84:87]
	v_mfma_f32_16x16x32_bf16 v[80:83], v[218:221], v[194:197], v[80:83]
	v_mfma_f32_16x16x32_bf16 v[68:71], v[210:213], v[202:205], v[68:71]
	v_mfma_f32_16x16x32_bf16 v[64:67], v[218:221], v[202:205], v[64:67]
	v_mfma_f32_16x16x32_bf16 v[116:119], v[214:217], v[182:185], v[116:119]
	v_mfma_f32_16x16x32_bf16 v[112:115], v[222:225], v[182:185], v[112:115]
	v_mfma_f32_16x16x32_bf16 v[100:103], v[214:217], v[190:193], v[100:103]
	v_mfma_f32_16x16x32_bf16 v[96:99], v[222:225], v[190:193], v[96:99]
	v_mfma_f32_16x16x32_bf16 v[84:87], v[214:217], v[198:201], v[84:87]
	v_mfma_f32_16x16x32_bf16 v[80:83], v[222:225], v[198:201], v[80:83]
	v_mfma_f32_16x16x32_bf16 v[68:71], v[214:217], v[206:209], v[68:71]
	v_mfma_f32_16x16x32_bf16 v[64:67], v[222:225], v[206:209], v[64:67]
	s_barrier
	s_setprio 0
	s_mov_b32 m0, s28
	v_lshl_add_u64 v[144:145], v[228:229], 0, s[0:1]
	ds_read_b128 v[178:181], v148 offset:49152
	ds_read_b128 v[182:185], v148 offset:50176
	ds_read_b128 v[186:189], v148 offset:51200
	ds_read_b128 v[190:193], v148 offset:52224
	ds_read_b128 v[194:197], v148 offset:53248
	ds_read_b128 v[198:201], v148 offset:54272
	ds_read_b128 v[202:205], v148 offset:55296
	ds_read_b128 v[206:209], v148 offset:56320
	global_load_lds_dwordx4 v[144:145], off
	v_lshl_add_u64 v[144:145], v[230:231], 0, s[0:1]
	s_mov_b32 m0, s29
	s_nop 0
	global_load_lds_dwordx4 v[144:145], off
	s_waitcnt lgkmcnt(0)
	s_setprio 1
	s_barrier
	v_mfma_f32_16x16x32_bf16 v[60:63], v[162:165], v[178:181], v[60:63]
	v_mfma_f32_16x16x32_bf16 v[56:59], v[170:173], v[178:181], v[56:59]
	v_mfma_f32_16x16x32_bf16 v[44:47], v[162:165], v[186:189], v[44:47]
	v_mfma_f32_16x16x32_bf16 v[40:43], v[170:173], v[186:189], v[40:43]
	v_mfma_f32_16x16x32_bf16 v[28:31], v[162:165], v[194:197], v[28:31]
	v_mfma_f32_16x16x32_bf16 v[24:27], v[170:173], v[194:197], v[24:27]
	v_mfma_f32_16x16x32_bf16 v[12:15], v[162:165], v[202:205], v[12:15]
	v_mfma_f32_16x16x32_bf16 v[8:11], v[170:173], v[202:205], v[8:11]
	v_mfma_f32_16x16x32_bf16 v[60:63], v[166:169], v[182:185], v[60:63]
	v_mfma_f32_16x16x32_bf16 v[56:59], v[174:177], v[182:185], v[56:59]
	v_mfma_f32_16x16x32_bf16 v[44:47], v[166:169], v[190:193], v[44:47]
	v_mfma_f32_16x16x32_bf16 v[40:43], v[174:177], v[190:193], v[40:43]
	v_mfma_f32_16x16x32_bf16 v[28:31], v[166:169], v[198:201], v[28:31]
	v_mfma_f32_16x16x32_bf16 v[24:27], v[174:177], v[198:201], v[24:27]
	v_mfma_f32_16x16x32_bf16 v[12:15], v[166:169], v[206:209], v[12:15]
	v_mfma_f32_16x16x32_bf16 v[8:11], v[174:177], v[206:209], v[8:11]
	s_barrier
	s_setprio 0
	s_add_u32 s12, s18, 0x18080
	s_addc_u32 s13, s19, 0
	s_mov_b32 m0, s42
	s_nop 0
	global_load_lds_dwordx4 v132, s[12:13]
	s_mov_b32 m0, s43
	s_nop 0
	global_load_lds_dwordx4 v128, s[12:13]
	s_waitcnt vmcnt(6)
	s_setprio 1
	s_barrier
	v_mfma_f32_16x16x32_bf16 v[52:55], v[210:213], v[178:181], v[52:55]
	v_mfma_f32_16x16x32_bf16 v[48:51], v[218:221], v[178:181], v[48:51]
	v_mfma_f32_16x16x32_bf16 v[36:39], v[210:213], v[186:189], v[36:39]
	v_mfma_f32_16x16x32_bf16 v[32:35], v[218:221], v[186:189], v[32:35]
	v_mfma_f32_16x16x32_bf16 v[20:23], v[210:213], v[194:197], v[20:23]
	v_mfma_f32_16x16x32_bf16 v[16:19], v[218:221], v[194:197], v[16:19]
	v_mfma_f32_16x16x32_bf16 v[4:7], v[210:213], v[202:205], v[4:7]
	v_mfma_f32_16x16x32_bf16 v[0:3], v[218:221], v[202:205], v[0:3]
	v_mfma_f32_16x16x32_bf16 v[52:55], v[214:217], v[182:185], v[52:55]
	v_mfma_f32_16x16x32_bf16 v[48:51], v[222:225], v[182:185], v[48:51]
	v_mfma_f32_16x16x32_bf16 v[36:39], v[214:217], v[190:193], v[36:39]
	v_mfma_f32_16x16x32_bf16 v[32:35], v[222:225], v[190:193], v[32:35]
	v_mfma_f32_16x16x32_bf16 v[20:23], v[214:217], v[198:201], v[20:23]
	v_mfma_f32_16x16x32_bf16 v[16:19], v[222:225], v[198:201], v[16:19]
	v_mfma_f32_16x16x32_bf16 v[4:7], v[214:217], v[206:209], v[4:7]
	v_mfma_f32_16x16x32_bf16 v[0:3], v[222:225], v[206:209], v[0:3]
	s_barrier
	s_setprio 0
	s_add_u32 s56, s56, 0x100
	s_addc_u32 s57, s57, 0
	s_cmp_ge_i32 s58, s54
	s_mov_b64 s[12:13], s[16:17]
	s_mov_b32 s18, s58
	s_cbranch_scc0 .LBB0_1426
	s_branch .LBB0_1428

;     __device__ bool next(int i, Unit& u) const { const int L = i * G + c; if (L >= 64 * 9) return false; u.pm = L; u.pn = L / 9; u.kt0 = 0; u.nt = ntf; u.ks = 0; return true; }
; #define PG8_STAGE(bufoff, gbase, voff) do { _Pragma("unroll") for (int _i = 0; _i < 2; ++_i) \
;         __builtin_amdgcn_global_load_lds((const unsigned*)((const char*)(gbase) + (voff)[_i]), (LAS unsigned*)(lds + (bufoff) + ldsw + _i * 8192), 16, 0, 0); } while (0)
; #define PG8_LDA(dst, b, h) do { _Pragma("unroll") for (int m = 0; m < 4; ++m) _Pragma("unroll") for (int k = 0; k < 2; ++k) dst[m][k] = *(const LAS bf16x8*)(lds + PG8_SA(b, h) + aoff + m * 2048 + k * 1024); } while (0)
; #define PG8_LDB(dst, b, h) do { _Pragma("unroll") for (int n = 0; n < 2; ++n) _Pragma("unroll") for (int k = 0; k < 2; ++k) dst[n][k] = *(const LAS bf16x8*)(lds + PG8_SB(b, h) + boff + n * 2048 + k * 1024); } while (0)
; template <class Epi, class Sched, bool ATILE = false>
; __device__ __forceinline__ void gemm_phase(LAS unsigned char* lds, const Gemm g, const Sched& S, const Epi& E) {
;     ...
;         const bool has_next = S.next(ui + 1, nxt);
;         const char* nA = has_next ? (const char*)g.A + (size_t)nxt.pm * tstepA + (size_t)nxt.kt0 * kstepA : cA; const char* nB = has_next ? (const char*)g.Bt + (size_t)nxt.pn * tstepB + (size_t)nxt.kt0 * kstep : cB;
;         int nt = cur.nt; asm volatile("" : "+s"(nt));
;         for (int t = 0; t < nt; t += 2) {
;             const bool last = (t == nt - 2);
;             const char* a1 = cA + (size_t)(t + 1) * kstepA;
;             const char* a2 = last ? nA : cA + (size_t)(t + 2) * kstepA; const char* b2 = last ? nB : cB + (size_t)(t + 2) * kstep;
;             const char* a3 = a2 + kstepA; const char* b3 = b2 + kstep;
;             PG8_LDB(B0, 0, 0); PG8_SCHED; PG8_LDA(At, 0, 0); PG8_STAGE(PG8_SA(1, 1), a1 + hstepA, voffA);
;             PG8_WAIT_L(8); PG8_BAR; PG8_WAIT_L(0); PG8_MMA(0, 0, At, B0); PG8_BAR; PG8_SCHED;
;             PG8_LDB(B1, 0, 1); PG8_STAGE(PG8_SB(0, 0), b2, voffB);
;             PG8_BAR; PG8_WAIT_L(0); PG8_MMA(0, 1, At, B1); PG8_BAR;
;             PG8_LDA(At, 0, 1); PG8_STAGE(PG8_SA(0, 0), a2, voffA);
;             PG8_BAR; PG8_WAIT_L(0); PG8_MMA(1, 0, At, B0); PG8_BAR; PG8_SCHED;
;             PG8_STAGE(PG8_SB(0, 1), b2 + hstepB, voffB);
;             PG8_WAIT_V(6); PG8_BAR; PG8_MMA(1, 1, At, B1); PG8_BAR;
.LBB0_1517:
	ds_read_b128 v[96:99], v182
	ds_read_b128 v[100:103], v182 offset:1024
	ds_read_b128 v[112:115], v182 offset:2048
	ds_read_b128 v[116:119], v182 offset:3072
	s_add_i32 s54, s26, 2
	s_add_u32 s27, s24, 0xfffc0080
	s_addc_u32 s28, s25, -1
	s_cmp_eq_u32 s45, s26
	s_cselect_b32 s26, s44, s52
	s_cselect_b32 s29, s17, s28
	s_cselect_b32 s28, s42, s27
	s_cselect_b32 s27, s43, s53
	s_add_i32 m0, s23, 0xc000
	ds_read_b128 v[144:147], v183
	ds_read_b128 v[174:177], v183 offset:1024
	ds_read_b128 v[178:181], v183 offset:2048
	ds_read_b128 v[186:189], v183 offset:3072
	ds_read_b128 v[190:193], v183 offset:4096
	ds_read_b128 v[194:197], v183 offset:5120
	ds_read_b128 v[198:201], v183 offset:6144
	ds_read_b128 v[202:205], v183 offset:7168
	global_load_lds_dwordx4 v166, s[24:25]
	s_add_i32 m0, s23, 0xe000
	s_nop 0
	global_load_lds_dwordx4 v168, s[24:25]
	s_waitcnt lgkmcnt(8)
	s_waitcnt lgkmcnt(0)
	s_setprio 1
	s_barrier
	v_mfma_f32_16x16x32_bf16 v[140:143], v[96:99], v[144:147], v[140:143]
	v_mfma_f32_16x16x32_bf16 v[136:139], v[112:115], v[144:147], v[136:139]
	v_mfma_f32_16x16x32_bf16 v[124:127], v[96:99], v[178:181], v[124:127]
	v_mfma_f32_16x16x32_bf16 v[120:123], v[112:115], v[178:181], v[120:123]
	v_mfma_f32_16x16x32_bf16 v[92:95], v[96:99], v[190:193], v[92:95]
	v_mfma_f32_16x16x32_bf16 v[88:91], v[112:115], v[190:193], v[88:91]
	v_mfma_f32_16x16x32_bf16 v[76:79], v[96:99], v[198:201], v[76:79]
	v_mfma_f32_16x16x32_bf16 v[72:75], v[112:115], v[198:201], v[72:75]
	v_mfma_f32_16x16x32_bf16 v[140:143], v[100:103], v[174:177], v[140:143]
	v_mfma_f32_16x16x32_bf16 v[136:139], v[116:119], v[174:177], v[136:139]
	v_mfma_f32_16x16x32_bf16 v[124:127], v[100:103], v[186:189], v[124:127]
	v_mfma_f32_16x16x32_bf16 v[120:123], v[116:119], v[186:189], v[120:123]
	v_mfma_f32_16x16x32_bf16 v[92:95], v[100:103], v[194:197], v[92:95]
	v_mfma_f32_16x16x32_bf16 v[88:91], v[116:119], v[194:197], v[88:91]
	v_mfma_f32_16x16x32_bf16 v[76:79], v[100:103], v[202:205], v[76:79]
	v_mfma_f32_16x16x32_bf16 v[72:75], v[116:119], v[202:205], v[72:75]
	s_barrier
	s_setprio 0
	s_add_i32 s55, s39, s5
	s_add_u32 s98, s26, s10
	s_addc_u32 s99, s27, s11
	s_mov_b32 m0, s55
	ds_read_b128 v[206:209], v184
	ds_read_b128 v[210:213], v184 offset:1024
	ds_read_b128 v[214:217], v184 offset:2048
	ds_read_b128 v[218:221], v184 offset:3072
	global_load_lds_dwordx4 v150, s[26:27]
	s_add_i32 m0, s55, 0x2000
	s_nop 0
	global_load_lds_dwordx4 v164, s[26:27]
	s_waitcnt lgkmcnt(0)
	s_setprio 1
	s_barrier
	v_mfma_f32_16x16x32_bf16 v[132:135], v[206:209], v[144:147], v[132:135]
	v_mfma_f32_16x16x32_bf16 v[128:131], v[214:217], v[144:147], v[128:131]
	v_mfma_f32_16x16x32_bf16 v[108:111], v[206:209], v[178:181], v[108:111]
	v_mfma_f32_16x16x32_bf16 v[104:107], v[214:217], v[178:181], v[104:107]
	v_mfma_f32_16x16x32_bf16 v[84:87], v[206:209], v[190:193], v[84:87]
	v_mfma_f32_16x16x32_bf16 v[80:83], v[214:217], v[190:193], v[80:83]
	v_mfma_f32_16x16x32_bf16 v[68:71], v[206:209], v[198:201], v[68:71]
	v_mfma_f32_16x16x32_bf16 v[64:67], v[214:217], v[198:201], v[64:67]
	v_mfma_f32_16x16x32_bf16 v[132:135], v[210:213], v[174:177], v[132:135]
	v_mfma_f32_16x16x32_bf16 v[128:131], v[218:221], v[174:177], v[128:131]
	v_mfma_f32_16x16x32_bf16 v[108:111], v[210:213], v[186:189], v[108:111]
	v_mfma_f32_16x16x32_bf16 v[104:107], v[218:221], v[186:189], v[104:107]
	v_mfma_f32_16x16x32_bf16 v[84:87], v[210:213], v[194:197], v[84:87]
	v_mfma_f32_16x16x32_bf16 v[80:83], v[218:221], v[194:197], v[80:83]
	v_mfma_f32_16x16x32_bf16 v[68:71], v[210:213], v[202:205], v[68:71]
	v_mfma_f32_16x16x32_bf16 v[64:67], v[218:221], v[202:205], v[64:67]
	s_barrier
	s_setprio 0
	s_mov_b32 m0, s23
	s_add_u32 s100, s28, s10
	s_addc_u32 s101, s29, s11
	ds_read_b128 v[144:147], v183 offset:16384
	ds_read_b128 v[174:177], v183 offset:17408
	ds_read_b128 v[178:181], v183 offset:18432
	ds_read_b128 v[186:189], v183 offset:19456
	ds_read_b128 v[190:193], v183 offset:20480
	ds_read_b128 v[194:197], v183 offset:21504
	ds_read_b128 v[198:201], v183 offset:22528
	ds_read_b128 v[202:205], v183 offset:23552
	global_load_lds_dwordx4 v148, s[28:29]
	s_mov_b32 m0, s30
	s_nop 0
	global_load_lds_dwordx4 v162, s[28:29]
	s_waitcnt lgkmcnt(0)
	s_setprio 1
	s_barrier
	v_mfma_f32_16x16x32_bf16 v[60:63], v[96:99], v[144:147], v[60:63]
	v_mfma_f32_16x16x32_bf16 v[56:59], v[112:115], v[144:147], v[56:59]
	v_mfma_f32_16x16x32_bf16 v[44:47], v[96:99], v[178:181], v[44:47]
	v_mfma_f32_16x16x32_bf16 v[40:43], v[112:115], v[178:181], v[40:43]
	v_mfma_f32_16x16x32_bf16 v[28:31], v[96:99], v[190:193], v[28:31]
	v_mfma_f32_16x16x32_bf16 v[24:27], v[112:115], v[190:193], v[24:27]
	v_mfma_f32_16x16x32_bf16 v[12:15], v[96:99], v[198:201], v[12:15]
	v_mfma_f32_16x16x32_bf16 v[8:11], v[112:115], v[198:201], v[8:11]
	v_mfma_f32_16x16x32_bf16 v[60:63], v[100:103], v[174:177], v[60:63]
	v_mfma_f32_16x16x32_bf16 v[56:59], v[116:119], v[174:177], v[56:59]
	v_mfma_f32_16x16x32_bf16 v[44:47], v[100:103], v[186:189], v[44:47]
	v_mfma_f32_16x16x32_bf16 v[40:43], v[116:119], v[186:189], v[40:43]
	v_mfma_f32_16x16x32_bf16 v[28:31], v[100:103], v[194:197], v[28:31]
	v_mfma_f32_16x16x32_bf16 v[24:27], v[116:119], v[194:197], v[24:27]
	v_mfma_f32_16x16x32_bf16 v[12:15], v[100:103], v[202:205], v[12:15]
	v_mfma_f32_16x16x32_bf16 v[8:11], v[116:119], v[202:205], v[8:11]
	s_barrier
	s_setprio 0
	s_add_u32 s56, s26, 0x40000
	s_addc_u32 s57, s27, 0
	s_add_i32 s55, s40, s5
	s_mov_b32 m0, s55
	s_nop 0
	global_load_lds_dwordx4 v150, s[56:57]
	s_add_i32 m0, s55, 0x2000
	s_nop 0
	global_load_lds_dwordx4 v164, s[56:57]
	s_waitcnt vmcnt(6)
	s_setprio 1
	s_barrier
; #define PG8_STAGE(bufoff, gbase, voff) do { _Pragma("unroll") for (int _i = 0; _i < 2; ++_i) \
;         __builtin_amdgcn_global_load_lds((const unsigned*)((const char*)(gbase) + (voff)[_i]), (LAS unsigned*)(lds + (bufoff) + ldsw + _i * 8192), 16, 0, 0); } while (0)
; #define PG8_LDA(dst, b, h) do { _Pragma("unroll") for (int m = 0; m < 4; ++m) _Pragma("unroll") for (int k = 0; k < 2; ++k) dst[m][k] = *(const LAS bf16x8*)(lds + PG8_SA(b, h) + aoff + m * 2048 + k * 1024); } while (0)
; #define PG8_LDB(dst, b, h) do { _Pragma("unroll") for (int n = 0; n < 2; ++n) _Pragma("unroll") for (int k = 0; k < 2; ++k) dst[n][k] = *(const LAS bf16x8*)(lds + PG8_SB(b, h) + boff + n * 2048 + k * 1024); } while (0)
; #define PG8_MMA(ai, bj, At, Bt) do { __builtin_amdgcn_s_setprio(1); _Pragma("unroll") for (int m = 0; m < 4; ++m) _Pragma("unroll") for (int n = 0; n < 2; ++n) _Pragma("unroll") for (int k = 0; k < 2; ++k) \
;         acc[ai][bj][m][n] = __builtin_amdgcn_mfma_f32_16x16x32_bf16(Bt[n][k], At[m][k], acc[ai][bj][m][n], 0, 0, 0); __builtin_amdgcn_s_setprio(0); } while (0)
; #define PG8_WAIT_V(n) asm volatile("s_waitcnt vmcnt(" #n ")" ::: "memory")
; #define PG8_WAIT_L(n) asm volatile("s_waitcnt lgkmcnt(" #n ")" ::: "memory")
; #define PG8_BAR __builtin_amdgcn_s_barrier()
; #define PG8_SCHED __builtin_amdgcn_sched_barrier(0)
; template <class Epi, class Sched, bool ATILE = false>
; __device__ __forceinline__ void gemm_phase(LAS unsigned char* lds, const Gemm g, const Sched& S, const Epi& E) {
;     ...
;             PG8_WAIT_V(6); PG8_BAR; PG8_MMA(1, 1, At, B1); PG8_BAR;
;             PG8_LDB(B0, 1, 0); PG8_SCHED; PG8_LDA(At, 1, 0); PG8_STAGE(PG8_SA(0, 1), a2 + hstepA, voffA);
;             PG8_WAIT_L(8); PG8_BAR; PG8_WAIT_L(0); PG8_MMA(0, 0, At, B0); PG8_BAR; PG8_SCHED;
;             PG8_LDB(B1, 1, 1); PG8_STAGE(PG8_SB(1, 0), b3, voffB);
;             PG8_BAR; PG8_WAIT_L(0); PG8_MMA(0, 1, At, B1); PG8_BAR;
	v_mfma_f32_16x16x32_bf16 v[52:55], v[206:209], v[144:147], v[52:55]
	v_mfma_f32_16x16x32_bf16 v[48:51], v[214:217], v[144:147], v[48:51]
	v_mfma_f32_16x16x32_bf16 v[36:39], v[206:209], v[178:181], v[36:39]
	v_mfma_f32_16x16x32_bf16 v[32:35], v[214:217], v[178:181], v[32:35]
	v_mfma_f32_16x16x32_bf16 v[20:23], v[206:209], v[190:193], v[20:23]
	v_mfma_f32_16x16x32_bf16 v[16:19], v[214:217], v[190:193], v[16:19]
	v_mfma_f32_16x16x32_bf16 v[4:7], v[206:209], v[198:201], v[4:7]
	v_mfma_f32_16x16x32_bf16 v[0:3], v[214:217], v[198:201], v[0:3]
	v_mfma_f32_16x16x32_bf16 v[52:55], v[210:213], v[174:177], v[52:55]
	v_mfma_f32_16x16x32_bf16 v[48:51], v[218:221], v[174:177], v[48:51]
	v_mfma_f32_16x16x32_bf16 v[36:39], v[210:213], v[186:189], v[36:39]
	v_mfma_f32_16x16x32_bf16 v[32:35], v[218:221], v[186:189], v[32:35]
	v_mfma_f32_16x16x32_bf16 v[20:23], v[210:213], v[194:197], v[20:23]
	v_mfma_f32_16x16x32_bf16 v[16:19], v[218:221], v[194:197], v[16:19]
	v_mfma_f32_16x16x32_bf16 v[4:7], v[210:213], v[202:205], v[4:7]
	v_mfma_f32_16x16x32_bf16 v[0:3], v[218:221], v[202:205], v[0:3]
	s_barrier
	s_setprio 0
	s_add_i32 s55, 0, 0x18000
	v_add_u32_e32 v116, s55, v159
	ds_read_b128 v[96:99], v116
	ds_read_b128 v[100:103], v116 offset:1024
	ds_read_b128 v[112:115], v116 offset:2048
	ds_read_b128 v[116:119], v116 offset:3072
	s_add_u32 s28, s28, 0x40000
	s_addc_u32 s29, s29, 0
	s_mov_b32 m0, s31
	ds_read_b128 v[144:147], v183 offset:32768
	ds_read_b128 v[174:177], v183 offset:33792
	ds_read_b128 v[178:181], v183 offset:34816
	ds_read_b128 v[186:189], v183 offset:35840
	ds_read_b128 v[190:193], v183 offset:36864
	ds_read_b128 v[194:197], v183 offset:37888
	ds_read_b128 v[198:201], v183 offset:38912
	ds_read_b128 v[202:205], v183 offset:39936
	global_load_lds_dwordx4 v148, s[28:29]
	s_mov_b32 m0, s33
	s_nop 0
	global_load_lds_dwordx4 v162, s[28:29]
	s_waitcnt lgkmcnt(8)
	s_waitcnt lgkmcnt(0)
	s_setprio 1
	s_barrier
	v_mfma_f32_16x16x32_bf16 v[140:143], v[96:99], v[144:147], v[140:143]
	v_mfma_f32_16x16x32_bf16 v[136:139], v[112:115], v[144:147], v[136:139]
	v_mfma_f32_16x16x32_bf16 v[124:127], v[96:99], v[178:181], v[124:127]
	v_mfma_f32_16x16x32_bf16 v[120:123], v[112:115], v[178:181], v[120:123]
	v_mfma_f32_16x16x32_bf16 v[92:95], v[96:99], v[190:193], v[92:95]
	v_mfma_f32_16x16x32_bf16 v[88:91], v[112:115], v[190:193], v[88:91]
	v_mfma_f32_16x16x32_bf16 v[76:79], v[96:99], v[198:201], v[76:79]
	v_mfma_f32_16x16x32_bf16 v[72:75], v[112:115], v[198:201], v[72:75]
	v_mfma_f32_16x16x32_bf16 v[140:143], v[100:103], v[174:177], v[140:143]
	v_mfma_f32_16x16x32_bf16 v[136:139], v[116:119], v[174:177], v[136:139]
	v_mfma_f32_16x16x32_bf16 v[124:127], v[100:103], v[186:189], v[124:127]
	v_mfma_f32_16x16x32_bf16 v[120:123], v[116:119], v[186:189], v[120:123]
	v_mfma_f32_16x16x32_bf16 v[92:95], v[100:103], v[194:197], v[92:95]
	v_mfma_f32_16x16x32_bf16 v[88:91], v[116:119], v[194:197], v[88:91]
	v_mfma_f32_16x16x32_bf16 v[76:79], v[100:103], v[202:205], v[76:79]
	v_mfma_f32_16x16x32_bf16 v[72:75], v[116:119], v[202:205], v[72:75]
	s_barrier
	s_setprio 0
	s_add_i32 s28, 0, 0x1c000
	s_add_i32 s29, s55, s5
	v_add_u32_e32 v185, s28, v159
	s_mov_b32 m0, s29
	ds_read_b128 v[206:209], v185
	ds_read_b128 v[210:213], v185 offset:1024
	ds_read_b128 v[214:217], v185 offset:2048
	ds_read_b128 v[218:221], v185 offset:3072
	global_load_lds_dwordx4 v150, s[98:99]
	s_add_i32 m0, s29, 0x2000
	s_nop 0
	global_load_lds_dwordx4 v164, s[98:99]
	s_waitcnt lgkmcnt(0)
	s_setprio 1
	s_barrier
; #define PG8_STAGE(bufoff, gbase, voff) do { _Pragma("unroll") for (int _i = 0; _i < 2; ++_i) \
;         __builtin_amdgcn_global_load_lds((const unsigned*)((const char*)(gbase) + (voff)[_i]), (LAS unsigned*)(lds + (bufoff) + ldsw + _i * 8192), 16, 0, 0); } while (0)
; #define PG8_LDA(dst, b, h) do { _Pragma("unroll") for (int m = 0; m < 4; ++m) _Pragma("unroll") for (int k = 0; k < 2; ++k) dst[m][k] = *(const LAS bf16x8*)(lds + PG8_SA(b, h) + aoff + m * 2048 + k * 1024); } while (0)
; #define PG8_MMA(ai, bj, At, Bt) do { __builtin_amdgcn_s_setprio(1); _Pragma("unroll") for (int m = 0; m < 4; ++m) _Pragma("unroll") for (int n = 0; n < 2; ++n) _Pragma("unroll") for (int k = 0; k < 2; ++k) \
;         acc[ai][bj][m][n] = __builtin_amdgcn_mfma_f32_16x16x32_bf16(Bt[n][k], At[m][k], acc[ai][bj][m][n], 0, 0, 0); __builtin_amdgcn_s_setprio(0); } while (0)
; #define PG8_WAIT_V(n) asm volatile("s_waitcnt vmcnt(" #n ")" ::: "memory")
; #define PG8_WAIT_L(n) asm volatile("s_waitcnt lgkmcnt(" #n ")" ::: "memory")
; #define PG8_BAR __builtin_amdgcn_s_barrier()
; #define PG8_SCHED __builtin_amdgcn_sched_barrier(0)
; template <class Epi, class Sched, bool ATILE = false>
; __device__ __forceinline__ void gemm_phase(LAS unsigned char* lds, const Gemm g, const Sched& S, const Epi& E) {
;     ...
;             PG8_BAR; PG8_WAIT_L(0); PG8_MMA(0, 1, At, B1); PG8_BAR;
;             PG8_LDA(At, 1, 1); PG8_STAGE(PG8_SA(1, 0), a3, voffA);
;             PG8_BAR; PG8_WAIT_L(0); PG8_MMA(1, 0, At, B0); PG8_BAR; PG8_SCHED;
;             PG8_STAGE(PG8_SB(1, 1), b3 + hstepB, voffB);
;             PG8_WAIT_V(6); PG8_BAR; PG8_MMA(1, 1, At, B1); PG8_BAR;
;         }
	v_mfma_f32_16x16x32_bf16 v[132:135], v[206:209], v[144:147], v[132:135]
	v_mfma_f32_16x16x32_bf16 v[128:131], v[214:217], v[144:147], v[128:131]
	v_mfma_f32_16x16x32_bf16 v[108:111], v[206:209], v[178:181], v[108:111]
	v_mfma_f32_16x16x32_bf16 v[104:107], v[214:217], v[178:181], v[104:107]
	v_mfma_f32_16x16x32_bf16 v[84:87], v[206:209], v[190:193], v[84:87]
	v_mfma_f32_16x16x32_bf16 v[80:83], v[214:217], v[190:193], v[80:83]
	v_mfma_f32_16x16x32_bf16 v[68:71], v[206:209], v[198:201], v[68:71]
	v_mfma_f32_16x16x32_bf16 v[64:67], v[214:217], v[198:201], v[64:67]
	v_mfma_f32_16x16x32_bf16 v[132:135], v[210:213], v[174:177], v[132:135]
	v_mfma_f32_16x16x32_bf16 v[128:131], v[218:221], v[174:177], v[128:131]
	v_mfma_f32_16x16x32_bf16 v[108:111], v[210:213], v[186:189], v[108:111]
	v_mfma_f32_16x16x32_bf16 v[104:107], v[218:221], v[186:189], v[104:107]
	v_mfma_f32_16x16x32_bf16 v[84:87], v[210:213], v[194:197], v[84:87]
	v_mfma_f32_16x16x32_bf16 v[80:83], v[218:221], v[194:197], v[80:83]
	v_mfma_f32_16x16x32_bf16 v[68:71], v[210:213], v[202:205], v[68:71]
	v_mfma_f32_16x16x32_bf16 v[64:67], v[218:221], v[202:205], v[64:67]
	s_barrier
	s_setprio 0
	s_mov_b32 m0, s35
	ds_read_b128 v[144:147], v183 offset:49152
	ds_read_b128 v[174:177], v183 offset:50176
	ds_read_b128 v[178:181], v183 offset:51200
	ds_read_b128 v[186:189], v183 offset:52224
	ds_read_b128 v[190:193], v183 offset:53248
	ds_read_b128 v[194:197], v183 offset:54272
	ds_read_b128 v[198:201], v183 offset:55296
	ds_read_b128 v[202:205], v183 offset:56320
	global_load_lds_dwordx4 v148, s[100:101]
	s_mov_b32 m0, s36
	s_nop 0
	global_load_lds_dwordx4 v162, s[100:101]
	s_waitcnt lgkmcnt(0)
	s_setprio 1
	s_barrier
	v_mfma_f32_16x16x32_bf16 v[60:63], v[96:99], v[144:147], v[60:63]
	v_mfma_f32_16x16x32_bf16 v[56:59], v[112:115], v[144:147], v[56:59]
	v_mfma_f32_16x16x32_bf16 v[44:47], v[96:99], v[178:181], v[44:47]
	v_mfma_f32_16x16x32_bf16 v[40:43], v[112:115], v[178:181], v[40:43]
	v_mfma_f32_16x16x32_bf16 v[28:31], v[96:99], v[190:193], v[28:31]
	v_mfma_f32_16x16x32_bf16 v[24:27], v[112:115], v[190:193], v[24:27]
	v_mfma_f32_16x16x32_bf16 v[12:15], v[96:99], v[198:201], v[12:15]
	v_mfma_f32_16x16x32_bf16 v[8:11], v[112:115], v[198:201], v[8:11]
	v_mfma_f32_16x16x32_bf16 v[60:63], v[100:103], v[174:177], v[60:63]
	v_mfma_f32_16x16x32_bf16 v[56:59], v[116:119], v[174:177], v[56:59]
	v_mfma_f32_16x16x32_bf16 v[44:47], v[100:103], v[186:189], v[44:47]
	v_mfma_f32_16x16x32_bf16 v[40:43], v[116:119], v[186:189], v[40:43]
	v_mfma_f32_16x16x32_bf16 v[28:31], v[100:103], v[194:197], v[28:31]
	v_mfma_f32_16x16x32_bf16 v[24:27], v[116:119], v[194:197], v[24:27]
	v_mfma_f32_16x16x32_bf16 v[12:15], v[100:103], v[202:205], v[12:15]
	v_mfma_f32_16x16x32_bf16 v[8:11], v[116:119], v[202:205], v[8:11]
	s_barrier
	s_setprio 0
	s_add_u32 s26, s26, 0x40080
	s_addc_u32 s27, s27, 0
	s_add_i32 s28, s28, s5
	s_mov_b32 m0, s28
	s_nop 0
	global_load_lds_dwordx4 v150, s[26:27]
	s_add_i32 m0, s28, 0x2000
	s_nop 0
	global_load_lds_dwordx4 v164, s[26:27]
	s_waitcnt vmcnt(6)
	s_setprio 1
	s_barrier
	v_mfma_f32_16x16x32_bf16 v[52:55], v[206:209], v[144:147], v[52:55]
	v_mfma_f32_16x16x32_bf16 v[48:51], v[214:217], v[144:147], v[48:51]
	v_mfma_f32_16x16x32_bf16 v[36:39], v[206:209], v[178:181], v[36:39]
	v_mfma_f32_16x16x32_bf16 v[32:35], v[214:217], v[178:181], v[32:35]
	v_mfma_f32_16x16x32_bf16 v[20:23], v[206:209], v[190:193], v[20:23]
	v_mfma_f32_16x16x32_bf16 v[16:19], v[214:217], v[190:193], v[16:19]
	v_mfma_f32_16x16x32_bf16 v[4:7], v[206:209], v[198:201], v[4:7]
	v_mfma_f32_16x16x32_bf16 v[0:3], v[214:217], v[198:201], v[0:3]
	v_mfma_f32_16x16x32_bf16 v[52:55], v[210:213], v[174:177], v[52:55]
	v_mfma_f32_16x16x32_bf16 v[48:51], v[218:221], v[174:177], v[48:51]
	v_mfma_f32_16x16x32_bf16 v[36:39], v[210:213], v[186:189], v[36:39]
	v_mfma_f32_16x16x32_bf16 v[32:35], v[218:221], v[186:189], v[32:35]
	v_mfma_f32_16x16x32_bf16 v[20:23], v[210:213], v[194:197], v[20:23]
	v_mfma_f32_16x16x32_bf16 v[16:19], v[218:221], v[194:197], v[16:19]
	v_mfma_f32_16x16x32_bf16 v[4:7], v[210:213], v[202:205], v[4:7]
	v_mfma_f32_16x16x32_bf16 v[0:3], v[218:221], v[202:205], v[0:3]
	s_barrier
	s_setprio 0
	s_add_u32 s24, s24, 0x100
	s_addc_u32 s25, s25, 0
	s_add_u32 s52, s52, 0x100
	s_addc_u32 s53, s53, 0
	s_cmp_ge_i32 s54, s13
	s_mov_b32 s26, s54
	s_cbranch_scc0 .LBB0_1517
	s_branch .LBB0_1508

;     __device__ bool next(int i, Unit& u) const { const int L = i * G + c; if (L >= 64 * 9) return false; u.pm = L; u.pn = L / 9; u.kt0 = 0; u.nt = ntf; u.ks = 0; return true; }
; #define PG8_STAGE(bufoff, gbase, voff) do { _Pragma("unroll") for (int _i = 0; _i < 2; ++_i) \
;         __builtin_amdgcn_global_load_lds((const unsigned*)((const char*)(gbase) + (voff)[_i]), (LAS unsigned*)(lds + (bufoff) + ldsw + _i * 8192), 16, 0, 0); } while (0)
; #define PG8_LDA(dst, b, h) do { _Pragma("unroll") for (int m = 0; m < 4; ++m) _Pragma("unroll") for (int k = 0; k < 2; ++k) dst[m][k] = *(const LAS bf16x8*)(lds + PG8_SA(b, h) + aoff + m * 2048 + k * 1024); } while (0)
; #define PG8_LDB(dst, b, h) do { _Pragma("unroll") for (int n = 0; n < 2; ++n) _Pragma("unroll") for (int k = 0; k < 2; ++k) dst[n][k] = *(const LAS bf16x8*)(lds + PG8_SB(b, h) + boff + n * 2048 + k * 1024); } while (0)
; template <class Epi, class Sched, bool ATILE = false>
; __device__ __forceinline__ void gemm_phase(LAS unsigned char* lds, const Gemm g, const Sched& S, const Epi& E) {
;     ...
;         const bool has_next = S.next(ui + 1, nxt);
;         const char* nA = has_next ? (const char*)g.A + (size_t)nxt.pm * tstepA + (size_t)nxt.kt0 * kstepA : cA; const char* nB = has_next ? (const char*)g.Bt + (size_t)nxt.pn * tstepB + (size_t)nxt.kt0 * kstep : cB;
;         int nt = cur.nt; asm volatile("" : "+s"(nt));
;         for (int t = 0; t < nt; t += 2) {
;             const bool last = (t == nt - 2);
;             const char* a1 = cA + (size_t)(t + 1) * kstepA;
;             const char* a2 = last ? nA : cA + (size_t)(t + 2) * kstepA; const char* b2 = last ? nB : cB + (size_t)(t + 2) * kstep;
;             const char* a3 = a2 + kstepA; const char* b3 = b2 + kstep;
;             PG8_LDB(B0, 0, 0); PG8_SCHED; PG8_LDA(At, 0, 0); PG8_STAGE(PG8_SA(1, 1), a1 + hstepA, voffA);
;             PG8_WAIT_L(8); PG8_BAR; PG8_WAIT_L(0); PG8_MMA(0, 0, At, B0); PG8_BAR; PG8_SCHED;
;             PG8_LDB(B1, 0, 1); PG8_STAGE(PG8_SB(0, 0), b2, voffB);
;             PG8_BAR; PG8_WAIT_L(0); PG8_MMA(0, 1, At, B1); PG8_BAR;
;             PG8_LDA(At, 0, 1); PG8_STAGE(PG8_SA(0, 0), a2, voffA);
;             PG8_BAR; PG8_WAIT_L(0); PG8_MMA(1, 0, At, B0); PG8_BAR; PG8_SCHED;
;             PG8_STAGE(PG8_SB(0, 1), b2 + hstepB, voffB);
;             PG8_WAIT_V(6); PG8_BAR; PG8_MMA(1, 1, At, B1); PG8_BAR;
.LBB0_1658:
	s_waitcnt lgkmcnt(0)
	ds_read_b128 v[128:131], v169
	ds_read_b128 v[132:135], v169 offset:1024
	ds_read_b128 v[136:139], v169 offset:2048
	ds_read_b128 v[140:143], v169 offset:3072
	s_add_i32 s29, s27, 2
	s_add_u32 s34, s30, 0x4000
	s_addc_u32 s35, s31, 0
	s_cmp_eq_u32 s11, s27
	s_cselect_b32 s38, s22, s34
	s_cselect_b32 s39, s23, s35
	s_cselect_b32 s34, s24, s13
	s_cselect_b32 s35, s25, s17
	s_add_u32 s36, s38, 0x8000
	s_addc_u32 s37, s39, 0
	s_add_i32 m0, s5, 0xc000
	ds_read_b128 v[144:147], v210
	ds_read_b128 v[148:151], v210 offset:1024
	ds_read_b128 v[192:195], v210 offset:2048
	ds_read_b128 v[196:199], v210 offset:3072
	ds_read_b128 v[200:203], v210 offset:4096
	ds_read_b128 v[204:207], v210 offset:5120
	ds_read_b128 v[214:217], v210 offset:6144
	ds_read_b128 v[218:221], v210 offset:7168
	global_load_lds_dwordx4 v186, s[30:31]
	s_add_i32 m0, s5, 0xe000
	s_nop 0
	global_load_lds_dwordx4 v188, s[30:31]
	s_waitcnt lgkmcnt(8)
	s_waitcnt lgkmcnt(0)
	s_setprio 1
	s_barrier
	v_mfma_f32_16x16x32_bf16 v[120:123], v[128:131], v[144:147], v[120:123]
	v_mfma_f32_16x16x32_bf16 v[116:119], v[136:139], v[144:147], v[116:119]
	v_mfma_f32_16x16x32_bf16 v[108:111], v[128:131], v[192:195], v[108:111]
	v_mfma_f32_16x16x32_bf16 v[100:103], v[136:139], v[192:195], v[100:103]
	v_mfma_f32_16x16x32_bf16 v[92:95], v[128:131], v[200:203], v[92:95]
	v_mfma_f32_16x16x32_bf16 v[84:87], v[136:139], v[200:203], v[84:87]
	v_mfma_f32_16x16x32_bf16 v[76:79], v[128:131], v[214:217], v[76:79]
	v_mfma_f32_16x16x32_bf16 v[68:71], v[136:139], v[214:217], v[68:71]
	v_mfma_f32_16x16x32_bf16 v[120:123], v[132:135], v[148:151], v[120:123]
	v_mfma_f32_16x16x32_bf16 v[116:119], v[140:143], v[148:151], v[116:119]
	v_mfma_f32_16x16x32_bf16 v[108:111], v[132:135], v[196:199], v[108:111]
	v_mfma_f32_16x16x32_bf16 v[100:103], v[140:143], v[196:199], v[100:103]
	v_mfma_f32_16x16x32_bf16 v[92:95], v[132:135], v[204:207], v[92:95]
	v_mfma_f32_16x16x32_bf16 v[84:87], v[140:143], v[204:207], v[84:87]
	v_mfma_f32_16x16x32_bf16 v[76:79], v[132:135], v[218:221], v[76:79]
	v_mfma_f32_16x16x32_bf16 v[68:71], v[140:143], v[218:221], v[68:71]
	s_barrier
	s_setprio 0
	s_add_i32 s27, s52, s4
	s_add_u32 s98, s34, s8
	s_addc_u32 s99, s35, s9
	s_mov_b32 m0, s27
	ds_read_b128 v[222:225], v211
	ds_read_b128 v[226:229], v211 offset:1024
	ds_read_b128 v[230:233], v211 offset:2048
	ds_read_b128 v[234:237], v211 offset:3072
	global_load_lds_dwordx4 v162, s[34:35]
	s_add_i32 m0, s27, 0x2000
	s_nop 0
	global_load_lds_dwordx4 v166, s[34:35]
	s_waitcnt lgkmcnt(0)
	s_setprio 1
	s_barrier
	v_mfma_f32_16x16x32_bf16 v[124:127], v[222:225], v[144:147], v[124:127]
	v_mfma_f32_16x16x32_bf16 v[112:115], v[230:233], v[144:147], v[112:115]
	v_mfma_f32_16x16x32_bf16 v[104:107], v[222:225], v[192:195], v[104:107]
	v_mfma_f32_16x16x32_bf16 v[96:99], v[230:233], v[192:195], v[96:99]
	v_mfma_f32_16x16x32_bf16 v[88:91], v[222:225], v[200:203], v[88:91]
	v_mfma_f32_16x16x32_bf16 v[80:83], v[230:233], v[200:203], v[80:83]
	v_mfma_f32_16x16x32_bf16 v[72:75], v[222:225], v[214:217], v[72:75]
	v_mfma_f32_16x16x32_bf16 v[64:67], v[230:233], v[214:217], v[64:67]
	v_mfma_f32_16x16x32_bf16 v[124:127], v[226:229], v[148:151], v[124:127]
	v_mfma_f32_16x16x32_bf16 v[112:115], v[234:237], v[148:151], v[112:115]
	v_mfma_f32_16x16x32_bf16 v[104:107], v[226:229], v[196:199], v[104:107]
	v_mfma_f32_16x16x32_bf16 v[96:99], v[234:237], v[196:199], v[96:99]
	v_mfma_f32_16x16x32_bf16 v[88:91], v[226:229], v[204:207], v[88:91]
	v_mfma_f32_16x16x32_bf16 v[80:83], v[234:237], v[204:207], v[80:83]
	v_mfma_f32_16x16x32_bf16 v[72:75], v[226:229], v[218:221], v[72:75]
	v_mfma_f32_16x16x32_bf16 v[64:67], v[234:237], v[218:221], v[64:67]
	s_barrier
	s_setprio 0
	s_mov_b32 m0, s5
	ds_read_b128 v[144:147], v210 offset:16384
	ds_read_b128 v[148:151], v210 offset:17408
	ds_read_b128 v[192:195], v210 offset:18432
	ds_read_b128 v[196:199], v210 offset:19456
	ds_read_b128 v[200:203], v210 offset:20480
	ds_read_b128 v[204:207], v210 offset:21504
	ds_read_b128 v[214:217], v210 offset:22528
	ds_read_b128 v[218:221], v210 offset:23552
	global_load_lds_dwordx4 v160, s[38:39]
	s_mov_b32 m0, s33
	s_nop 0
	global_load_lds_dwordx4 v164, s[38:39]
	s_waitcnt lgkmcnt(0)
	s_setprio 1
	s_barrier
	v_mfma_f32_16x16x32_bf16 v[60:63], v[128:131], v[144:147], v[60:63]
	v_mfma_f32_16x16x32_bf16 v[56:59], v[136:139], v[144:147], v[56:59]
	v_mfma_f32_16x16x32_bf16 v[44:47], v[128:131], v[192:195], v[44:47]
	v_mfma_f32_16x16x32_bf16 v[40:43], v[136:139], v[192:195], v[40:43]
	v_mfma_f32_16x16x32_bf16 v[28:31], v[128:131], v[200:203], v[28:31]
	v_mfma_f32_16x16x32_bf16 v[24:27], v[136:139], v[200:203], v[24:27]
	v_mfma_f32_16x16x32_bf16 v[12:15], v[128:131], v[214:217], v[12:15]
	v_mfma_f32_16x16x32_bf16 v[8:11], v[136:139], v[214:217], v[8:11]
	v_mfma_f32_16x16x32_bf16 v[60:63], v[132:135], v[148:151], v[60:63]
	v_mfma_f32_16x16x32_bf16 v[56:59], v[140:143], v[148:151], v[56:59]
	v_mfma_f32_16x16x32_bf16 v[44:47], v[132:135], v[196:199], v[44:47]
	v_mfma_f32_16x16x32_bf16 v[40:43], v[140:143], v[196:199], v[40:43]
	v_mfma_f32_16x16x32_bf16 v[28:31], v[132:135], v[204:207], v[28:31]
	v_mfma_f32_16x16x32_bf16 v[24:27], v[140:143], v[204:207], v[24:27]
	v_mfma_f32_16x16x32_bf16 v[12:15], v[132:135], v[218:221], v[12:15]
	v_mfma_f32_16x16x32_bf16 v[8:11], v[140:143], v[218:221], v[8:11]
	s_barrier
	s_setprio 0
	s_add_u32 s56, s34, 0x80000
	s_addc_u32 s57, s35, 0
	s_add_i32 s27, s53, s4
	s_mov_b32 m0, s27
	s_nop 0
	global_load_lds_dwordx4 v162, s[56:57]
	s_add_i32 m0, s27, 0x2000
	s_nop 0
	global_load_lds_dwordx4 v166, s[56:57]
	s_waitcnt vmcnt(6)
	s_setprio 1
	s_barrier
; #define PG8_STAGE(bufoff, gbase, voff) do { _Pragma("unroll") for (int _i = 0; _i < 2; ++_i) \
;         __builtin_amdgcn_global_load_lds((const unsigned*)((const char*)(gbase) + (voff)[_i]), (LAS unsigned*)(lds + (bufoff) + ldsw + _i * 8192), 16, 0, 0); } while (0)
; #define PG8_LDA(dst, b, h) do { _Pragma("unroll") for (int m = 0; m < 4; ++m) _Pragma("unroll") for (int k = 0; k < 2; ++k) dst[m][k] = *(const LAS bf16x8*)(lds + PG8_SA(b, h) + aoff + m * 2048 + k * 1024); } while (0)
; #define PG8_LDB(dst, b, h) do { _Pragma("unroll") for (int n = 0; n < 2; ++n) _Pragma("unroll") for (int k = 0; k < 2; ++k) dst[n][k] = *(const LAS bf16x8*)(lds + PG8_SB(b, h) + boff + n * 2048 + k * 1024); } while (0)
; #define PG8_MMA(ai, bj, At, Bt) do { __builtin_amdgcn_s_setprio(1); _Pragma("unroll") for (int m = 0; m < 4; ++m) _Pragma("unroll") for (int n = 0; n < 2; ++n) _Pragma("unroll") for (int k = 0; k < 2; ++k) \
;         acc[ai][bj][m][n] = __builtin_amdgcn_mfma_f32_16x16x32_bf16(Bt[n][k], At[m][k], acc[ai][bj][m][n], 0, 0, 0); __builtin_amdgcn_s_setprio(0); } while (0)
; #define PG8_WAIT_V(n) asm volatile("s_waitcnt vmcnt(" #n ")" ::: "memory")
; #define PG8_WAIT_L(n) asm volatile("s_waitcnt lgkmcnt(" #n ")" ::: "memory")
; #define PG8_BAR __builtin_amdgcn_s_barrier()
; #define PG8_SCHED __builtin_amdgcn_sched_barrier(0)
; template <class Epi, class Sched, bool ATILE = false>
; __device__ __forceinline__ void gemm_phase(LAS unsigned char* lds, const Gemm g, const Sched& S, const Epi& E) {
;     ...
;             PG8_WAIT_V(6); PG8_BAR; PG8_MMA(1, 1, At, B1); PG8_BAR;
;             PG8_LDB(B0, 1, 0); PG8_SCHED; PG8_LDA(At, 1, 0); PG8_STAGE(PG8_SA(0, 1), a2 + hstepA, voffA);
;             PG8_WAIT_L(8); PG8_BAR; PG8_WAIT_L(0); PG8_MMA(0, 0, At, B0); PG8_BAR; PG8_SCHED;
;             PG8_LDB(B1, 1, 1); PG8_STAGE(PG8_SB(1, 0), b3, voffB);
;             PG8_BAR; PG8_WAIT_L(0); PG8_MMA(0, 1, At, B1); PG8_BAR;
	v_mfma_f32_16x16x32_bf16 v[52:55], v[222:225], v[144:147], v[52:55]
	v_mfma_f32_16x16x32_bf16 v[48:51], v[230:233], v[144:147], v[48:51]
	v_mfma_f32_16x16x32_bf16 v[36:39], v[222:225], v[192:195], v[36:39]
	v_mfma_f32_16x16x32_bf16 v[32:35], v[230:233], v[192:195], v[32:35]
	v_mfma_f32_16x16x32_bf16 v[20:23], v[222:225], v[200:203], v[20:23]
	v_mfma_f32_16x16x32_bf16 v[16:19], v[230:233], v[200:203], v[16:19]
	v_mfma_f32_16x16x32_bf16 v[4:7], v[222:225], v[214:217], v[4:7]
	v_mfma_f32_16x16x32_bf16 v[0:3], v[230:233], v[214:217], v[0:3]
	v_mfma_f32_16x16x32_bf16 v[52:55], v[226:229], v[148:151], v[52:55]
	v_mfma_f32_16x16x32_bf16 v[48:51], v[234:237], v[148:151], v[48:51]
	v_mfma_f32_16x16x32_bf16 v[36:39], v[226:229], v[196:199], v[36:39]
	v_mfma_f32_16x16x32_bf16 v[32:35], v[234:237], v[196:199], v[32:35]
	v_mfma_f32_16x16x32_bf16 v[20:23], v[226:229], v[204:207], v[20:23]
	v_mfma_f32_16x16x32_bf16 v[16:19], v[234:237], v[204:207], v[16:19]
	v_mfma_f32_16x16x32_bf16 v[4:7], v[226:229], v[218:221], v[4:7]
	v_mfma_f32_16x16x32_bf16 v[0:3], v[234:237], v[218:221], v[0:3]
	s_barrier
	s_setprio 0
	s_add_i32 s27, 0, 0x18000
	v_add_u32_e32 v140, s27, v157
	ds_read_b128 v[128:131], v140
	ds_read_b128 v[132:135], v140 offset:1024
	ds_read_b128 v[136:139], v140 offset:2048
	ds_read_b128 v[140:143], v140 offset:3072
	s_add_u32 s38, s38, 0x4000
	s_addc_u32 s39, s39, 0
	s_mov_b32 m0, s40
	ds_read_b128 v[144:147], v210 offset:32768
	ds_read_b128 v[148:151], v210 offset:33792
	ds_read_b128 v[192:195], v210 offset:34816
	ds_read_b128 v[196:199], v210 offset:35840
	ds_read_b128 v[200:203], v210 offset:36864
	ds_read_b128 v[204:207], v210 offset:37888
	ds_read_b128 v[214:217], v210 offset:38912
	ds_read_b128 v[218:221], v210 offset:39936
	global_load_lds_dwordx4 v160, s[38:39]
	s_mov_b32 m0, s41
	s_nop 0
	global_load_lds_dwordx4 v164, s[38:39]
	s_waitcnt lgkmcnt(8)
	s_waitcnt lgkmcnt(0)
	s_setprio 1
	s_barrier
	v_mfma_f32_16x16x32_bf16 v[120:123], v[128:131], v[144:147], v[120:123]
	v_mfma_f32_16x16x32_bf16 v[116:119], v[136:139], v[144:147], v[116:119]
	v_mfma_f32_16x16x32_bf16 v[108:111], v[128:131], v[192:195], v[108:111]
	v_mfma_f32_16x16x32_bf16 v[100:103], v[136:139], v[192:195], v[100:103]
	v_mfma_f32_16x16x32_bf16 v[92:95], v[128:131], v[200:203], v[92:95]
	v_mfma_f32_16x16x32_bf16 v[84:87], v[136:139], v[200:203], v[84:87]
	v_mfma_f32_16x16x32_bf16 v[76:79], v[128:131], v[214:217], v[76:79]
	v_mfma_f32_16x16x32_bf16 v[68:71], v[136:139], v[214:217], v[68:71]
	v_mfma_f32_16x16x32_bf16 v[120:123], v[132:135], v[148:151], v[120:123]
	v_mfma_f32_16x16x32_bf16 v[116:119], v[140:143], v[148:151], v[116:119]
	v_mfma_f32_16x16x32_bf16 v[108:111], v[132:135], v[196:199], v[108:111]
	v_mfma_f32_16x16x32_bf16 v[100:103], v[140:143], v[196:199], v[100:103]
	v_mfma_f32_16x16x32_bf16 v[92:95], v[132:135], v[204:207], v[92:95]
	v_mfma_f32_16x16x32_bf16 v[84:87], v[140:143], v[204:207], v[84:87]
	v_mfma_f32_16x16x32_bf16 v[76:79], v[132:135], v[218:221], v[76:79]
	v_mfma_f32_16x16x32_bf16 v[68:71], v[140:143], v[218:221], v[68:71]
	s_barrier
	s_setprio 0
	s_add_i32 s38, 0, 0x1c000
	s_add_i32 s27, s27, s4
	v_add_u32_e32 v213, s38, v157
	s_mov_b32 m0, s27
	ds_read_b128 v[222:225], v213
	ds_read_b128 v[226:229], v213 offset:1024
	ds_read_b128 v[230:233], v213 offset:2048
	ds_read_b128 v[234:237], v213 offset:3072
	global_load_lds_dwordx4 v162, s[98:99]
	s_add_i32 m0, s27, 0x2000
	s_nop 0
	global_load_lds_dwordx4 v166, s[98:99]
	s_waitcnt lgkmcnt(0)
	s_setprio 1
	s_barrier
; #define PG8_STAGE(bufoff, gbase, voff) do { _Pragma("unroll") for (int _i = 0; _i < 2; ++_i) \
;         __builtin_amdgcn_global_load_lds((const unsigned*)((const char*)(gbase) + (voff)[_i]), (LAS unsigned*)(lds + (bufoff) + ldsw + _i * 8192), 16, 0, 0); } while (0)
; #define PG8_LDA(dst, b, h) do { _Pragma("unroll") for (int m = 0; m < 4; ++m) _Pragma("unroll") for (int k = 0; k < 2; ++k) dst[m][k] = *(const LAS bf16x8*)(lds + PG8_SA(b, h) + aoff + m * 2048 + k * 1024); } while (0)
; #define PG8_MMA(ai, bj, At, Bt) do { __builtin_amdgcn_s_setprio(1); _Pragma("unroll") for (int m = 0; m < 4; ++m) _Pragma("unroll") for (int n = 0; n < 2; ++n) _Pragma("unroll") for (int k = 0; k < 2; ++k) \
;         acc[ai][bj][m][n] = __builtin_amdgcn_mfma_f32_16x16x32_bf16(Bt[n][k], At[m][k], acc[ai][bj][m][n], 0, 0, 0); __builtin_amdgcn_s_setprio(0); } while (0)
; #define PG8_WAIT_V(n) asm volatile("s_waitcnt vmcnt(" #n ")" ::: "memory")
; #define PG8_WAIT_L(n) asm volatile("s_waitcnt lgkmcnt(" #n ")" ::: "memory")
; #define PG8_BAR __builtin_amdgcn_s_barrier()
; #define PG8_SCHED __builtin_amdgcn_sched_barrier(0)
; template <class Epi, class Sched, bool ATILE = false>
; __device__ __forceinline__ void gemm_phase(LAS unsigned char* lds, const Gemm g, const Sched& S, const Epi& E) {
;     ...
;             PG8_BAR; PG8_WAIT_L(0); PG8_MMA(0, 1, At, B1); PG8_BAR;
;             PG8_LDA(At, 1, 1); PG8_STAGE(PG8_SA(1, 0), a3, voffA);
;             PG8_BAR; PG8_WAIT_L(0); PG8_MMA(1, 0, At, B0); PG8_BAR; PG8_SCHED;
;             PG8_STAGE(PG8_SB(1, 1), b3 + hstepB, voffB);
;             PG8_WAIT_V(6); PG8_BAR; PG8_MMA(1, 1, At, B1); PG8_BAR;
;         }
	v_mfma_f32_16x16x32_bf16 v[124:127], v[222:225], v[144:147], v[124:127]
	v_mfma_f32_16x16x32_bf16 v[112:115], v[230:233], v[144:147], v[112:115]
	v_mfma_f32_16x16x32_bf16 v[104:107], v[222:225], v[192:195], v[104:107]
	v_mfma_f32_16x16x32_bf16 v[96:99], v[230:233], v[192:195], v[96:99]
	v_mfma_f32_16x16x32_bf16 v[88:91], v[222:225], v[200:203], v[88:91]
	v_mfma_f32_16x16x32_bf16 v[80:83], v[230:233], v[200:203], v[80:83]
	v_mfma_f32_16x16x32_bf16 v[72:75], v[222:225], v[214:217], v[72:75]
	v_mfma_f32_16x16x32_bf16 v[64:67], v[230:233], v[214:217], v[64:67]
	v_mfma_f32_16x16x32_bf16 v[124:127], v[226:229], v[148:151], v[124:127]
	v_mfma_f32_16x16x32_bf16 v[112:115], v[234:237], v[148:151], v[112:115]
	v_mfma_f32_16x16x32_bf16 v[104:107], v[226:229], v[196:199], v[104:107]
	v_mfma_f32_16x16x32_bf16 v[96:99], v[234:237], v[196:199], v[96:99]
	v_mfma_f32_16x16x32_bf16 v[88:91], v[226:229], v[204:207], v[88:91]
	v_mfma_f32_16x16x32_bf16 v[80:83], v[234:237], v[204:207], v[80:83]
	v_mfma_f32_16x16x32_bf16 v[72:75], v[226:229], v[218:221], v[72:75]
	v_mfma_f32_16x16x32_bf16 v[64:67], v[234:237], v[218:221], v[64:67]
	s_barrier
	s_setprio 0
	s_mov_b32 m0, s43
	ds_read_b128 v[144:147], v210 offset:49152
	ds_read_b128 v[148:151], v210 offset:50176
	ds_read_b128 v[192:195], v210 offset:51200
	ds_read_b128 v[196:199], v210 offset:52224
	ds_read_b128 v[200:203], v210 offset:53248
	ds_read_b128 v[204:207], v210 offset:54272
	ds_read_b128 v[214:217], v210 offset:55296
	ds_read_b128 v[218:221], v210 offset:56320
	global_load_lds_dwordx4 v160, s[36:37]
	s_mov_b32 m0, s44
	s_nop 0
	global_load_lds_dwordx4 v164, s[36:37]
	s_waitcnt lgkmcnt(0)
	s_setprio 1
	s_barrier
	v_mfma_f32_16x16x32_bf16 v[60:63], v[128:131], v[144:147], v[60:63]
	v_mfma_f32_16x16x32_bf16 v[56:59], v[136:139], v[144:147], v[56:59]
	v_mfma_f32_16x16x32_bf16 v[44:47], v[128:131], v[192:195], v[44:47]
	v_mfma_f32_16x16x32_bf16 v[40:43], v[136:139], v[192:195], v[40:43]
	v_mfma_f32_16x16x32_bf16 v[28:31], v[128:131], v[200:203], v[28:31]
	v_mfma_f32_16x16x32_bf16 v[24:27], v[136:139], v[200:203], v[24:27]
	v_mfma_f32_16x16x32_bf16 v[12:15], v[128:131], v[214:217], v[12:15]
	v_mfma_f32_16x16x32_bf16 v[8:11], v[136:139], v[214:217], v[8:11]
	v_mfma_f32_16x16x32_bf16 v[60:63], v[132:135], v[148:151], v[60:63]
	v_mfma_f32_16x16x32_bf16 v[56:59], v[140:143], v[148:151], v[56:59]
	v_mfma_f32_16x16x32_bf16 v[44:47], v[132:135], v[196:199], v[44:47]
	v_mfma_f32_16x16x32_bf16 v[40:43], v[140:143], v[196:199], v[40:43]
	v_mfma_f32_16x16x32_bf16 v[28:31], v[132:135], v[204:207], v[28:31]
	v_mfma_f32_16x16x32_bf16 v[24:27], v[140:143], v[204:207], v[24:27]
	v_mfma_f32_16x16x32_bf16 v[12:15], v[132:135], v[218:221], v[12:15]
	v_mfma_f32_16x16x32_bf16 v[8:11], v[140:143], v[218:221], v[8:11]
	s_barrier
	s_setprio 0
	s_add_u32 s34, s34, 0x80080
	s_addc_u32 s35, s35, 0
	s_add_i32 s27, s38, s4
	s_mov_b32 m0, s27
	s_nop 0
	global_load_lds_dwordx4 v162, s[34:35]
	s_add_i32 m0, s27, 0x2000
	s_nop 0
	global_load_lds_dwordx4 v166, s[34:35]
	s_waitcnt vmcnt(6)
	s_setprio 1
	s_barrier
	v_mfma_f32_16x16x32_bf16 v[52:55], v[222:225], v[144:147], v[52:55]
	v_mfma_f32_16x16x32_bf16 v[48:51], v[230:233], v[144:147], v[48:51]
	v_mfma_f32_16x16x32_bf16 v[36:39], v[222:225], v[192:195], v[36:39]
	v_mfma_f32_16x16x32_bf16 v[32:35], v[230:233], v[192:195], v[32:35]
	v_mfma_f32_16x16x32_bf16 v[20:23], v[222:225], v[200:203], v[20:23]
	v_mfma_f32_16x16x32_bf16 v[16:19], v[230:233], v[200:203], v[16:19]
	v_mfma_f32_16x16x32_bf16 v[4:7], v[222:225], v[214:217], v[4:7]
	v_mfma_f32_16x16x32_bf16 v[0:3], v[230:233], v[214:217], v[0:3]
	v_mfma_f32_16x16x32_bf16 v[52:55], v[226:229], v[148:151], v[52:55]
	v_mfma_f32_16x16x32_bf16 v[48:51], v[234:237], v[148:151], v[48:51]
	v_mfma_f32_16x16x32_bf16 v[36:39], v[226:229], v[196:199], v[36:39]
	v_mfma_f32_16x16x32_bf16 v[32:35], v[234:237], v[196:199], v[32:35]
	v_mfma_f32_16x16x32_bf16 v[20:23], v[226:229], v[204:207], v[20:23]
	v_mfma_f32_16x16x32_bf16 v[16:19], v[234:237], v[204:207], v[16:19]
	v_mfma_f32_16x16x32_bf16 v[4:7], v[226:229], v[218:221], v[4:7]
	v_mfma_f32_16x16x32_bf16 v[0:3], v[234:237], v[218:221], v[0:3]
	s_barrier
	s_setprio 0
	s_add_u32 s13, s13, 0x100
	s_addc_u32 s17, s17, 0
	s_add_u32 s30, s30, 0x10000
	s_addc_u32 s31, s31, 0
	s_cmp_ge_i32 s29, s1
	s_mov_b32 s27, s29
	s_cbranch_scc0 .LBB0_1658
	s_branch .LBB0_1662

; #define PG8_STAGE(bufoff, gbase, voff) do { _Pragma("unroll") for (int _i = 0; _i < 2; ++_i) \
;         __builtin_amdgcn_global_load_lds((const unsigned*)((const char*)(gbase) + (voff)[_i]), (LAS unsigned*)(lds + (bufoff) + ldsw + _i * 8192), 16, 0, 0); } while (0)
; #define PG8_LDA(dst, b, h) do { _Pragma("unroll") for (int m = 0; m < 4; ++m) _Pragma("unroll") for (int k = 0; k < 2; ++k) dst[m][k] = *(const LAS bf16x8*)(lds + PG8_SA(b, h) + aoff + m * 2048 + k * 1024); } while (0)
; #define PG8_LDB(dst, b, h) do { _Pragma("unroll") for (int n = 0; n < 2; ++n) _Pragma("unroll") for (int k = 0; k < 2; ++k) dst[n][k] = *(const LAS bf16x8*)(lds + PG8_SB(b, h) + boff + n * 2048 + k * 1024); } while (0)
; #define PG8_MMA(ai, bj, At, Bt) do { __builtin_amdgcn_s_setprio(1); _Pragma("unroll") for (int m = 0; m < 4; ++m) _Pragma("unroll") for (int n = 0; n < 2; ++n) _Pragma("unroll") for (int k = 0; k < 2; ++k) \
;         acc[ai][bj][m][n] = __builtin_amdgcn_mfma_f32_16x16x32_bf16(Bt[n][k], At[m][k], acc[ai][bj][m][n], 0, 0, 0); __builtin_amdgcn_s_setprio(0); } while (0)
; #define PG8_WAIT_V(n) asm volatile("s_waitcnt vmcnt(" #n ")" ::: "memory")
; #define PG8_WAIT_L(n) asm volatile("s_waitcnt lgkmcnt(" #n ")" ::: "memory")
; template <class Epi, class Sched, bool ATILE = false>
; __device__ __forceinline__ void gemm_phase(LAS unsigned char* lds, const Gemm g, const Sched& S, const Epi& E) {
;     ...
;         for (int t = 0; t < nt; t += 2) {
;             const bool last = (t == nt - 2);
;             const char* a1 = cA + (size_t)(t + 1) * kstepA;
;             const char* a2 = last ? nA : cA + (size_t)(t + 2) * kstepA; const char* b2 = last ? nB : cB + (size_t)(t + 2) * kstep;
;             const char* a3 = a2 + kstepA; const char* b3 = b2 + kstep;
;             PG8_LDB(B0, 0, 0); PG8_SCHED; PG8_LDA(At, 0, 0); PG8_STAGE(PG8_SA(1, 1), a1 + hstepA, voffA);
;             PG8_WAIT_L(8); PG8_BAR; PG8_WAIT_L(0); PG8_MMA(0, 0, At, B0); PG8_BAR; PG8_SCHED;
;             PG8_LDB(B1, 0, 1); PG8_STAGE(PG8_SB(0, 0), b2, voffB);
;             PG8_BAR; PG8_WAIT_L(0); PG8_MMA(0, 1, At, B1); PG8_BAR;
;             PG8_LDA(At, 0, 1); PG8_STAGE(PG8_SA(0, 0), a2, voffA);
;             PG8_BAR; PG8_WAIT_L(0); PG8_MMA(1, 0, At, B0); PG8_BAR; PG8_SCHED;
;             PG8_STAGE(PG8_SB(0, 1), b2 + hstepB, voffB);
;             PG8_WAIT_V(6); PG8_BAR; PG8_MMA(1, 1, At, B1); PG8_BAR;
.LBB0_1812:
	ds_read_b128 v[176:179], v139
	ds_read_b128 v[180:183], v139 offset:1024
	ds_read_b128 v[184:187], v139 offset:2048
	ds_read_b128 v[188:191], v139 offset:3072
	s_add_i32 s34, s8, 2
	s_add_u32 s9, s6, 0xfff80080
	s_addc_u32 s10, s7, -1
	s_cmp_eq_u32 s19, s8
	s_cselect_b32 s8, s18, s25
	s_cselect_b32 s11, s13, s10
	s_cselect_b32 s10, s16, s9
	s_cselect_b32 s9, s17, s27
	s_add_i32 m0, s37, 0xc000
	ds_read_b128 v[192:195], v159
	ds_read_b128 v[196:199], v159 offset:1024
	ds_read_b128 v[200:203], v159 offset:2048
	ds_read_b128 v[204:207], v159 offset:3072
	ds_read_b128 v[208:211], v159 offset:4096
	ds_read_b128 v[212:215], v159 offset:5120
	ds_read_b128 v[216:219], v159 offset:6144
	ds_read_b128 v[220:223], v159 offset:7168
	global_load_lds_dwordx4 v164, s[6:7]
	s_add_i32 m0, s37, 0xe000
	s_nop 0
	global_load_lds_dwordx4 v166, s[6:7]
	s_waitcnt lgkmcnt(8)
	s_waitcnt lgkmcnt(0)
	s_setprio 1
	s_barrier
	v_mfma_f32_16x16x32_bf16 v[120:123], v[176:179], v[192:195], v[120:123]
	v_mfma_f32_16x16x32_bf16 v[112:115], v[184:187], v[192:195], v[112:115]
	v_mfma_f32_16x16x32_bf16 v[104:107], v[176:179], v[200:203], v[104:107]
	v_mfma_f32_16x16x32_bf16 v[96:99], v[184:187], v[200:203], v[96:99]
	v_mfma_f32_16x16x32_bf16 v[88:91], v[176:179], v[208:211], v[88:91]
	v_mfma_f32_16x16x32_bf16 v[80:83], v[184:187], v[208:211], v[80:83]
	v_mfma_f32_16x16x32_bf16 v[72:75], v[176:179], v[216:219], v[72:75]
	v_mfma_f32_16x16x32_bf16 v[64:67], v[184:187], v[216:219], v[64:67]
	v_mfma_f32_16x16x32_bf16 v[120:123], v[180:183], v[196:199], v[120:123]
	v_mfma_f32_16x16x32_bf16 v[112:115], v[188:191], v[196:199], v[112:115]
	v_mfma_f32_16x16x32_bf16 v[104:107], v[180:183], v[204:207], v[104:107]
	v_mfma_f32_16x16x32_bf16 v[96:99], v[188:191], v[204:207], v[96:99]
	v_mfma_f32_16x16x32_bf16 v[88:91], v[180:183], v[212:215], v[88:91]
	v_mfma_f32_16x16x32_bf16 v[80:83], v[188:191], v[212:215], v[80:83]
	v_mfma_f32_16x16x32_bf16 v[72:75], v[180:183], v[220:223], v[72:75]
	v_mfma_f32_16x16x32_bf16 v[64:67], v[188:191], v[220:223], v[64:67]
	s_barrier
	s_setprio 0
	s_add_i32 s35, s51, s36
	s_add_u32 s98, s8, s22
	s_addc_u32 s99, s9, s23
	s_mov_b32 m0, s35
	ds_read_b128 v[224:227], v173
	ds_read_b128 v[228:231], v173 offset:1024
	ds_read_b128 v[232:235], v173 offset:2048
	ds_read_b128 v[236:239], v173 offset:3072
	global_load_lds_dwordx4 v130, s[8:9]
	s_add_i32 m0, s35, 0x2000
	s_nop 0
	global_load_lds_dwordx4 v134, s[8:9]
	s_waitcnt lgkmcnt(0)
	s_setprio 1
	s_barrier
	v_mfma_f32_16x16x32_bf16 v[124:127], v[224:227], v[192:195], v[124:127]
	v_mfma_f32_16x16x32_bf16 v[116:119], v[232:235], v[192:195], v[116:119]
	v_mfma_f32_16x16x32_bf16 v[108:111], v[224:227], v[200:203], v[108:111]
	v_mfma_f32_16x16x32_bf16 v[100:103], v[232:235], v[200:203], v[100:103]
	v_mfma_f32_16x16x32_bf16 v[92:95], v[224:227], v[208:211], v[92:95]
	v_mfma_f32_16x16x32_bf16 v[84:87], v[232:235], v[208:211], v[84:87]
	v_mfma_f32_16x16x32_bf16 v[76:79], v[224:227], v[216:219], v[76:79]
	v_mfma_f32_16x16x32_bf16 v[68:71], v[232:235], v[216:219], v[68:71]
	v_mfma_f32_16x16x32_bf16 v[124:127], v[228:231], v[196:199], v[124:127]
	v_mfma_f32_16x16x32_bf16 v[116:119], v[236:239], v[196:199], v[116:119]
	v_mfma_f32_16x16x32_bf16 v[108:111], v[228:231], v[204:207], v[108:111]
	v_mfma_f32_16x16x32_bf16 v[100:103], v[236:239], v[204:207], v[100:103]
	v_mfma_f32_16x16x32_bf16 v[92:95], v[228:231], v[212:215], v[92:95]
	v_mfma_f32_16x16x32_bf16 v[84:87], v[236:239], v[212:215], v[84:87]
	v_mfma_f32_16x16x32_bf16 v[76:79], v[228:231], v[220:223], v[76:79]
	v_mfma_f32_16x16x32_bf16 v[68:71], v[236:239], v[220:223], v[68:71]
	s_barrier
	s_setprio 0
	s_mov_b32 m0, s37
	s_add_u32 s100, s10, s22
	s_addc_u32 s101, s11, s23
	ds_read_b128 v[192:195], v159 offset:16384
	ds_read_b128 v[196:199], v159 offset:17408
	ds_read_b128 v[200:203], v159 offset:18432
	ds_read_b128 v[204:207], v159 offset:19456
	ds_read_b128 v[208:211], v159 offset:20480
	ds_read_b128 v[212:215], v159 offset:21504
	ds_read_b128 v[216:219], v159 offset:22528
	ds_read_b128 v[220:223], v159 offset:23552
	global_load_lds_dwordx4 v128, s[10:11]
	s_mov_b32 m0, s38
	s_nop 0
	global_load_lds_dwordx4 v132, s[10:11]
	s_waitcnt lgkmcnt(0)
	s_setprio 1
	s_barrier
	v_mfma_f32_16x16x32_bf16 v[56:59], v[176:179], v[192:195], v[56:59]
	v_mfma_f32_16x16x32_bf16 v[48:51], v[184:187], v[192:195], v[48:51]
	v_mfma_f32_16x16x32_bf16 v[40:43], v[176:179], v[200:203], v[40:43]
	v_mfma_f32_16x16x32_bf16 v[32:35], v[184:187], v[200:203], v[32:35]
	v_mfma_f32_16x16x32_bf16 v[24:27], v[176:179], v[208:211], v[24:27]
	v_mfma_f32_16x16x32_bf16 v[16:19], v[184:187], v[208:211], v[16:19]
	v_mfma_f32_16x16x32_bf16 v[8:11], v[176:179], v[216:219], v[8:11]
	v_mfma_f32_16x16x32_bf16 v[4:7], v[184:187], v[216:219], v[4:7]
	v_mfma_f32_16x16x32_bf16 v[56:59], v[180:183], v[196:199], v[56:59]
	v_mfma_f32_16x16x32_bf16 v[48:51], v[188:191], v[196:199], v[48:51]
	v_mfma_f32_16x16x32_bf16 v[40:43], v[180:183], v[204:207], v[40:43]
	v_mfma_f32_16x16x32_bf16 v[32:35], v[188:191], v[204:207], v[32:35]
	v_mfma_f32_16x16x32_bf16 v[24:27], v[180:183], v[212:215], v[24:27]
	v_mfma_f32_16x16x32_bf16 v[16:19], v[188:191], v[212:215], v[16:19]
	v_mfma_f32_16x16x32_bf16 v[8:11], v[180:183], v[220:223], v[8:11]
	v_mfma_f32_16x16x32_bf16 v[4:7], v[188:191], v[220:223], v[4:7]
	s_barrier
	s_setprio 0
	s_add_u32 s54, s8, 0x80000
	s_addc_u32 s55, s9, 0
	s_add_i32 s35, s52, s36
	s_mov_b32 m0, s35
	s_nop 0
	global_load_lds_dwordx4 v130, s[54:55]
	s_add_i32 m0, s35, 0x2000
	s_nop 0
	global_load_lds_dwordx4 v134, s[54:55]
	s_waitcnt vmcnt(6)
	s_setprio 1
	s_barrier
; #define PG8_STAGE(bufoff, gbase, voff) do { _Pragma("unroll") for (int _i = 0; _i < 2; ++_i) \
;         __builtin_amdgcn_global_load_lds((const unsigned*)((const char*)(gbase) + (voff)[_i]), (LAS unsigned*)(lds + (bufoff) + ldsw + _i * 8192), 16, 0, 0); } while (0)
; #define PG8_LDA(dst, b, h) do { _Pragma("unroll") for (int m = 0; m < 4; ++m) _Pragma("unroll") for (int k = 0; k < 2; ++k) dst[m][k] = *(const LAS bf16x8*)(lds + PG8_SA(b, h) + aoff + m * 2048 + k * 1024); } while (0)
; #define PG8_LDB(dst, b, h) do { _Pragma("unroll") for (int n = 0; n < 2; ++n) _Pragma("unroll") for (int k = 0; k < 2; ++k) dst[n][k] = *(const LAS bf16x8*)(lds + PG8_SB(b, h) + boff + n * 2048 + k * 1024); } while (0)
; #define PG8_MMA(ai, bj, At, Bt) do { __builtin_amdgcn_s_setprio(1); _Pragma("unroll") for (int m = 0; m < 4; ++m) _Pragma("unroll") for (int n = 0; n < 2; ++n) _Pragma("unroll") for (int k = 0; k < 2; ++k) \
;         acc[ai][bj][m][n] = __builtin_amdgcn_mfma_f32_16x16x32_bf16(Bt[n][k], At[m][k], acc[ai][bj][m][n], 0, 0, 0); __builtin_amdgcn_s_setprio(0); } while (0)
; #define PG8_WAIT_V(n) asm volatile("s_waitcnt vmcnt(" #n ")" ::: "memory")
; #define PG8_WAIT_L(n) asm volatile("s_waitcnt lgkmcnt(" #n ")" ::: "memory")
; #define PG8_BAR __builtin_amdgcn_s_barrier()
; #define PG8_SCHED __builtin_amdgcn_sched_barrier(0)
; template <class Epi, class Sched, bool ATILE = false>
; __device__ __forceinline__ void gemm_phase(LAS unsigned char* lds, const Gemm g, const Sched& S, const Epi& E) {
;     ...
;             PG8_WAIT_V(6); PG8_BAR; PG8_MMA(1, 1, At, B1); PG8_BAR;
;             PG8_LDB(B0, 1, 0); PG8_SCHED; PG8_LDA(At, 1, 0); PG8_STAGE(PG8_SA(0, 1), a2 + hstepA, voffA);
;             PG8_WAIT_L(8); PG8_BAR; PG8_WAIT_L(0); PG8_MMA(0, 0, At, B0); PG8_BAR; PG8_SCHED;
;             PG8_LDB(B1, 1, 1); PG8_STAGE(PG8_SB(1, 0), b3, voffB);
;             PG8_BAR; PG8_WAIT_L(0); PG8_MMA(0, 1, At, B1); PG8_BAR;
	v_mfma_f32_16x16x32_bf16 v[60:63], v[224:227], v[192:195], v[60:63]
	v_mfma_f32_16x16x32_bf16 v[52:55], v[232:235], v[192:195], v[52:55]
	v_mfma_f32_16x16x32_bf16 v[44:47], v[224:227], v[200:203], v[44:47]
	v_mfma_f32_16x16x32_bf16 v[36:39], v[232:235], v[200:203], v[36:39]
	v_mfma_f32_16x16x32_bf16 v[28:31], v[224:227], v[208:211], v[28:31]
	v_mfma_f32_16x16x32_bf16 v[20:23], v[232:235], v[208:211], v[20:23]
	v_mfma_f32_16x16x32_bf16 v[12:15], v[224:227], v[216:219], v[12:15]
	v_mfma_f32_16x16x32_bf16 v[0:3], v[232:235], v[216:219], v[0:3]
	v_mfma_f32_16x16x32_bf16 v[60:63], v[228:231], v[196:199], v[60:63]
	v_mfma_f32_16x16x32_bf16 v[52:55], v[236:239], v[196:199], v[52:55]
	v_mfma_f32_16x16x32_bf16 v[44:47], v[228:231], v[204:207], v[44:47]
	v_mfma_f32_16x16x32_bf16 v[36:39], v[236:239], v[204:207], v[36:39]
	v_mfma_f32_16x16x32_bf16 v[28:31], v[228:231], v[212:215], v[28:31]
	v_mfma_f32_16x16x32_bf16 v[20:23], v[236:239], v[212:215], v[20:23]
	v_mfma_f32_16x16x32_bf16 v[12:15], v[228:231], v[220:223], v[12:15]
	v_mfma_f32_16x16x32_bf16 v[0:3], v[236:239], v[220:223], v[0:3]
	s_barrier
	s_setprio 0
	s_add_i32 s35, 0, 0x18000
	v_add_u32_e32 v172, s35, v157
	ds_read_b128 v[176:179], v172
	ds_read_b128 v[180:183], v172 offset:1024
	ds_read_b128 v[184:187], v172 offset:2048
	ds_read_b128 v[188:191], v172 offset:3072
	s_add_u32 s10, s10, 0x80000
	s_addc_u32 s11, s11, 0
	s_mov_b32 m0, s39
	ds_read_b128 v[192:195], v159 offset:32768
	ds_read_b128 v[196:199], v159 offset:33792
	ds_read_b128 v[200:203], v159 offset:34816
	ds_read_b128 v[204:207], v159 offset:35840
	ds_read_b128 v[208:211], v159 offset:36864
	ds_read_b128 v[212:215], v159 offset:37888
	ds_read_b128 v[216:219], v159 offset:38912
	ds_read_b128 v[220:223], v159 offset:39936
	global_load_lds_dwordx4 v128, s[10:11]
	s_mov_b32 m0, s40
	s_nop 0
	global_load_lds_dwordx4 v132, s[10:11]
	s_waitcnt lgkmcnt(8)
	s_waitcnt lgkmcnt(0)
	s_setprio 1
	s_barrier
	v_mfma_f32_16x16x32_bf16 v[120:123], v[176:179], v[192:195], v[120:123]
	v_mfma_f32_16x16x32_bf16 v[112:115], v[184:187], v[192:195], v[112:115]
	v_mfma_f32_16x16x32_bf16 v[104:107], v[176:179], v[200:203], v[104:107]
	v_mfma_f32_16x16x32_bf16 v[96:99], v[184:187], v[200:203], v[96:99]
	v_mfma_f32_16x16x32_bf16 v[88:91], v[176:179], v[208:211], v[88:91]
	v_mfma_f32_16x16x32_bf16 v[80:83], v[184:187], v[208:211], v[80:83]
	v_mfma_f32_16x16x32_bf16 v[72:75], v[176:179], v[216:219], v[72:75]
	v_mfma_f32_16x16x32_bf16 v[64:67], v[184:187], v[216:219], v[64:67]
	v_mfma_f32_16x16x32_bf16 v[120:123], v[180:183], v[196:199], v[120:123]
	v_mfma_f32_16x16x32_bf16 v[112:115], v[188:191], v[196:199], v[112:115]
	v_mfma_f32_16x16x32_bf16 v[104:107], v[180:183], v[204:207], v[104:107]
	v_mfma_f32_16x16x32_bf16 v[96:99], v[188:191], v[204:207], v[96:99]
	v_mfma_f32_16x16x32_bf16 v[88:91], v[180:183], v[212:215], v[88:91]
	v_mfma_f32_16x16x32_bf16 v[80:83], v[188:191], v[212:215], v[80:83]
	v_mfma_f32_16x16x32_bf16 v[72:75], v[180:183], v[220:223], v[72:75]
	v_mfma_f32_16x16x32_bf16 v[64:67], v[188:191], v[220:223], v[64:67]
	s_barrier
	s_setprio 0
	s_add_i32 s10, 0, 0x1c000
	s_add_i32 s11, s35, s36
	v_add_u32_e32 v172, s10, v157
	s_mov_b32 m0, s11
	ds_read_b128 v[224:227], v172
	ds_read_b128 v[228:231], v172 offset:1024
	ds_read_b128 v[232:235], v172 offset:2048
	ds_read_b128 v[236:239], v172 offset:3072
	global_load_lds_dwordx4 v130, s[98:99]
	s_add_i32 m0, s11, 0x2000
	s_nop 0
	global_load_lds_dwordx4 v134, s[98:99]
	s_waitcnt lgkmcnt(0)
	s_setprio 1
	s_barrier
; #define PG8_STAGE(bufoff, gbase, voff) do { _Pragma("unroll") for (int _i = 0; _i < 2; ++_i) \
;         __builtin_amdgcn_global_load_lds((const unsigned*)((const char*)(gbase) + (voff)[_i]), (LAS unsigned*)(lds + (bufoff) + ldsw + _i * 8192), 16, 0, 0); } while (0)
; #define PG8_LDA(dst, b, h) do { _Pragma("unroll") for (int m = 0; m < 4; ++m) _Pragma("unroll") for (int k = 0; k < 2; ++k) dst[m][k] = *(const LAS bf16x8*)(lds + PG8_SA(b, h) + aoff + m * 2048 + k * 1024); } while (0)
; #define PG8_MMA(ai, bj, At, Bt) do { __builtin_amdgcn_s_setprio(1); _Pragma("unroll") for (int m = 0; m < 4; ++m) _Pragma("unroll") for (int n = 0; n < 2; ++n) _Pragma("unroll") for (int k = 0; k < 2; ++k) \
;         acc[ai][bj][m][n] = __builtin_amdgcn_mfma_f32_16x16x32_bf16(Bt[n][k], At[m][k], acc[ai][bj][m][n], 0, 0, 0); __builtin_amdgcn_s_setprio(0); } while (0)
; #define PG8_WAIT_V(n) asm volatile("s_waitcnt vmcnt(" #n ")" ::: "memory")
; #define PG8_WAIT_L(n) asm volatile("s_waitcnt lgkmcnt(" #n ")" ::: "memory")
; #define PG8_BAR __builtin_amdgcn_s_barrier()
; #define PG8_SCHED __builtin_amdgcn_sched_barrier(0)
; template <class Epi, class Sched, bool ATILE = false>
; __device__ __forceinline__ void gemm_phase(LAS unsigned char* lds, const Gemm g, const Sched& S, const Epi& E) {
;     ...
;             PG8_BAR; PG8_WAIT_L(0); PG8_MMA(0, 1, At, B1); PG8_BAR;
;             PG8_LDA(At, 1, 1); PG8_STAGE(PG8_SA(1, 0), a3, voffA);
;             PG8_BAR; PG8_WAIT_L(0); PG8_MMA(1, 0, At, B0); PG8_BAR; PG8_SCHED;
;             PG8_STAGE(PG8_SB(1, 1), b3 + hstepB, voffB);
;             PG8_WAIT_V(6); PG8_BAR; PG8_MMA(1, 1, At, B1); PG8_BAR;
;         }
	v_mfma_f32_16x16x32_bf16 v[124:127], v[224:227], v[192:195], v[124:127]
	v_mfma_f32_16x16x32_bf16 v[116:119], v[232:235], v[192:195], v[116:119]
	v_mfma_f32_16x16x32_bf16 v[108:111], v[224:227], v[200:203], v[108:111]
	v_mfma_f32_16x16x32_bf16 v[100:103], v[232:235], v[200:203], v[100:103]
	v_mfma_f32_16x16x32_bf16 v[92:95], v[224:227], v[208:211], v[92:95]
	v_mfma_f32_16x16x32_bf16 v[84:87], v[232:235], v[208:211], v[84:87]
	v_mfma_f32_16x16x32_bf16 v[76:79], v[224:227], v[216:219], v[76:79]
	v_mfma_f32_16x16x32_bf16 v[68:71], v[232:235], v[216:219], v[68:71]
	v_mfma_f32_16x16x32_bf16 v[124:127], v[228:231], v[196:199], v[124:127]
	v_mfma_f32_16x16x32_bf16 v[116:119], v[236:239], v[196:199], v[116:119]
	v_mfma_f32_16x16x32_bf16 v[108:111], v[228:231], v[204:207], v[108:111]
	v_mfma_f32_16x16x32_bf16 v[100:103], v[236:239], v[204:207], v[100:103]
	v_mfma_f32_16x16x32_bf16 v[92:95], v[228:231], v[212:215], v[92:95]
	v_mfma_f32_16x16x32_bf16 v[84:87], v[236:239], v[212:215], v[84:87]
	v_mfma_f32_16x16x32_bf16 v[76:79], v[228:231], v[220:223], v[76:79]
	v_mfma_f32_16x16x32_bf16 v[68:71], v[236:239], v[220:223], v[68:71]
	s_barrier
	s_setprio 0
	s_mov_b32 m0, s43
	ds_read_b128 v[192:195], v159 offset:49152
	ds_read_b128 v[196:199], v159 offset:50176
	ds_read_b128 v[200:203], v159 offset:51200
	ds_read_b128 v[204:207], v159 offset:52224
	ds_read_b128 v[208:211], v159 offset:53248
	ds_read_b128 v[212:215], v159 offset:54272
	ds_read_b128 v[216:219], v159 offset:55296
	ds_read_b128 v[220:223], v159 offset:56320
	global_load_lds_dwordx4 v128, s[100:101]
	s_mov_b32 m0, s44
	s_nop 0
	global_load_lds_dwordx4 v132, s[100:101]
	s_waitcnt lgkmcnt(0)
	s_setprio 1
	s_barrier
	v_mfma_f32_16x16x32_bf16 v[56:59], v[176:179], v[192:195], v[56:59]
	v_mfma_f32_16x16x32_bf16 v[48:51], v[184:187], v[192:195], v[48:51]
	v_mfma_f32_16x16x32_bf16 v[40:43], v[176:179], v[200:203], v[40:43]
	v_mfma_f32_16x16x32_bf16 v[32:35], v[184:187], v[200:203], v[32:35]
	v_mfma_f32_16x16x32_bf16 v[24:27], v[176:179], v[208:211], v[24:27]
	v_mfma_f32_16x16x32_bf16 v[16:19], v[184:187], v[208:211], v[16:19]
	v_mfma_f32_16x16x32_bf16 v[8:11], v[176:179], v[216:219], v[8:11]
	v_mfma_f32_16x16x32_bf16 v[4:7], v[184:187], v[216:219], v[4:7]
	v_mfma_f32_16x16x32_bf16 v[56:59], v[180:183], v[196:199], v[56:59]
	v_mfma_f32_16x16x32_bf16 v[48:51], v[188:191], v[196:199], v[48:51]
	v_mfma_f32_16x16x32_bf16 v[40:43], v[180:183], v[204:207], v[40:43]
	v_mfma_f32_16x16x32_bf16 v[32:35], v[188:191], v[204:207], v[32:35]
	v_mfma_f32_16x16x32_bf16 v[24:27], v[180:183], v[212:215], v[24:27]
	v_mfma_f32_16x16x32_bf16 v[16:19], v[188:191], v[212:215], v[16:19]
	v_mfma_f32_16x16x32_bf16 v[8:11], v[180:183], v[220:223], v[8:11]
	v_mfma_f32_16x16x32_bf16 v[4:7], v[188:191], v[220:223], v[4:7]
	s_barrier
	s_setprio 0
	s_add_u32 s8, s8, 0x80080
	s_addc_u32 s9, s9, 0
	s_add_i32 s10, s10, s36
	s_mov_b32 m0, s10
	s_nop 0
	global_load_lds_dwordx4 v130, s[8:9]
	s_add_i32 m0, s10, 0x2000
	s_nop 0
	global_load_lds_dwordx4 v134, s[8:9]
	s_waitcnt vmcnt(6)
	s_setprio 1
	s_barrier
	v_mfma_f32_16x16x32_bf16 v[60:63], v[224:227], v[192:195], v[60:63]
	v_mfma_f32_16x16x32_bf16 v[52:55], v[232:235], v[192:195], v[52:55]
	v_mfma_f32_16x16x32_bf16 v[44:47], v[224:227], v[200:203], v[44:47]
	v_mfma_f32_16x16x32_bf16 v[36:39], v[232:235], v[200:203], v[36:39]
	v_mfma_f32_16x16x32_bf16 v[28:31], v[224:227], v[208:211], v[28:31]
	v_mfma_f32_16x16x32_bf16 v[20:23], v[232:235], v[208:211], v[20:23]
	v_mfma_f32_16x16x32_bf16 v[12:15], v[224:227], v[216:219], v[12:15]
	v_mfma_f32_16x16x32_bf16 v[0:3], v[232:235], v[216:219], v[0:3]
	v_mfma_f32_16x16x32_bf16 v[60:63], v[228:231], v[196:199], v[60:63]
	v_mfma_f32_16x16x32_bf16 v[52:55], v[236:239], v[196:199], v[52:55]
	v_mfma_f32_16x16x32_bf16 v[44:47], v[228:231], v[204:207], v[44:47]
	v_mfma_f32_16x16x32_bf16 v[36:39], v[236:239], v[204:207], v[36:39]
	v_mfma_f32_16x16x32_bf16 v[28:31], v[228:231], v[212:215], v[28:31]
	v_mfma_f32_16x16x32_bf16 v[20:23], v[236:239], v[212:215], v[20:23]
	v_mfma_f32_16x16x32_bf16 v[12:15], v[228:231], v[220:223], v[12:15]
	v_mfma_f32_16x16x32_bf16 v[0:3], v[236:239], v[220:223], v[0:3]
	s_barrier
	s_setprio 0
	s_add_u32 s6, s6, 0x100
	s_addc_u32 s7, s7, 0
	s_add_u32 s25, s25, 0x100
	s_addc_u32 s27, s27, 0
	s_cmp_ge_i32 s34, s12
	s_mov_b32 s8, s34
	s_cbranch_scc0 .LBB0_1812
	s_branch .LBB0_1803

; #define PG8_STAGE(bufoff, gbase, voff) do { _Pragma("unroll") for (int _i = 0; _i < 2; ++_i) \
;         __builtin_amdgcn_global_load_lds((const unsigned*)((const char*)(gbase) + (voff)[_i]), (LAS unsigned*)(lds + (bufoff) + ldsw + _i * 8192), 16, 0, 0); } while (0)
; #define PG8_LDA(dst, b, h) do { _Pragma("unroll") for (int m = 0; m < 4; ++m) _Pragma("unroll") for (int k = 0; k < 2; ++k) dst[m][k] = *(const LAS bf16x8*)(lds + PG8_SA(b, h) + aoff + m * 2048 + k * 1024); } while (0)
; #define PG8_LDB(dst, b, h) do { _Pragma("unroll") for (int n = 0; n < 2; ++n) _Pragma("unroll") for (int k = 0; k < 2; ++k) dst[n][k] = *(const LAS bf16x8*)(lds + PG8_SB(b, h) + boff + n * 2048 + k * 1024); } while (0)
; #define PG8_MMA(ai, bj, At, Bt) do { __builtin_amdgcn_s_setprio(1); _Pragma("unroll") for (int m = 0; m < 4; ++m) _Pragma("unroll") for (int n = 0; n < 2; ++n) _Pragma("unroll") for (int k = 0; k < 2; ++k) \
;         acc[ai][bj][m][n] = __builtin_amdgcn_mfma_f32_16x16x32_bf16(Bt[n][k], At[m][k], acc[ai][bj][m][n], 0, 0, 0); __builtin_amdgcn_s_setprio(0); } while (0)
; #define PG8_WAIT_V(n) asm volatile("s_waitcnt vmcnt(" #n ")" ::: "memory")
; #define PG8_WAIT_L(n) asm volatile("s_waitcnt lgkmcnt(" #n ")" ::: "memory")
; template <class Epi, class Sched, bool ATILE = false>
; __device__ __forceinline__ void gemm_phase(LAS unsigned char* lds, const Gemm g, const Sched& S, const Epi& E) {
;     ...
;         for (int t = 0; t < nt; t += 2) {
;             const bool last = (t == nt - 2);
;             const char* a1 = cA + (size_t)(t + 1) * kstepA;
;             const char* a2 = last ? nA : cA + (size_t)(t + 2) * kstepA; const char* b2 = last ? nB : cB + (size_t)(t + 2) * kstep;
;             const char* a3 = a2 + kstepA; const char* b3 = b2 + kstep;
;             PG8_LDB(B0, 0, 0); PG8_SCHED; PG8_LDA(At, 0, 0); PG8_STAGE(PG8_SA(1, 1), a1 + hstepA, voffA);
;             PG8_WAIT_L(8); PG8_BAR; PG8_WAIT_L(0); PG8_MMA(0, 0, At, B0); PG8_BAR; PG8_SCHED;
;             PG8_LDB(B1, 0, 1); PG8_STAGE(PG8_SB(0, 0), b2, voffB);
;             PG8_BAR; PG8_WAIT_L(0); PG8_MMA(0, 1, At, B1); PG8_BAR;
;             PG8_LDA(At, 0, 1); PG8_STAGE(PG8_SA(0, 0), a2, voffA);
;             PG8_BAR; PG8_WAIT_L(0); PG8_MMA(1, 0, At, B0); PG8_BAR; PG8_SCHED;
;             PG8_STAGE(PG8_SB(0, 1), b2 + hstepB, voffB);
;             PG8_WAIT_V(6); PG8_BAR; PG8_MMA(1, 1, At, B1); PG8_BAR;
.LBB0_1898:
	ds_read_b128 v[20:23], v180
	ds_read_b128 v[28:31], v180 offset:1024
	ds_read_b128 v[174:177], v180 offset:2048
	ds_read_b128 v[184:187], v180 offset:3072
	s_add_i32 s58, s26, 2
	s_add_u32 s27, s24, 0x4000
	s_addc_u32 s28, s25, 0
	s_cmp_eq_u32 s17, s26
	s_cselect_b32 s30, s20, s27
	s_cselect_b32 s31, s21, s28
	s_cselect_b32 s26, s22, s56
	s_cselect_b32 s27, s23, s57
	s_add_u32 s28, s30, 0x8000
	s_addc_u32 s29, s31, 0
	s_add_i32 m0, s34, 0xc000
	ds_read_b128 v[188:191], v181
	ds_read_b128 v[192:195], v181 offset:1024
	ds_read_b128 v[196:199], v181 offset:2048
	ds_read_b128 v[200:203], v181 offset:3072
	ds_read_b128 v[204:207], v181 offset:4096
	ds_read_b128 v[208:211], v181 offset:5120
	ds_read_b128 v[212:215], v181 offset:6144
	ds_read_b128 v[216:219], v181 offset:7168
	global_load_lds_dwordx4 v168, s[24:25]
	s_add_i32 m0, s34, 0xe000
	s_nop 0
	global_load_lds_dwordx4 v170, s[24:25]
	s_waitcnt lgkmcnt(8)
	s_waitcnt lgkmcnt(0)
	s_setprio 1
	s_barrier
	v_mfma_f32_16x16x32_bf16 v[0:3], v[20:23], v[188:191], v[0:3]
	v_mfma_f32_16x16x32_bf16 v[4:7], v[174:177], v[188:191], v[4:7]
	v_mfma_f32_16x16x32_bf16 v[44:47], v[20:23], v[196:199], v[44:47]
	v_mfma_f32_16x16x32_bf16 v[36:39], v[174:177], v[196:199], v[36:39]
	v_mfma_f32_16x16x32_bf16 v[52:55], v[20:23], v[204:207], v[52:55]
	v_mfma_f32_16x16x32_bf16 v[48:51], v[174:177], v[204:207], v[48:51]
	v_mfma_f32_16x16x32_bf16 v[92:95], v[20:23], v[212:215], v[92:95]
	v_mfma_f32_16x16x32_bf16 v[84:87], v[174:177], v[212:215], v[84:87]
	v_mfma_f32_16x16x32_bf16 v[0:3], v[28:31], v[192:195], v[0:3]
	v_mfma_f32_16x16x32_bf16 v[4:7], v[184:187], v[192:195], v[4:7]
	v_mfma_f32_16x16x32_bf16 v[44:47], v[28:31], v[200:203], v[44:47]
	v_mfma_f32_16x16x32_bf16 v[36:39], v[184:187], v[200:203], v[36:39]
	v_mfma_f32_16x16x32_bf16 v[52:55], v[28:31], v[208:211], v[52:55]
	v_mfma_f32_16x16x32_bf16 v[48:51], v[184:187], v[208:211], v[48:51]
	v_mfma_f32_16x16x32_bf16 v[92:95], v[28:31], v[216:219], v[92:95]
	v_mfma_f32_16x16x32_bf16 v[84:87], v[184:187], v[216:219], v[84:87]
	s_barrier
	s_setprio 0
	s_add_i32 s59, s44, s33
	s_add_u32 s98, s26, s4
	s_addc_u32 s99, s27, s5
	s_mov_b32 m0, s59
	ds_read_b128 v[220:223], v182
	ds_read_b128 v[224:227], v182 offset:1024
	ds_read_b128 v[228:231], v182 offset:2048
	ds_read_b128 v[232:235], v182 offset:3072
	global_load_lds_dwordx4 v138, s[26:27]
	s_add_i32 m0, s59, 0x2000
	s_nop 0
	global_load_lds_dwordx4 v142, s[26:27]
	s_waitcnt lgkmcnt(0)
	s_setprio 1
	s_barrier
	v_mfma_f32_16x16x32_bf16 v[12:15], v[220:223], v[188:191], v[12:15]
	v_mfma_f32_16x16x32_bf16 v[8:11], v[228:231], v[188:191], v[8:11]
	v_mfma_f32_16x16x32_bf16 v[24:27], v[220:223], v[196:199], v[24:27]
	v_mfma_f32_16x16x32_bf16 v[16:19], v[228:231], v[196:199], v[16:19]
	v_mfma_f32_16x16x32_bf16 v[40:43], v[220:223], v[204:207], v[40:43]
	v_mfma_f32_16x16x32_bf16 v[32:35], v[228:231], v[204:207], v[32:35]
	v_mfma_f32_16x16x32_bf16 v[56:59], v[220:223], v[212:215], v[56:59]
	v_mfma_f32_16x16x32_bf16 v[60:63], v[228:231], v[212:215], v[60:63]
	v_mfma_f32_16x16x32_bf16 v[12:15], v[224:227], v[192:195], v[12:15]
	v_mfma_f32_16x16x32_bf16 v[8:11], v[232:235], v[192:195], v[8:11]
	v_mfma_f32_16x16x32_bf16 v[24:27], v[224:227], v[200:203], v[24:27]
	v_mfma_f32_16x16x32_bf16 v[16:19], v[232:235], v[200:203], v[16:19]
	v_mfma_f32_16x16x32_bf16 v[40:43], v[224:227], v[208:211], v[40:43]
	v_mfma_f32_16x16x32_bf16 v[32:35], v[232:235], v[208:211], v[32:35]
	v_mfma_f32_16x16x32_bf16 v[56:59], v[224:227], v[216:219], v[56:59]
	v_mfma_f32_16x16x32_bf16 v[60:63], v[232:235], v[216:219], v[60:63]
	s_barrier
	s_setprio 0
	s_mov_b32 m0, s34
	ds_read_b128 v[188:191], v181 offset:16384
	ds_read_b128 v[192:195], v181 offset:17408
	ds_read_b128 v[196:199], v181 offset:18432
	ds_read_b128 v[200:203], v181 offset:19456
	ds_read_b128 v[204:207], v181 offset:20480
	ds_read_b128 v[208:211], v181 offset:21504
	ds_read_b128 v[212:215], v181 offset:22528
	ds_read_b128 v[216:219], v181 offset:23552
	global_load_lds_dwordx4 v136, s[30:31]
	s_mov_b32 m0, s35
	s_nop 0
	global_load_lds_dwordx4 v140, s[30:31]
	s_waitcnt lgkmcnt(0)
	s_setprio 1
	s_barrier
	v_mfma_f32_16x16x32_bf16 v[64:67], v[20:23], v[188:191], v[64:67]
	v_mfma_f32_16x16x32_bf16 v[68:71], v[174:177], v[188:191], v[68:71]
	v_mfma_f32_16x16x32_bf16 v[108:111], v[20:23], v[196:199], v[108:111]
	v_mfma_f32_16x16x32_bf16 v[100:103], v[174:177], v[196:199], v[100:103]
	v_mfma_f32_16x16x32_bf16 v[116:119], v[20:23], v[204:207], v[116:119]
	v_mfma_f32_16x16x32_bf16 v[112:115], v[174:177], v[204:207], v[112:115]
	v_mfma_f32_16x16x32_bf16 v[20:23], v[20:23], v[212:215], v[132:135]
	v_mfma_f32_16x16x32_bf16 v[64:67], v[28:31], v[192:195], v[64:67]
	v_mfma_f32_16x16x32_bf16 v[68:71], v[184:187], v[192:195], v[68:71]
	v_mfma_f32_16x16x32_bf16 v[108:111], v[28:31], v[200:203], v[108:111]
	v_mfma_f32_16x16x32_bf16 v[100:103], v[184:187], v[200:203], v[100:103]
	v_mfma_f32_16x16x32_bf16 v[116:119], v[28:31], v[208:211], v[116:119]
	v_mfma_f32_16x16x32_bf16 v[112:115], v[184:187], v[208:211], v[112:115]
	v_mfma_f32_16x16x32_bf16 v[20:23], v[28:31], v[216:219], v[20:23]
	v_mfma_f32_16x16x32_bf16 v[28:31], v[174:177], v[212:215], v[128:131]
	v_mfma_f32_16x16x32_bf16 v[28:31], v[184:187], v[216:219], v[28:31]
	s_barrier
	s_setprio 0
	s_add_u32 s60, s26, 0x158000
	s_addc_u32 s61, s27, 0
	s_add_i32 s59, s45, s33
	s_mov_b32 m0, s59
	s_nop 0
	global_load_lds_dwordx4 v138, s[60:61]
	s_add_i32 m0, s59, 0x2000
	s_nop 0
	global_load_lds_dwordx4 v142, s[60:61]
	s_waitcnt vmcnt(6)
	s_setprio 1
	s_barrier
; #define PG8_STAGE(bufoff, gbase, voff) do { _Pragma("unroll") for (int _i = 0; _i < 2; ++_i) \
;         __builtin_amdgcn_global_load_lds((const unsigned*)((const char*)(gbase) + (voff)[_i]), (LAS unsigned*)(lds + (bufoff) + ldsw + _i * 8192), 16, 0, 0); } while (0)
; #define PG8_LDA(dst, b, h) do { _Pragma("unroll") for (int m = 0; m < 4; ++m) _Pragma("unroll") for (int k = 0; k < 2; ++k) dst[m][k] = *(const LAS bf16x8*)(lds + PG8_SA(b, h) + aoff + m * 2048 + k * 1024); } while (0)
; #define PG8_LDB(dst, b, h) do { _Pragma("unroll") for (int n = 0; n < 2; ++n) _Pragma("unroll") for (int k = 0; k < 2; ++k) dst[n][k] = *(const LAS bf16x8*)(lds + PG8_SB(b, h) + boff + n * 2048 + k * 1024); } while (0)
; #define PG8_MMA(ai, bj, At, Bt) do { __builtin_amdgcn_s_setprio(1); _Pragma("unroll") for (int m = 0; m < 4; ++m) _Pragma("unroll") for (int n = 0; n < 2; ++n) _Pragma("unroll") for (int k = 0; k < 2; ++k) \
;         acc[ai][bj][m][n] = __builtin_amdgcn_mfma_f32_16x16x32_bf16(Bt[n][k], At[m][k], acc[ai][bj][m][n], 0, 0, 0); __builtin_amdgcn_s_setprio(0); } while (0)
; #define PG8_WAIT_V(n) asm volatile("s_waitcnt vmcnt(" #n ")" ::: "memory")
; #define PG8_WAIT_L(n) asm volatile("s_waitcnt lgkmcnt(" #n ")" ::: "memory")
; #define PG8_BAR __builtin_amdgcn_s_barrier()
; #define PG8_SCHED __builtin_amdgcn_sched_barrier(0)
; template <class Epi, class Sched, bool ATILE = false>
; __device__ __forceinline__ void gemm_phase(LAS unsigned char* lds, const Gemm g, const Sched& S, const Epi& E) {
;     ...
;             PG8_WAIT_V(6); PG8_BAR; PG8_MMA(1, 1, At, B1); PG8_BAR;
;             PG8_LDB(B0, 1, 0); PG8_SCHED; PG8_LDA(At, 1, 0); PG8_STAGE(PG8_SA(0, 1), a2 + hstepA, voffA);
;             PG8_WAIT_L(8); PG8_BAR; PG8_WAIT_L(0); PG8_MMA(0, 0, At, B0); PG8_BAR; PG8_SCHED;
;             PG8_LDB(B1, 1, 1); PG8_STAGE(PG8_SB(1, 0), b3, voffB);
;             PG8_BAR; PG8_WAIT_L(0); PG8_MMA(0, 1, At, B1); PG8_BAR;
;             PG8_LDA(At, 1, 1); PG8_STAGE(PG8_SA(1, 0), a3, voffA);
;             PG8_BAR; PG8_WAIT_L(0); PG8_MMA(1, 0, At, B0); PG8_BAR; PG8_SCHED;
	v_mfma_f32_16x16x32_bf16 v[76:79], v[220:223], v[188:191], v[76:79]
	v_mfma_f32_16x16x32_bf16 v[72:75], v[228:231], v[188:191], v[72:75]
	v_mfma_f32_16x16x32_bf16 v[88:91], v[220:223], v[196:199], v[88:91]
	v_mfma_f32_16x16x32_bf16 v[80:83], v[228:231], v[196:199], v[80:83]
	v_mfma_f32_16x16x32_bf16 v[104:107], v[220:223], v[204:207], v[104:107]
	v_mfma_f32_16x16x32_bf16 v[96:99], v[228:231], v[204:207], v[96:99]
	v_mfma_f32_16x16x32_bf16 v[120:123], v[220:223], v[212:215], v[120:123]
	v_mfma_f32_16x16x32_bf16 v[124:127], v[228:231], v[212:215], v[124:127]
	v_mfma_f32_16x16x32_bf16 v[76:79], v[224:227], v[192:195], v[76:79]
	v_mfma_f32_16x16x32_bf16 v[72:75], v[232:235], v[192:195], v[72:75]
	v_mfma_f32_16x16x32_bf16 v[88:91], v[224:227], v[200:203], v[88:91]
	v_mfma_f32_16x16x32_bf16 v[80:83], v[232:235], v[200:203], v[80:83]
	v_mfma_f32_16x16x32_bf16 v[104:107], v[224:227], v[208:211], v[104:107]
	v_mfma_f32_16x16x32_bf16 v[96:99], v[232:235], v[208:211], v[96:99]
	v_mfma_f32_16x16x32_bf16 v[120:123], v[224:227], v[216:219], v[120:123]
	v_mfma_f32_16x16x32_bf16 v[124:127], v[232:235], v[216:219], v[124:127]
	s_barrier
	s_setprio 0
	s_add_i32 s59, 0, 0x18000
	v_add_u32_e32 v183, s59, v157
	ds_read_b128 v[128:131], v183
	ds_read_b128 v[132:135], v183 offset:1024
	ds_read_b128 v[174:177], v183 offset:2048
	ds_read_b128 v[184:187], v183 offset:3072
	s_add_u32 s30, s30, 0x4000
	s_addc_u32 s31, s31, 0
	s_mov_b32 m0, s36
	ds_read_b128 v[188:191], v181 offset:32768
	ds_read_b128 v[192:195], v181 offset:33792
	ds_read_b128 v[196:199], v181 offset:34816
	ds_read_b128 v[200:203], v181 offset:35840
	ds_read_b128 v[204:207], v181 offset:36864
	ds_read_b128 v[208:211], v181 offset:37888
	ds_read_b128 v[212:215], v181 offset:38912
	ds_read_b128 v[216:219], v181 offset:39936
	global_load_lds_dwordx4 v136, s[30:31]
	s_mov_b32 m0, s37
	s_nop 0
	global_load_lds_dwordx4 v140, s[30:31]
	s_waitcnt lgkmcnt(8)
	s_waitcnt lgkmcnt(0)
	s_setprio 1
	s_barrier
	v_mfma_f32_16x16x32_bf16 v[0:3], v[128:131], v[188:191], v[0:3]
	v_mfma_f32_16x16x32_bf16 v[4:7], v[174:177], v[188:191], v[4:7]
	v_mfma_f32_16x16x32_bf16 v[44:47], v[128:131], v[196:199], v[44:47]
	v_mfma_f32_16x16x32_bf16 v[36:39], v[174:177], v[196:199], v[36:39]
	v_mfma_f32_16x16x32_bf16 v[52:55], v[128:131], v[204:207], v[52:55]
	v_mfma_f32_16x16x32_bf16 v[48:51], v[174:177], v[204:207], v[48:51]
	v_mfma_f32_16x16x32_bf16 v[92:95], v[128:131], v[212:215], v[92:95]
	v_mfma_f32_16x16x32_bf16 v[84:87], v[174:177], v[212:215], v[84:87]
	v_mfma_f32_16x16x32_bf16 v[0:3], v[132:135], v[192:195], v[0:3]
	v_mfma_f32_16x16x32_bf16 v[4:7], v[184:187], v[192:195], v[4:7]
	v_mfma_f32_16x16x32_bf16 v[44:47], v[132:135], v[200:203], v[44:47]
	v_mfma_f32_16x16x32_bf16 v[36:39], v[184:187], v[200:203], v[36:39]
	v_mfma_f32_16x16x32_bf16 v[52:55], v[132:135], v[208:211], v[52:55]
	v_mfma_f32_16x16x32_bf16 v[48:51], v[184:187], v[208:211], v[48:51]
	v_mfma_f32_16x16x32_bf16 v[92:95], v[132:135], v[216:219], v[92:95]
	v_mfma_f32_16x16x32_bf16 v[84:87], v[184:187], v[216:219], v[84:87]
	s_barrier
	s_setprio 0
	s_add_i32 s30, 0, 0x1c000
	s_add_i32 s31, s59, s33
	v_add_u32_e32 v183, s30, v157
	s_mov_b32 m0, s31
	ds_read_b128 v[220:223], v183
	ds_read_b128 v[224:227], v183 offset:1024
	ds_read_b128 v[228:231], v183 offset:2048
	ds_read_b128 v[232:235], v183 offset:3072
	global_load_lds_dwordx4 v138, s[98:99]
	s_add_i32 m0, s31, 0x2000
	s_nop 0
	global_load_lds_dwordx4 v142, s[98:99]
	s_waitcnt lgkmcnt(0)
	s_setprio 1
	s_barrier
	v_mfma_f32_16x16x32_bf16 v[12:15], v[220:223], v[188:191], v[12:15]
	v_mfma_f32_16x16x32_bf16 v[8:11], v[228:231], v[188:191], v[8:11]
	v_mfma_f32_16x16x32_bf16 v[24:27], v[220:223], v[196:199], v[24:27]
	v_mfma_f32_16x16x32_bf16 v[16:19], v[228:231], v[196:199], v[16:19]
	v_mfma_f32_16x16x32_bf16 v[40:43], v[220:223], v[204:207], v[40:43]
	v_mfma_f32_16x16x32_bf16 v[32:35], v[228:231], v[204:207], v[32:35]
	v_mfma_f32_16x16x32_bf16 v[56:59], v[220:223], v[212:215], v[56:59]
	v_mfma_f32_16x16x32_bf16 v[60:63], v[228:231], v[212:215], v[60:63]
	v_mfma_f32_16x16x32_bf16 v[12:15], v[224:227], v[192:195], v[12:15]
	v_mfma_f32_16x16x32_bf16 v[8:11], v[232:235], v[192:195], v[8:11]
	v_mfma_f32_16x16x32_bf16 v[24:27], v[224:227], v[200:203], v[24:27]
	v_mfma_f32_16x16x32_bf16 v[16:19], v[232:235], v[200:203], v[16:19]
	v_mfma_f32_16x16x32_bf16 v[40:43], v[224:227], v[208:211], v[40:43]
	v_mfma_f32_16x16x32_bf16 v[32:35], v[232:235], v[208:211], v[32:35]
	v_mfma_f32_16x16x32_bf16 v[56:59], v[224:227], v[216:219], v[56:59]
	v_mfma_f32_16x16x32_bf16 v[60:63], v[232:235], v[216:219], v[60:63]
	s_barrier
	s_setprio 0
	s_mov_b32 m0, s39
	ds_read_b128 v[188:191], v181 offset:49152
	ds_read_b128 v[192:195], v181 offset:50176
	ds_read_b128 v[196:199], v181 offset:51200
	ds_read_b128 v[200:203], v181 offset:52224
	ds_read_b128 v[204:207], v181 offset:53248
	ds_read_b128 v[208:211], v181 offset:54272
	ds_read_b128 v[212:215], v181 offset:55296
	ds_read_b128 v[216:219], v181 offset:56320
	global_load_lds_dwordx4 v136, s[28:29]
	s_mov_b32 m0, s40
	s_nop 0
	global_load_lds_dwordx4 v140, s[28:29]
	s_waitcnt lgkmcnt(0)
	s_setprio 1
	s_barrier
; #define PG8_STAGE(bufoff, gbase, voff) do { _Pragma("unroll") for (int _i = 0; _i < 2; ++_i) \
;         __builtin_amdgcn_global_load_lds((const unsigned*)((const char*)(gbase) + (voff)[_i]), (LAS unsigned*)(lds + (bufoff) + ldsw + _i * 8192), 16, 0, 0); } while (0)
; #define PG8_MMA(ai, bj, At, Bt) do { __builtin_amdgcn_s_setprio(1); _Pragma("unroll") for (int m = 0; m < 4; ++m) _Pragma("unroll") for (int n = 0; n < 2; ++n) _Pragma("unroll") for (int k = 0; k < 2; ++k) \
;         acc[ai][bj][m][n] = __builtin_amdgcn_mfma_f32_16x16x32_bf16(Bt[n][k], At[m][k], acc[ai][bj][m][n], 0, 0, 0); __builtin_amdgcn_s_setprio(0); } while (0)
; #define PG8_WAIT_V(n) asm volatile("s_waitcnt vmcnt(" #n ")" ::: "memory")
; #define PG8_WAIT_L(n) asm volatile("s_waitcnt lgkmcnt(" #n ")" ::: "memory")
; #define PG8_BAR __builtin_amdgcn_s_barrier()
; #define PG8_SCHED __builtin_amdgcn_sched_barrier(0)
; template <class Epi, class Sched, bool ATILE = false>
; __device__ __forceinline__ void gemm_phase(LAS unsigned char* lds, const Gemm g, const Sched& S, const Epi& E) {
;     ...
;             PG8_BAR; PG8_WAIT_L(0); PG8_MMA(1, 0, At, B0); PG8_BAR; PG8_SCHED;
;             PG8_STAGE(PG8_SB(1, 1), b3 + hstepB, voffB);
;             PG8_WAIT_V(6); PG8_BAR; PG8_MMA(1, 1, At, B1); PG8_BAR;
;         }
;         E(acc, cur, wr, wc, fr, fq);
	v_mfma_f32_16x16x32_bf16 v[64:67], v[128:131], v[188:191], v[64:67]
	v_mfma_f32_16x16x32_bf16 v[108:111], v[128:131], v[196:199], v[108:111]
	v_mfma_f32_16x16x32_bf16 v[116:119], v[128:131], v[204:207], v[116:119]
	v_mfma_f32_16x16x32_bf16 v[20:23], v[128:131], v[212:215], v[20:23]
	v_mfma_f32_16x16x32_bf16 v[64:67], v[132:135], v[192:195], v[64:67]
	v_mfma_f32_16x16x32_bf16 v[68:71], v[174:177], v[188:191], v[68:71]
	v_mfma_f32_16x16x32_bf16 v[108:111], v[132:135], v[200:203], v[108:111]
	v_mfma_f32_16x16x32_bf16 v[100:103], v[174:177], v[196:199], v[100:103]
	v_mfma_f32_16x16x32_bf16 v[116:119], v[132:135], v[208:211], v[116:119]
	v_mfma_f32_16x16x32_bf16 v[112:115], v[174:177], v[204:207], v[112:115]
	v_mfma_f32_16x16x32_bf16 v[132:135], v[132:135], v[216:219], v[20:23]
	v_mfma_f32_16x16x32_bf16 v[20:23], v[174:177], v[212:215], v[28:31]
	v_mfma_f32_16x16x32_bf16 v[68:71], v[184:187], v[192:195], v[68:71]
	v_mfma_f32_16x16x32_bf16 v[100:103], v[184:187], v[200:203], v[100:103]
	v_mfma_f32_16x16x32_bf16 v[112:115], v[184:187], v[208:211], v[112:115]
	v_mfma_f32_16x16x32_bf16 v[128:131], v[184:187], v[216:219], v[20:23]
	s_barrier
	s_setprio 0
	s_add_u32 s26, s26, 0x158080
	s_addc_u32 s27, s27, 0
	s_add_i32 s28, s30, s33
	s_mov_b32 m0, s28
	s_nop 0
	global_load_lds_dwordx4 v138, s[26:27]
	s_add_i32 m0, s28, 0x2000
	s_nop 0
	global_load_lds_dwordx4 v142, s[26:27]
	s_waitcnt vmcnt(6)
	s_setprio 1
	s_barrier
	v_mfma_f32_16x16x32_bf16 v[20:23], v[220:223], v[188:191], v[76:79]
	v_mfma_f32_16x16x32_bf16 v[76:79], v[224:227], v[192:195], v[20:23]
	v_mfma_f32_16x16x32_bf16 v[20:23], v[228:231], v[188:191], v[72:75]
	v_mfma_f32_16x16x32_bf16 v[72:75], v[232:235], v[192:195], v[20:23]
	v_mfma_f32_16x16x32_bf16 v[20:23], v[220:223], v[196:199], v[88:91]
	v_mfma_f32_16x16x32_bf16 v[88:91], v[224:227], v[200:203], v[20:23]
	v_mfma_f32_16x16x32_bf16 v[20:23], v[228:231], v[196:199], v[80:83]
	v_mfma_f32_16x16x32_bf16 v[80:83], v[232:235], v[200:203], v[20:23]
	v_mfma_f32_16x16x32_bf16 v[20:23], v[220:223], v[204:207], v[104:107]
	v_mfma_f32_16x16x32_bf16 v[104:107], v[224:227], v[208:211], v[20:23]
	v_mfma_f32_16x16x32_bf16 v[20:23], v[228:231], v[204:207], v[96:99]
	v_mfma_f32_16x16x32_bf16 v[96:99], v[232:235], v[208:211], v[20:23]
	v_mfma_f32_16x16x32_bf16 v[20:23], v[220:223], v[212:215], v[120:123]
	v_mfma_f32_16x16x32_bf16 v[120:123], v[224:227], v[216:219], v[20:23]
	v_mfma_f32_16x16x32_bf16 v[20:23], v[228:231], v[212:215], v[124:127]
	v_mfma_f32_16x16x32_bf16 v[124:127], v[232:235], v[216:219], v[20:23]
	s_barrier
	s_setprio 0
	s_add_u32 s56, s56, 0x100
	s_addc_u32 s57, s57, 0
	s_add_u32 s24, s24, 0x10000
	s_addc_u32 s25, s25, 0
	s_cmp_ge_i32 s58, s55
	s_mov_b32 s26, s58
	s_cbranch_scc0 .LBB0_1898
	v_pk_mul_f32 v[2:3], v[2:3], 0.5 op_sel_hi:[1,0]
	v_pk_mul_f32 v[0:1], v[0:1], 0.5 op_sel_hi:[1,0]
	v_pk_mul_f32 v[6:7], v[6:7], 0.5 op_sel_hi:[1,0]
	v_pk_mul_f32 v[4:5], v[4:5], 0.5 op_sel_hi:[1,0]
	v_pk_mul_f32 v[22:23], v[14:15], 0.5 op_sel_hi:[1,0]
	v_pk_mul_f32 v[20:21], v[12:13], 0.5 op_sel_hi:[1,0]
	v_pk_mul_f32 v[30:31], v[10:11], 0.5 op_sel_hi:[1,0]
	v_pk_mul_f32 v[28:29], v[8:9], 0.5 op_sel_hi:[1,0]
	v_pk_mul_f32 v[10:11], v[46:47], 0.5 op_sel_hi:[1,0]
	v_pk_mul_f32 v[8:9], v[44:45], 0.5 op_sel_hi:[1,0]
	v_pk_mul_f32 v[14:15], v[38:39], 0.5 op_sel_hi:[1,0]
	v_pk_mul_f32 v[12:13], v[36:37], 0.5 op_sel_hi:[1,0]
	v_pk_mul_f32 v[38:39], v[26:27], 0.5 op_sel_hi:[1,0]
	v_pk_mul_f32 v[36:37], v[24:25], 0.5 op_sel_hi:[1,0]
	v_pk_mul_f32 v[46:47], v[18:19], 0.5 op_sel_hi:[1,0]
	v_pk_mul_f32 v[44:45], v[16:17], 0.5 op_sel_hi:[1,0]
	v_pk_mul_f32 v[18:19], v[54:55], 0.5 op_sel_hi:[1,0]
	v_pk_mul_f32 v[16:17], v[52:53], 0.5 op_sel_hi:[1,0]
	v_pk_mul_f32 v[26:27], v[50:51], 0.5 op_sel_hi:[1,0]
	v_pk_mul_f32 v[24:25], v[48:49], 0.5 op_sel_hi:[1,0]
	v_pk_mul_f32 v[50:51], v[42:43], 0.5 op_sel_hi:[1,0]
	v_pk_mul_f32 v[48:49], v[40:41], 0.5 op_sel_hi:[1,0]
	v_pk_mul_f32 v[54:55], v[34:35], 0.5 op_sel_hi:[1,0]
	v_pk_mul_f32 v[52:53], v[32:33], 0.5 op_sel_hi:[1,0]
	v_pk_mul_f32 v[34:35], v[94:95], 0.5 op_sel_hi:[1,0]
	v_pk_mul_f32 v[32:33], v[92:93], 0.5 op_sel_hi:[1,0]
	v_pk_mul_f32 v[42:43], v[86:87], 0.5 op_sel_hi:[1,0]
	v_pk_mul_f32 v[40:41], v[84:85], 0.5 op_sel_hi:[1,0]
	v_pk_mul_f32 v[58:59], v[58:59], 0.5 op_sel_hi:[1,0]
	v_pk_mul_f32 v[56:57], v[56:57], 0.5 op_sel_hi:[1,0]
	v_pk_mul_f32 v[62:63], v[62:63], 0.5 op_sel_hi:[1,0]
	v_pk_mul_f32 v[60:61], v[60:61], 0.5 op_sel_hi:[1,0]
	v_pk_mul_f32 v[66:67], v[66:67], 0.5 op_sel_hi:[1,0]
	v_pk_mul_f32 v[64:65], v[64:65], 0.5 op_sel_hi:[1,0]
	v_pk_mul_f32 v[70:71], v[70:71], 0.5 op_sel_hi:[1,0]
	v_pk_mul_f32 v[68:69], v[68:69], 0.5 op_sel_hi:[1,0]
	v_pk_mul_f32 v[86:87], v[78:79], 0.5 op_sel_hi:[1,0]
	v_pk_mul_f32 v[84:85], v[76:77], 0.5 op_sel_hi:[1,0]
	v_pk_mul_f32 v[94:95], v[74:75], 0.5 op_sel_hi:[1,0]
	v_pk_mul_f32 v[92:93], v[72:73], 0.5 op_sel_hi:[1,0]
	v_pk_mul_f32 v[74:75], v[110:111], 0.5 op_sel_hi:[1,0]
	v_pk_mul_f32 v[72:73], v[108:109], 0.5 op_sel_hi:[1,0]
	v_pk_mul_f32 v[78:79], v[102:103], 0.5 op_sel_hi:[1,0]
	v_pk_mul_f32 v[76:77], v[100:101], 0.5 op_sel_hi:[1,0]
	v_pk_mul_f32 v[102:103], v[90:91], 0.5 op_sel_hi:[1,0]
	v_pk_mul_f32 v[100:101], v[88:89], 0.5 op_sel_hi:[1,0]
	v_pk_mul_f32 v[110:111], v[82:83], 0.5 op_sel_hi:[1,0]
	v_pk_mul_f32 v[108:109], v[80:81], 0.5 op_sel_hi:[1,0]
	v_pk_mul_f32 v[82:83], v[118:119], 0.5 op_sel_hi:[1,0]
	v_pk_mul_f32 v[80:81], v[116:117], 0.5 op_sel_hi:[1,0]
	v_pk_mul_f32 v[90:91], v[114:115], 0.5 op_sel_hi:[1,0]
	v_pk_mul_f32 v[88:89], v[112:113], 0.5 op_sel_hi:[1,0]
	v_pk_mul_f32 v[114:115], v[106:107], 0.5 op_sel_hi:[1,0]
	v_pk_mul_f32 v[112:113], v[104:105], 0.5 op_sel_hi:[1,0]
	v_pk_mul_f32 v[118:119], v[98:99], 0.5 op_sel_hi:[1,0]
	v_pk_mul_f32 v[116:117], v[96:97], 0.5 op_sel_hi:[1,0]
	v_pk_mul_f32 v[98:99], v[134:135], 0.5 op_sel_hi:[1,0]
	v_pk_mul_f32 v[96:97], v[132:133], 0.5 op_sel_hi:[1,0]
	v_pk_mul_f32 v[106:107], v[130:131], 0.5 op_sel_hi:[1,0]
	v_pk_mul_f32 v[104:105], v[128:129], 0.5 op_sel_hi:[1,0]
	v_pk_mul_f32 v[122:123], v[122:123], 0.5 op_sel_hi:[1,0]
	v_pk_mul_f32 v[120:121], v[120:121], 0.5 op_sel_hi:[1,0]
	v_pk_mul_f32 v[126:127], v[126:127], 0.5 op_sel_hi:[1,0]
	v_pk_mul_f32 v[124:125], v[124:125], 0.5 op_sel_hi:[1,0]
	s_branch .LBB0_1903
